# v68 + GEMM K-loops: s_setprio 1 issued before the barrier that opens each MFMA block instead of after it (76 sites), so the computing half wakes already prioritised
# baseline (speedup 1.0000x reference)
.LBB0_126:
	ds_read_b128 v[152:155], v149
	ds_read_b128 v[156:159], v149 offset:1024
	ds_read_b128 v[160:163], v149 offset:2048
	ds_read_b128 v[164:167], v149 offset:3072
	ds_read_b128 v[168:171], v150
	ds_read_b128 v[172:175], v150 offset:1024
	ds_read_b128 v[176:179], v150 offset:2048
	ds_read_b128 v[180:183], v150 offset:3072
	s_add_u32 s26, s24, 0xfffc0080
	s_addc_u32 s27, s25, -1
	s_cmp_eq_u32 s49, 12
	s_cselect_b32 s29, s19, s27
	s_cselect_b32 s28, s45, s26
	s_cselect_b32 s27, s17, s48
	s_cselect_b32 s26, s46, s47
	v_lshl_add_u64 v[144:145], s[24:25], 0, v[138:139]
	s_add_i32 m0, s31, 0xc000
	ds_read_b128 v[184:187], v151
	ds_read_b128 v[188:191], v151 offset:1024
	ds_read_b128 v[192:195], v151 offset:2048
	ds_read_b128 v[196:199], v151 offset:3072
	ds_read_b128 v[200:203], v151 offset:4096
	ds_read_b128 v[204:207], v151 offset:5120
	ds_read_b128 v[208:211], v151 offset:6144
	ds_read_b128 v[212:215], v151 offset:7168
	global_load_lds_dwordx4 v[144:145], off
	v_lshl_add_u64 v[144:145], s[24:25], 0, v[136:137]
	s_add_i32 m0, s31, 0xe000
	s_nop 0
	global_load_lds_dwordx4 v[144:145], off
	s_waitcnt vmcnt(8)
	s_waitcnt lgkmcnt(0)
	s_setprio 1
	s_barrier
	s_waitcnt lgkmcnt(0)
	v_mfma_f32_16x16x32_bf16 v[124:127], v[152:155], v[184:187], v[124:127]
	v_mfma_f32_16x16x32_bf16 v[120:123], v[160:163], v[184:187], v[120:123]
	v_mfma_f32_16x16x32_bf16 v[108:111], v[152:155], v[192:195], v[108:111]
	v_mfma_f32_16x16x32_bf16 v[104:107], v[160:163], v[192:195], v[104:107]
	v_mfma_f32_16x16x32_bf16 v[92:95], v[152:155], v[200:203], v[92:95]
	v_mfma_f32_16x16x32_bf16 v[88:91], v[160:163], v[200:203], v[88:91]
	v_mfma_f32_16x16x32_bf16 v[76:79], v[152:155], v[208:211], v[76:79]
	v_mfma_f32_16x16x32_bf16 v[72:75], v[160:163], v[208:211], v[72:75]
	v_mfma_f32_16x16x32_bf16 v[124:127], v[156:159], v[188:191], v[124:127]
	v_mfma_f32_16x16x32_bf16 v[120:123], v[164:167], v[188:191], v[120:123]
	v_mfma_f32_16x16x32_bf16 v[108:111], v[156:159], v[196:199], v[108:111]
	v_mfma_f32_16x16x32_bf16 v[104:107], v[164:167], v[196:199], v[104:107]
	v_mfma_f32_16x16x32_bf16 v[92:95], v[156:159], v[204:207], v[92:95]
	v_mfma_f32_16x16x32_bf16 v[88:91], v[164:167], v[204:207], v[88:91]
	v_mfma_f32_16x16x32_bf16 v[76:79], v[156:159], v[212:215], v[76:79]
	v_mfma_f32_16x16x32_bf16 v[72:75], v[164:167], v[212:215], v[72:75]
	s_setprio 0
	s_setprio 1
	v_mfma_f32_16x16x32_bf16 v[116:119], v[168:171], v[184:187], v[116:119]
	v_mfma_f32_16x16x32_bf16 v[112:115], v[176:179], v[184:187], v[112:115]
	v_mfma_f32_16x16x32_bf16 v[100:103], v[168:171], v[192:195], v[100:103]
	v_mfma_f32_16x16x32_bf16 v[96:99], v[176:179], v[192:195], v[96:99]
	v_mfma_f32_16x16x32_bf16 v[84:87], v[168:171], v[200:203], v[84:87]
	v_mfma_f32_16x16x32_bf16 v[80:83], v[176:179], v[200:203], v[80:83]
	v_mfma_f32_16x16x32_bf16 v[68:71], v[168:171], v[208:211], v[68:71]
	v_mfma_f32_16x16x32_bf16 v[64:67], v[176:179], v[208:211], v[64:67]
	v_mfma_f32_16x16x32_bf16 v[116:119], v[172:175], v[188:191], v[116:119]
	v_mfma_f32_16x16x32_bf16 v[112:115], v[180:183], v[188:191], v[112:115]
	v_mfma_f32_16x16x32_bf16 v[100:103], v[172:175], v[196:199], v[100:103]
	v_mfma_f32_16x16x32_bf16 v[96:99], v[180:183], v[196:199], v[96:99]
	v_mfma_f32_16x16x32_bf16 v[84:87], v[172:175], v[204:207], v[84:87]
	v_mfma_f32_16x16x32_bf16 v[80:83], v[180:183], v[204:207], v[80:83]
	v_mfma_f32_16x16x32_bf16 v[68:71], v[172:175], v[212:215], v[68:71]
	v_mfma_f32_16x16x32_bf16 v[64:67], v[180:183], v[212:215], v[64:67]
	s_setprio 0
	s_barrier
	s_add_i32 s50, s40, s30
	v_lshl_add_u64 v[144:145], s[26:27], 0, v[132:133]
	s_mov_b32 m0, s50
	ds_read_b128 v[184:187], v151 offset:16384
	ds_read_b128 v[188:191], v151 offset:17408
	ds_read_b128 v[192:195], v151 offset:18432
	ds_read_b128 v[196:199], v151 offset:19456
	ds_read_b128 v[200:203], v151 offset:20480
	ds_read_b128 v[204:207], v151 offset:21504
	ds_read_b128 v[208:211], v151 offset:22528
	ds_read_b128 v[212:215], v151 offset:23552
	global_load_lds_dwordx4 v[144:145], off
	s_add_i32 m0, s50, 0x2000
	s_add_u32 s50, s26, 0x40000
	v_lshl_add_u64 v[216:217], s[26:27], 0, v[128:129]
	s_addc_u32 s51, s27, 0
	s_add_i32 s52, s41, s30
	global_load_lds_dwordx4 v[216:217], off
	v_lshl_add_u64 v[218:219], s[50:51], 0, v[132:133]
	s_mov_b32 m0, s52
	v_lshl_add_u64 v[220:221], s[28:29], 0, v[130:131]
	global_load_lds_dwordx4 v[218:219], off
	v_lshl_add_u64 v[218:219], s[50:51], 0, v[128:129]
	s_add_i32 m0, s52, 0x2000
	s_nop 0
	global_load_lds_dwordx4 v[218:219], off
	v_lshl_add_u64 v[218:219], s[28:29], 0, v[134:135]
	s_mov_b32 m0, s31
	s_nop 0
	global_load_lds_dwordx4 v[218:219], off
	s_mov_b32 m0, s33
	s_nop 0
	global_load_lds_dwordx4 v[220:221], off
	s_waitcnt vmcnt(8)
	s_waitcnt lgkmcnt(0)
	s_setprio 1
	s_barrier
	s_waitcnt lgkmcnt(0)
	v_mfma_f32_16x16x32_bf16 v[60:63], v[152:155], v[184:187], v[60:63]
	v_mfma_f32_16x16x32_bf16 v[56:59], v[160:163], v[184:187], v[56:59]
	v_mfma_f32_16x16x32_bf16 v[44:47], v[152:155], v[192:195], v[44:47]
	v_mfma_f32_16x16x32_bf16 v[40:43], v[160:163], v[192:195], v[40:43]
	v_mfma_f32_16x16x32_bf16 v[28:31], v[152:155], v[200:203], v[28:31]
	v_mfma_f32_16x16x32_bf16 v[24:27], v[160:163], v[200:203], v[24:27]
	v_mfma_f32_16x16x32_bf16 v[12:15], v[152:155], v[208:211], v[12:15]
	v_mfma_f32_16x16x32_bf16 v[8:11], v[160:163], v[208:211], v[8:11]
	v_mfma_f32_16x16x32_bf16 v[60:63], v[156:159], v[188:191], v[60:63]
	v_mfma_f32_16x16x32_bf16 v[56:59], v[164:167], v[188:191], v[56:59]
	v_mfma_f32_16x16x32_bf16 v[44:47], v[156:159], v[196:199], v[44:47]
	v_mfma_f32_16x16x32_bf16 v[40:43], v[164:167], v[196:199], v[40:43]
	v_mfma_f32_16x16x32_bf16 v[28:31], v[156:159], v[204:207], v[28:31]
	v_mfma_f32_16x16x32_bf16 v[24:27], v[164:167], v[204:207], v[24:27]
	v_mfma_f32_16x16x32_bf16 v[12:15], v[156:159], v[212:215], v[12:15]
	v_mfma_f32_16x16x32_bf16 v[8:11], v[164:167], v[212:215], v[8:11]
	s_setprio 0
	s_setprio 1
	v_mfma_f32_16x16x32_bf16 v[52:55], v[168:171], v[184:187], v[52:55]
	v_mfma_f32_16x16x32_bf16 v[48:51], v[176:179], v[184:187], v[48:51]
	v_mfma_f32_16x16x32_bf16 v[36:39], v[168:171], v[192:195], v[36:39]
	v_mfma_f32_16x16x32_bf16 v[32:35], v[176:179], v[192:195], v[32:35]
	v_mfma_f32_16x16x32_bf16 v[20:23], v[168:171], v[200:203], v[20:23]
	v_mfma_f32_16x16x32_bf16 v[16:19], v[176:179], v[200:203], v[16:19]
	v_mfma_f32_16x16x32_bf16 v[4:7], v[168:171], v[208:211], v[4:7]
	v_mfma_f32_16x16x32_bf16 v[0:3], v[176:179], v[208:211], v[0:3]
	v_mfma_f32_16x16x32_bf16 v[52:55], v[172:175], v[188:191], v[52:55]
	v_mfma_f32_16x16x32_bf16 v[48:51], v[180:183], v[188:191], v[48:51]
	v_mfma_f32_16x16x32_bf16 v[36:39], v[172:175], v[196:199], v[36:39]
	v_mfma_f32_16x16x32_bf16 v[32:35], v[180:183], v[196:199], v[32:35]
	v_mfma_f32_16x16x32_bf16 v[20:23], v[172:175], v[204:207], v[20:23]
	v_mfma_f32_16x16x32_bf16 v[16:19], v[180:183], v[204:207], v[16:19]
	v_mfma_f32_16x16x32_bf16 v[4:7], v[172:175], v[212:215], v[4:7]
	v_mfma_f32_16x16x32_bf16 v[0:3], v[180:183], v[212:215], v[0:3]
	s_setprio 0
	s_barrier
	s_add_i32 s50, 0, 0x18000
	s_add_i32 s51, 0, 0x1c000
	v_add_u32_e32 v164, s50, v147
	v_add_u32_e32 v180, s51, v147
	ds_read_b128 v[152:155], v164
	ds_read_b128 v[156:159], v164 offset:1024
	ds_read_b128 v[160:163], v164 offset:2048
	ds_read_b128 v[164:167], v164 offset:3072
	ds_read_b128 v[168:171], v180
	ds_read_b128 v[172:175], v180 offset:1024
	ds_read_b128 v[176:179], v180 offset:2048
	ds_read_b128 v[180:183], v180 offset:3072
	s_add_u32 s28, s28, 0x40000
	s_addc_u32 s29, s29, 0
	s_mov_b32 m0, s34
	v_lshl_add_u64 v[222:223], s[28:29], 0, v[134:135]
	ds_read_b128 v[184:187], v151 offset:32768
	ds_read_b128 v[188:191], v151 offset:33792
	ds_read_b128 v[192:195], v151 offset:34816
	ds_read_b128 v[196:199], v151 offset:35840
	ds_read_b128 v[200:203], v151 offset:36864
	ds_read_b128 v[204:207], v151 offset:37888
	ds_read_b128 v[208:211], v151 offset:38912
	ds_read_b128 v[212:215], v151 offset:39936
	global_load_lds_dwordx4 v[222:223], off
	v_lshl_add_u64 v[222:223], s[28:29], 0, v[130:131]
	s_mov_b32 m0, s35
	s_nop 0
	global_load_lds_dwordx4 v[222:223], off
	s_waitcnt vmcnt(8)
	s_waitcnt lgkmcnt(0)
	s_setprio 1
	s_barrier
	s_waitcnt lgkmcnt(0)
	v_mfma_f32_16x16x32_bf16 v[124:127], v[152:155], v[184:187], v[124:127]
	v_mfma_f32_16x16x32_bf16 v[120:123], v[160:163], v[184:187], v[120:123]
	v_mfma_f32_16x16x32_bf16 v[108:111], v[152:155], v[192:195], v[108:111]
	v_mfma_f32_16x16x32_bf16 v[104:107], v[160:163], v[192:195], v[104:107]
	v_mfma_f32_16x16x32_bf16 v[92:95], v[152:155], v[200:203], v[92:95]
	v_mfma_f32_16x16x32_bf16 v[88:91], v[160:163], v[200:203], v[88:91]
	v_mfma_f32_16x16x32_bf16 v[76:79], v[152:155], v[208:211], v[76:79]
	v_mfma_f32_16x16x32_bf16 v[72:75], v[160:163], v[208:211], v[72:75]
	v_mfma_f32_16x16x32_bf16 v[124:127], v[156:159], v[188:191], v[124:127]
	v_mfma_f32_16x16x32_bf16 v[120:123], v[164:167], v[188:191], v[120:123]
	v_mfma_f32_16x16x32_bf16 v[108:111], v[156:159], v[196:199], v[108:111]
	v_mfma_f32_16x16x32_bf16 v[104:107], v[164:167], v[196:199], v[104:107]
	v_mfma_f32_16x16x32_bf16 v[92:95], v[156:159], v[204:207], v[92:95]
	v_mfma_f32_16x16x32_bf16 v[88:91], v[164:167], v[204:207], v[88:91]
	v_mfma_f32_16x16x32_bf16 v[76:79], v[156:159], v[212:215], v[76:79]
	v_mfma_f32_16x16x32_bf16 v[72:75], v[164:167], v[212:215], v[72:75]
	s_setprio 0
	s_setprio 1
	v_mfma_f32_16x16x32_bf16 v[116:119], v[168:171], v[184:187], v[116:119]
	v_mfma_f32_16x16x32_bf16 v[112:115], v[176:179], v[184:187], v[112:115]
	v_mfma_f32_16x16x32_bf16 v[100:103], v[168:171], v[192:195], v[100:103]
	v_mfma_f32_16x16x32_bf16 v[96:99], v[176:179], v[192:195], v[96:99]
	v_mfma_f32_16x16x32_bf16 v[84:87], v[168:171], v[200:203], v[84:87]
	v_mfma_f32_16x16x32_bf16 v[80:83], v[176:179], v[200:203], v[80:83]
	v_mfma_f32_16x16x32_bf16 v[68:71], v[168:171], v[208:211], v[68:71]
	v_mfma_f32_16x16x32_bf16 v[64:67], v[176:179], v[208:211], v[64:67]
	v_mfma_f32_16x16x32_bf16 v[116:119], v[172:175], v[188:191], v[116:119]
	v_mfma_f32_16x16x32_bf16 v[112:115], v[180:183], v[188:191], v[112:115]
	v_mfma_f32_16x16x32_bf16 v[100:103], v[172:175], v[196:199], v[100:103]
	v_mfma_f32_16x16x32_bf16 v[96:99], v[180:183], v[196:199], v[96:99]
	v_mfma_f32_16x16x32_bf16 v[84:87], v[172:175], v[204:207], v[84:87]
	v_mfma_f32_16x16x32_bf16 v[80:83], v[180:183], v[204:207], v[80:83]
	v_mfma_f32_16x16x32_bf16 v[68:71], v[172:175], v[212:215], v[68:71]
	v_mfma_f32_16x16x32_bf16 v[64:67], v[180:183], v[212:215], v[64:67]
	s_setprio 0
	s_barrier
	s_add_i32 s28, s50, s30
	v_lshl_add_u64 v[144:145], v[144:145], 0, s[12:13]
	s_mov_b32 m0, s28
	ds_read_b128 v[184:187], v151 offset:49152
	ds_read_b128 v[188:191], v151 offset:50176
	ds_read_b128 v[192:195], v151 offset:51200
	ds_read_b128 v[196:199], v151 offset:52224
	ds_read_b128 v[200:203], v151 offset:53248
	ds_read_b128 v[204:207], v151 offset:54272
	ds_read_b128 v[208:211], v151 offset:55296
	ds_read_b128 v[212:215], v151 offset:56320
	global_load_lds_dwordx4 v[144:145], off
	s_add_i32 m0, s28, 0x2000
	s_add_u32 s26, s26, 0x40080
	v_lshl_add_u64 v[144:145], v[216:217], 0, s[12:13]
	s_addc_u32 s27, s27, 0
	s_add_i32 s28, s51, s30
	global_load_lds_dwordx4 v[144:145], off
	v_lshl_add_u64 v[144:145], s[26:27], 0, v[132:133]
	s_mov_b32 m0, s28
	s_nop 0
	global_load_lds_dwordx4 v[144:145], off
	v_lshl_add_u64 v[144:145], s[26:27], 0, v[128:129]
	s_add_i32 m0, s28, 0x2000
	s_nop 0
	global_load_lds_dwordx4 v[144:145], off
	v_lshl_add_u64 v[144:145], v[218:219], 0, s[12:13]
	s_mov_b32 m0, s36
	s_nop 0
	global_load_lds_dwordx4 v[144:145], off
	v_lshl_add_u64 v[144:145], v[220:221], 0, s[12:13]
	s_mov_b32 m0, s37
	s_nop 0
	global_load_lds_dwordx4 v[144:145], off
	s_waitcnt vmcnt(8)
	s_waitcnt lgkmcnt(0)
	s_setprio 1
	s_barrier
	s_waitcnt lgkmcnt(0)
	v_mfma_f32_16x16x32_bf16 v[60:63], v[152:155], v[184:187], v[60:63]
	v_mfma_f32_16x16x32_bf16 v[56:59], v[160:163], v[184:187], v[56:59]
	v_mfma_f32_16x16x32_bf16 v[44:47], v[152:155], v[192:195], v[44:47]
	v_mfma_f32_16x16x32_bf16 v[40:43], v[160:163], v[192:195], v[40:43]
	v_mfma_f32_16x16x32_bf16 v[28:31], v[152:155], v[200:203], v[28:31]
	v_mfma_f32_16x16x32_bf16 v[24:27], v[160:163], v[200:203], v[24:27]
	v_mfma_f32_16x16x32_bf16 v[12:15], v[152:155], v[208:211], v[12:15]
	v_mfma_f32_16x16x32_bf16 v[8:11], v[160:163], v[208:211], v[8:11]
	v_mfma_f32_16x16x32_bf16 v[60:63], v[156:159], v[188:191], v[60:63]
	v_mfma_f32_16x16x32_bf16 v[56:59], v[164:167], v[188:191], v[56:59]
	v_mfma_f32_16x16x32_bf16 v[44:47], v[156:159], v[196:199], v[44:47]
	v_mfma_f32_16x16x32_bf16 v[40:43], v[164:167], v[196:199], v[40:43]
	v_mfma_f32_16x16x32_bf16 v[28:31], v[156:159], v[204:207], v[28:31]
	v_mfma_f32_16x16x32_bf16 v[24:27], v[164:167], v[204:207], v[24:27]
	v_mfma_f32_16x16x32_bf16 v[12:15], v[156:159], v[212:215], v[12:15]
	v_mfma_f32_16x16x32_bf16 v[8:11], v[164:167], v[212:215], v[8:11]
	s_setprio 0
	s_setprio 1
	v_mfma_f32_16x16x32_bf16 v[52:55], v[168:171], v[184:187], v[52:55]
	v_mfma_f32_16x16x32_bf16 v[48:51], v[176:179], v[184:187], v[48:51]
	v_mfma_f32_16x16x32_bf16 v[36:39], v[168:171], v[192:195], v[36:39]
	v_mfma_f32_16x16x32_bf16 v[32:35], v[176:179], v[192:195], v[32:35]
	v_mfma_f32_16x16x32_bf16 v[20:23], v[168:171], v[200:203], v[20:23]
	v_mfma_f32_16x16x32_bf16 v[16:19], v[176:179], v[200:203], v[16:19]
	v_mfma_f32_16x16x32_bf16 v[4:7], v[168:171], v[208:211], v[4:7]
	v_mfma_f32_16x16x32_bf16 v[0:3], v[176:179], v[208:211], v[0:3]
	v_mfma_f32_16x16x32_bf16 v[52:55], v[172:175], v[188:191], v[52:55]
	v_mfma_f32_16x16x32_bf16 v[48:51], v[180:183], v[188:191], v[48:51]
	v_mfma_f32_16x16x32_bf16 v[36:39], v[172:175], v[196:199], v[36:39]
	v_mfma_f32_16x16x32_bf16 v[32:35], v[180:183], v[196:199], v[32:35]
	v_mfma_f32_16x16x32_bf16 v[20:23], v[172:175], v[204:207], v[20:23]
	v_mfma_f32_16x16x32_bf16 v[16:19], v[180:183], v[204:207], v[16:19]
	v_mfma_f32_16x16x32_bf16 v[4:7], v[172:175], v[212:215], v[4:7]
	v_mfma_f32_16x16x32_bf16 v[0:3], v[180:183], v[212:215], v[0:3]
	s_setprio 0
	s_barrier
	s_add_i32 s49, s49, 2
	s_add_u32 s47, s47, 0x100
	s_addc_u32 s48, s48, 0
	s_add_u32 s24, s24, 0x100
	s_addc_u32 s25, s25, 0
	s_cmp_gt_u32 s49, 13
	s_cbranch_scc0 .LBB0_126
	s_and_b64 vcc, exec, s[14:15]
	s_cbranch_vccz .LBB0_129
	s_barrier

.LBB0_198:
	ds_read_b128 v[150:153], v147
	ds_read_b128 v[154:157], v147 offset:1024
	ds_read_b128 v[158:161], v147 offset:2048
	ds_read_b128 v[162:165], v147 offset:3072
	ds_read_b128 v[166:169], v148
	ds_read_b128 v[170:173], v148 offset:1024
	ds_read_b128 v[174:177], v148 offset:2048
	ds_read_b128 v[178:181], v148 offset:3072
	s_add_u32 s34, s30, 0x100
	s_addc_u32 s35, s31, 0
	s_cmp_eq_u32 s58, 40
	s_cselect_b32 s39, s7, s35
	s_cselect_b32 s38, s6, s34
	s_cselect_b32 s37, s29, s57
	s_cselect_b32 s36, s28, s56
	v_lshl_add_u64 v[214:215], s[30:31], 0, v[138:139]
	s_add_i32 m0, s33, 0xc000
	ds_read_b128 v[182:185], v149
	ds_read_b128 v[186:189], v149 offset:1024
	ds_read_b128 v[190:193], v149 offset:2048
	ds_read_b128 v[194:197], v149 offset:3072
	ds_read_b128 v[198:201], v149 offset:4096
	ds_read_b128 v[202:205], v149 offset:5120
	ds_read_b128 v[206:209], v149 offset:6144
	ds_read_b128 v[210:213], v149 offset:7168
	global_load_lds_dwordx4 v[214:215], off
	v_lshl_add_u64 v[214:215], s[30:31], 0, v[136:137]
	s_add_i32 m0, s33, 0xe000
	s_nop 0
	global_load_lds_dwordx4 v[214:215], off
	s_waitcnt vmcnt(8)
	s_waitcnt lgkmcnt(0)
	s_setprio 1
	s_barrier
	s_waitcnt lgkmcnt(0)
	v_mfma_f32_16x16x32_bf16 v[124:127], v[150:153], v[182:185], v[124:127]
	v_mfma_f32_16x16x32_bf16 v[120:123], v[158:161], v[182:185], v[120:123]
	v_mfma_f32_16x16x32_bf16 v[116:119], v[150:153], v[190:193], v[116:119]
	v_mfma_f32_16x16x32_bf16 v[112:115], v[158:161], v[190:193], v[112:115]
	v_mfma_f32_16x16x32_bf16 v[100:103], v[150:153], v[198:201], v[100:103]
	v_mfma_f32_16x16x32_bf16 v[96:99], v[158:161], v[198:201], v[96:99]
	v_mfma_f32_16x16x32_bf16 v[84:87], v[150:153], v[206:209], v[84:87]
	v_mfma_f32_16x16x32_bf16 v[80:83], v[158:161], v[206:209], v[80:83]
	v_mfma_f32_16x16x32_bf16 v[124:127], v[154:157], v[186:189], v[124:127]
	v_mfma_f32_16x16x32_bf16 v[120:123], v[162:165], v[186:189], v[120:123]
	v_mfma_f32_16x16x32_bf16 v[116:119], v[154:157], v[194:197], v[116:119]
	v_mfma_f32_16x16x32_bf16 v[112:115], v[162:165], v[194:197], v[112:115]
	v_mfma_f32_16x16x32_bf16 v[100:103], v[154:157], v[202:205], v[100:103]
	v_mfma_f32_16x16x32_bf16 v[96:99], v[162:165], v[202:205], v[96:99]
	v_mfma_f32_16x16x32_bf16 v[84:87], v[154:157], v[210:213], v[84:87]
	v_mfma_f32_16x16x32_bf16 v[80:83], v[162:165], v[210:213], v[80:83]
	s_setprio 0
	s_setprio 1
	v_mfma_f32_16x16x32_bf16 v[108:111], v[166:169], v[182:185], v[108:111]
	v_mfma_f32_16x16x32_bf16 v[104:107], v[174:177], v[182:185], v[104:107]
	v_mfma_f32_16x16x32_bf16 v[92:95], v[166:169], v[190:193], v[92:95]
	v_mfma_f32_16x16x32_bf16 v[88:91], v[174:177], v[190:193], v[88:91]
	v_mfma_f32_16x16x32_bf16 v[76:79], v[166:169], v[198:201], v[76:79]
	v_mfma_f32_16x16x32_bf16 v[72:75], v[174:177], v[198:201], v[72:75]
	v_mfma_f32_16x16x32_bf16 v[68:71], v[166:169], v[206:209], v[68:71]
	v_mfma_f32_16x16x32_bf16 v[64:67], v[174:177], v[206:209], v[64:67]
	v_mfma_f32_16x16x32_bf16 v[108:111], v[170:173], v[186:189], v[108:111]
	v_mfma_f32_16x16x32_bf16 v[104:107], v[178:181], v[186:189], v[104:107]
	v_mfma_f32_16x16x32_bf16 v[92:95], v[170:173], v[194:197], v[92:95]
	v_mfma_f32_16x16x32_bf16 v[88:91], v[178:181], v[194:197], v[88:91]
	v_mfma_f32_16x16x32_bf16 v[76:79], v[170:173], v[202:205], v[76:79]
	v_mfma_f32_16x16x32_bf16 v[72:75], v[178:181], v[202:205], v[72:75]
	v_mfma_f32_16x16x32_bf16 v[68:71], v[170:173], v[210:213], v[68:71]
	v_mfma_f32_16x16x32_bf16 v[64:67], v[178:181], v[210:213], v[64:67]
	s_setprio 0
	s_barrier
	s_add_i32 s30, s46, s1
	v_lshl_add_u64 v[214:215], s[36:37], 0, v[132:133]
	s_mov_b32 m0, s30
	ds_read_b128 v[182:185], v149 offset:16384
	ds_read_b128 v[186:189], v149 offset:17408
	ds_read_b128 v[190:193], v149 offset:18432
	ds_read_b128 v[194:197], v149 offset:19456
	ds_read_b128 v[198:201], v149 offset:20480
	ds_read_b128 v[202:205], v149 offset:21504
	ds_read_b128 v[206:209], v149 offset:22528
	ds_read_b128 v[210:213], v149 offset:23552
	global_load_lds_dwordx4 v[214:215], off
	s_add_i32 m0, s30, 0x2000
	s_add_u32 s30, s36, 0xb0000
	v_lshl_add_u64 v[216:217], s[36:37], 0, v[128:129]
	s_addc_u32 s31, s37, 0
	s_add_i32 s59, s47, s1
	global_load_lds_dwordx4 v[216:217], off
	v_lshl_add_u64 v[218:219], s[30:31], 0, v[132:133]
	s_mov_b32 m0, s59
	v_lshl_add_u64 v[220:221], s[38:39], 0, v[130:131]
	global_load_lds_dwordx4 v[218:219], off
	v_lshl_add_u64 v[218:219], s[30:31], 0, v[128:129]
	s_add_i32 m0, s59, 0x2000
	s_nop 0
	global_load_lds_dwordx4 v[218:219], off
	v_lshl_add_u64 v[218:219], s[38:39], 0, v[134:135]
	s_mov_b32 m0, s33
	s_nop 0
	global_load_lds_dwordx4 v[218:219], off
	s_mov_b32 m0, s40
	s_nop 0
	global_load_lds_dwordx4 v[220:221], off
	s_waitcnt vmcnt(8)
	s_waitcnt lgkmcnt(0)
	s_setprio 1
	s_barrier
	s_waitcnt lgkmcnt(0)
	v_mfma_f32_16x16x32_bf16 v[60:63], v[150:153], v[182:185], v[60:63]
	v_mfma_f32_16x16x32_bf16 v[56:59], v[158:161], v[182:185], v[56:59]
	v_mfma_f32_16x16x32_bf16 v[52:55], v[150:153], v[190:193], v[52:55]
	v_mfma_f32_16x16x32_bf16 v[48:51], v[158:161], v[190:193], v[48:51]
	v_mfma_f32_16x16x32_bf16 v[36:39], v[150:153], v[198:201], v[36:39]
	v_mfma_f32_16x16x32_bf16 v[32:35], v[158:161], v[198:201], v[32:35]
	v_mfma_f32_16x16x32_bf16 v[20:23], v[150:153], v[206:209], v[20:23]
	v_mfma_f32_16x16x32_bf16 v[16:19], v[158:161], v[206:209], v[16:19]
	v_mfma_f32_16x16x32_bf16 v[60:63], v[154:157], v[186:189], v[60:63]
	v_mfma_f32_16x16x32_bf16 v[56:59], v[162:165], v[186:189], v[56:59]
	v_mfma_f32_16x16x32_bf16 v[52:55], v[154:157], v[194:197], v[52:55]
	v_mfma_f32_16x16x32_bf16 v[48:51], v[162:165], v[194:197], v[48:51]
	v_mfma_f32_16x16x32_bf16 v[36:39], v[154:157], v[202:205], v[36:39]
	v_mfma_f32_16x16x32_bf16 v[32:35], v[162:165], v[202:205], v[32:35]
	v_mfma_f32_16x16x32_bf16 v[20:23], v[154:157], v[210:213], v[20:23]
	v_mfma_f32_16x16x32_bf16 v[16:19], v[162:165], v[210:213], v[16:19]
	s_setprio 0
	s_setprio 1
	v_mfma_f32_16x16x32_bf16 v[44:47], v[166:169], v[182:185], v[44:47]
	v_mfma_f32_16x16x32_bf16 v[40:43], v[174:177], v[182:185], v[40:43]
	v_mfma_f32_16x16x32_bf16 v[28:31], v[166:169], v[190:193], v[28:31]
	v_mfma_f32_16x16x32_bf16 v[24:27], v[174:177], v[190:193], v[24:27]
	v_mfma_f32_16x16x32_bf16 v[12:15], v[166:169], v[198:201], v[12:15]
	v_mfma_f32_16x16x32_bf16 v[8:11], v[174:177], v[198:201], v[8:11]
	v_mfma_f32_16x16x32_bf16 v[4:7], v[166:169], v[206:209], v[4:7]
	v_mfma_f32_16x16x32_bf16 v[0:3], v[174:177], v[206:209], v[0:3]
	v_mfma_f32_16x16x32_bf16 v[44:47], v[170:173], v[186:189], v[44:47]
	v_mfma_f32_16x16x32_bf16 v[40:43], v[178:181], v[186:189], v[40:43]
	v_mfma_f32_16x16x32_bf16 v[28:31], v[170:173], v[194:197], v[28:31]
	v_mfma_f32_16x16x32_bf16 v[24:27], v[178:181], v[194:197], v[24:27]
	v_mfma_f32_16x16x32_bf16 v[12:15], v[170:173], v[202:205], v[12:15]
	v_mfma_f32_16x16x32_bf16 v[8:11], v[178:181], v[202:205], v[8:11]
	v_mfma_f32_16x16x32_bf16 v[4:7], v[170:173], v[210:213], v[4:7]
	v_mfma_f32_16x16x32_bf16 v[0:3], v[178:181], v[210:213], v[0:3]
	s_setprio 0
	s_barrier
	s_add_i32 s59, 0, 0x18000
	s_add_i32 s60, 0, 0x1c000
	v_add_u32_e32 v162, s59, v145
	v_add_u32_e32 v178, s60, v145
	ds_read_b128 v[150:153], v162
	ds_read_b128 v[154:157], v162 offset:1024
	ds_read_b128 v[158:161], v162 offset:2048
	ds_read_b128 v[162:165], v162 offset:3072
	ds_read_b128 v[166:169], v178
	ds_read_b128 v[170:173], v178 offset:1024
	ds_read_b128 v[174:177], v178 offset:2048
	ds_read_b128 v[178:181], v178 offset:3072
	s_add_u32 s30, s38, 0xb0000
	s_addc_u32 s31, s39, 0
	s_mov_b32 m0, s41
	v_lshl_add_u64 v[222:223], s[30:31], 0, v[134:135]
	ds_read_b128 v[182:185], v149 offset:32768
	ds_read_b128 v[186:189], v149 offset:33792
	ds_read_b128 v[190:193], v149 offset:34816
	ds_read_b128 v[194:197], v149 offset:35840
	ds_read_b128 v[198:201], v149 offset:36864
	ds_read_b128 v[202:205], v149 offset:37888
	ds_read_b128 v[206:209], v149 offset:38912
	ds_read_b128 v[210:213], v149 offset:39936
	global_load_lds_dwordx4 v[222:223], off
	v_lshl_add_u64 v[222:223], s[30:31], 0, v[130:131]
	s_mov_b32 m0, s42
	s_nop 0
	global_load_lds_dwordx4 v[222:223], off
	s_waitcnt vmcnt(8)
	s_waitcnt lgkmcnt(0)
	s_setprio 1
	s_barrier
	s_waitcnt lgkmcnt(0)
	v_mfma_f32_16x16x32_bf16 v[124:127], v[150:153], v[182:185], v[124:127]
	v_mfma_f32_16x16x32_bf16 v[120:123], v[158:161], v[182:185], v[120:123]
	v_mfma_f32_16x16x32_bf16 v[116:119], v[150:153], v[190:193], v[116:119]
	v_mfma_f32_16x16x32_bf16 v[112:115], v[158:161], v[190:193], v[112:115]
	v_mfma_f32_16x16x32_bf16 v[100:103], v[150:153], v[198:201], v[100:103]
	v_mfma_f32_16x16x32_bf16 v[96:99], v[158:161], v[198:201], v[96:99]
	v_mfma_f32_16x16x32_bf16 v[84:87], v[150:153], v[206:209], v[84:87]
	v_mfma_f32_16x16x32_bf16 v[80:83], v[158:161], v[206:209], v[80:83]
	v_mfma_f32_16x16x32_bf16 v[124:127], v[154:157], v[186:189], v[124:127]
	v_mfma_f32_16x16x32_bf16 v[120:123], v[162:165], v[186:189], v[120:123]
	v_mfma_f32_16x16x32_bf16 v[116:119], v[154:157], v[194:197], v[116:119]
	v_mfma_f32_16x16x32_bf16 v[112:115], v[162:165], v[194:197], v[112:115]
	v_mfma_f32_16x16x32_bf16 v[100:103], v[154:157], v[202:205], v[100:103]
	v_mfma_f32_16x16x32_bf16 v[96:99], v[162:165], v[202:205], v[96:99]
	v_mfma_f32_16x16x32_bf16 v[84:87], v[154:157], v[210:213], v[84:87]
	v_mfma_f32_16x16x32_bf16 v[80:83], v[162:165], v[210:213], v[80:83]
	s_setprio 0
	s_setprio 1
	v_mfma_f32_16x16x32_bf16 v[108:111], v[166:169], v[182:185], v[108:111]
	v_mfma_f32_16x16x32_bf16 v[104:107], v[174:177], v[182:185], v[104:107]
	v_mfma_f32_16x16x32_bf16 v[92:95], v[166:169], v[190:193], v[92:95]
	v_mfma_f32_16x16x32_bf16 v[88:91], v[174:177], v[190:193], v[88:91]
	v_mfma_f32_16x16x32_bf16 v[76:79], v[166:169], v[198:201], v[76:79]
	v_mfma_f32_16x16x32_bf16 v[72:75], v[174:177], v[198:201], v[72:75]
	v_mfma_f32_16x16x32_bf16 v[68:71], v[166:169], v[206:209], v[68:71]
	v_mfma_f32_16x16x32_bf16 v[64:67], v[174:177], v[206:209], v[64:67]
	v_mfma_f32_16x16x32_bf16 v[108:111], v[170:173], v[186:189], v[108:111]
	v_mfma_f32_16x16x32_bf16 v[104:107], v[178:181], v[186:189], v[104:107]
	v_mfma_f32_16x16x32_bf16 v[92:95], v[170:173], v[194:197], v[92:95]
	v_mfma_f32_16x16x32_bf16 v[88:91], v[178:181], v[194:197], v[88:91]
	v_mfma_f32_16x16x32_bf16 v[76:79], v[170:173], v[202:205], v[76:79]
	v_mfma_f32_16x16x32_bf16 v[72:75], v[178:181], v[202:205], v[72:75]
	v_mfma_f32_16x16x32_bf16 v[68:71], v[170:173], v[210:213], v[68:71]
	v_mfma_f32_16x16x32_bf16 v[64:67], v[178:181], v[210:213], v[64:67]
	s_setprio 0
	s_barrier
	s_add_i32 s30, s59, s1
	v_lshl_add_u64 v[214:215], v[214:215], 0, s[16:17]
	s_mov_b32 m0, s30
	ds_read_b128 v[182:185], v149 offset:49152
	ds_read_b128 v[186:189], v149 offset:50176
	ds_read_b128 v[190:193], v149 offset:51200
	ds_read_b128 v[194:197], v149 offset:52224
	ds_read_b128 v[198:201], v149 offset:53248
	ds_read_b128 v[202:205], v149 offset:54272
	ds_read_b128 v[206:209], v149 offset:55296
	ds_read_b128 v[210:213], v149 offset:56320
	global_load_lds_dwordx4 v[214:215], off
	s_add_i32 m0, s30, 0x2000
	s_add_u32 s30, s36, 0xb0080
	v_lshl_add_u64 v[214:215], v[216:217], 0, s[16:17]
	s_addc_u32 s31, s37, 0
	s_add_i32 s36, s60, s1
	global_load_lds_dwordx4 v[214:215], off
	v_lshl_add_u64 v[214:215], s[30:31], 0, v[132:133]
	s_mov_b32 m0, s36
	s_nop 0
	global_load_lds_dwordx4 v[214:215], off
	v_lshl_add_u64 v[214:215], s[30:31], 0, v[128:129]
	s_add_i32 m0, s36, 0x2000
	s_nop 0
	global_load_lds_dwordx4 v[214:215], off
	v_lshl_add_u64 v[214:215], v[218:219], 0, s[16:17]
	s_mov_b32 m0, s44
	s_nop 0
	global_load_lds_dwordx4 v[214:215], off
	v_lshl_add_u64 v[214:215], v[220:221], 0, s[16:17]
	s_mov_b32 m0, s45
	s_nop 0
	global_load_lds_dwordx4 v[214:215], off
	s_waitcnt vmcnt(8)
	s_waitcnt lgkmcnt(0)
	s_setprio 1
	s_barrier
	s_waitcnt lgkmcnt(0)
	v_mfma_f32_16x16x32_bf16 v[60:63], v[150:153], v[182:185], v[60:63]
	v_mfma_f32_16x16x32_bf16 v[56:59], v[158:161], v[182:185], v[56:59]
	v_mfma_f32_16x16x32_bf16 v[52:55], v[150:153], v[190:193], v[52:55]
	v_mfma_f32_16x16x32_bf16 v[48:51], v[158:161], v[190:193], v[48:51]
	v_mfma_f32_16x16x32_bf16 v[36:39], v[150:153], v[198:201], v[36:39]
	v_mfma_f32_16x16x32_bf16 v[32:35], v[158:161], v[198:201], v[32:35]
	v_mfma_f32_16x16x32_bf16 v[20:23], v[150:153], v[206:209], v[20:23]
	v_mfma_f32_16x16x32_bf16 v[16:19], v[158:161], v[206:209], v[16:19]
	v_mfma_f32_16x16x32_bf16 v[60:63], v[154:157], v[186:189], v[60:63]
	v_mfma_f32_16x16x32_bf16 v[56:59], v[162:165], v[186:189], v[56:59]
	v_mfma_f32_16x16x32_bf16 v[52:55], v[154:157], v[194:197], v[52:55]
	v_mfma_f32_16x16x32_bf16 v[48:51], v[162:165], v[194:197], v[48:51]
	v_mfma_f32_16x16x32_bf16 v[36:39], v[154:157], v[202:205], v[36:39]
	v_mfma_f32_16x16x32_bf16 v[32:35], v[162:165], v[202:205], v[32:35]
	v_mfma_f32_16x16x32_bf16 v[20:23], v[154:157], v[210:213], v[20:23]
	v_mfma_f32_16x16x32_bf16 v[16:19], v[162:165], v[210:213], v[16:19]
	s_setprio 0
	s_setprio 1
	v_mfma_f32_16x16x32_bf16 v[44:47], v[166:169], v[182:185], v[44:47]
	v_mfma_f32_16x16x32_bf16 v[40:43], v[174:177], v[182:185], v[40:43]
	v_mfma_f32_16x16x32_bf16 v[28:31], v[166:169], v[190:193], v[28:31]
	v_mfma_f32_16x16x32_bf16 v[24:27], v[174:177], v[190:193], v[24:27]
	v_mfma_f32_16x16x32_bf16 v[12:15], v[166:169], v[198:201], v[12:15]
	v_mfma_f32_16x16x32_bf16 v[8:11], v[174:177], v[198:201], v[8:11]
	v_mfma_f32_16x16x32_bf16 v[4:7], v[166:169], v[206:209], v[4:7]
	v_mfma_f32_16x16x32_bf16 v[0:3], v[174:177], v[206:209], v[0:3]
	v_mfma_f32_16x16x32_bf16 v[44:47], v[170:173], v[186:189], v[44:47]
	v_mfma_f32_16x16x32_bf16 v[40:43], v[178:181], v[186:189], v[40:43]
	v_mfma_f32_16x16x32_bf16 v[28:31], v[170:173], v[194:197], v[28:31]
	v_mfma_f32_16x16x32_bf16 v[24:27], v[178:181], v[194:197], v[24:27]
	v_mfma_f32_16x16x32_bf16 v[12:15], v[170:173], v[202:205], v[12:15]
	v_mfma_f32_16x16x32_bf16 v[8:11], v[178:181], v[202:205], v[8:11]
	v_mfma_f32_16x16x32_bf16 v[4:7], v[170:173], v[210:213], v[4:7]
	v_mfma_f32_16x16x32_bf16 v[0:3], v[178:181], v[210:213], v[0:3]
	s_setprio 0
	s_barrier
	s_add_i32 s58, s58, 2
	s_add_u32 s56, s56, 0x100
	s_addc_u32 s57, s57, 0
	s_cmp_gt_u32 s58, 41
	s_mov_b64 s[30:31], s[34:35]
	s_cbranch_scc0 .LBB0_198
	s_and_b64 vcc, exec, s[18:19]
	s_cbranch_vccz .LBB0_201
	s_barrier

.LBB0_356:
	ds_read_b128 v[152:155], v148
	ds_read_b128 v[156:159], v148 offset:1024
	ds_read_b128 v[160:163], v148 offset:2048
	ds_read_b128 v[164:167], v148 offset:3072
	ds_read_b128 v[168:171], v149
	ds_read_b128 v[172:175], v149 offset:1024
	ds_read_b128 v[176:179], v149 offset:2048
	ds_read_b128 v[180:183], v149 offset:3072
	s_add_u32 s28, s26, 0xfffc0080
	s_addc_u32 s29, s27, -1
	s_cmp_eq_u32 s49, 12
	s_cselect_b32 s31, s19, s29
	s_cselect_b32 s30, s45, s28
	s_cselect_b32 s29, s17, s48
	s_cselect_b32 s28, s46, s47
	v_lshl_add_u64 v[216:217], s[26:27], 0, v[138:139]
	s_add_i32 m0, s25, 0xc000
	ds_read_b128 v[184:187], v150
	ds_read_b128 v[188:191], v150 offset:1024
	ds_read_b128 v[192:195], v150 offset:2048
	ds_read_b128 v[196:199], v150 offset:3072
	ds_read_b128 v[200:203], v150 offset:4096
	ds_read_b128 v[204:207], v150 offset:5120
	ds_read_b128 v[208:211], v150 offset:6144
	ds_read_b128 v[212:215], v150 offset:7168
	global_load_lds_dwordx4 v[216:217], off
	v_lshl_add_u64 v[216:217], s[26:27], 0, v[136:137]
	s_add_i32 m0, s25, 0xe000
	s_nop 0
	global_load_lds_dwordx4 v[216:217], off
	s_waitcnt vmcnt(8)
	s_waitcnt lgkmcnt(0)
	s_setprio 1
	s_barrier
	s_waitcnt lgkmcnt(0)
	v_mfma_f32_16x16x32_bf16 v[124:127], v[152:155], v[184:187], v[124:127]
	v_mfma_f32_16x16x32_bf16 v[120:123], v[160:163], v[184:187], v[120:123]
	v_mfma_f32_16x16x32_bf16 v[116:119], v[152:155], v[192:195], v[116:119]
	v_mfma_f32_16x16x32_bf16 v[108:111], v[160:163], v[192:195], v[108:111]
	v_mfma_f32_16x16x32_bf16 v[100:103], v[152:155], v[200:203], v[100:103]
	v_mfma_f32_16x16x32_bf16 v[92:95], v[160:163], v[200:203], v[92:95]
	v_mfma_f32_16x16x32_bf16 v[84:87], v[152:155], v[208:211], v[84:87]
	v_mfma_f32_16x16x32_bf16 v[76:79], v[160:163], v[208:211], v[76:79]
	v_mfma_f32_16x16x32_bf16 v[124:127], v[156:159], v[188:191], v[124:127]
	v_mfma_f32_16x16x32_bf16 v[120:123], v[164:167], v[188:191], v[120:123]
	v_mfma_f32_16x16x32_bf16 v[116:119], v[156:159], v[196:199], v[116:119]
	v_mfma_f32_16x16x32_bf16 v[108:111], v[164:167], v[196:199], v[108:111]
	v_mfma_f32_16x16x32_bf16 v[100:103], v[156:159], v[204:207], v[100:103]
	v_mfma_f32_16x16x32_bf16 v[92:95], v[164:167], v[204:207], v[92:95]
	v_mfma_f32_16x16x32_bf16 v[84:87], v[156:159], v[212:215], v[84:87]
	v_mfma_f32_16x16x32_bf16 v[76:79], v[164:167], v[212:215], v[76:79]
	s_setprio 0
	s_setprio 1
	v_mfma_f32_16x16x32_bf16 v[112:115], v[168:171], v[184:187], v[112:115]
	v_mfma_f32_16x16x32_bf16 v[104:107], v[176:179], v[184:187], v[104:107]
	v_mfma_f32_16x16x32_bf16 v[96:99], v[168:171], v[192:195], v[96:99]
	v_mfma_f32_16x16x32_bf16 v[88:91], v[176:179], v[192:195], v[88:91]
	v_mfma_f32_16x16x32_bf16 v[80:83], v[168:171], v[200:203], v[80:83]
	v_mfma_f32_16x16x32_bf16 v[72:75], v[176:179], v[200:203], v[72:75]
	v_mfma_f32_16x16x32_bf16 v[68:71], v[168:171], v[208:211], v[68:71]
	v_mfma_f32_16x16x32_bf16 v[64:67], v[176:179], v[208:211], v[64:67]
	v_mfma_f32_16x16x32_bf16 v[112:115], v[172:175], v[188:191], v[112:115]
	v_mfma_f32_16x16x32_bf16 v[104:107], v[180:183], v[188:191], v[104:107]
	v_mfma_f32_16x16x32_bf16 v[96:99], v[172:175], v[196:199], v[96:99]
	v_mfma_f32_16x16x32_bf16 v[88:91], v[180:183], v[196:199], v[88:91]
	v_mfma_f32_16x16x32_bf16 v[80:83], v[172:175], v[204:207], v[80:83]
	v_mfma_f32_16x16x32_bf16 v[72:75], v[180:183], v[204:207], v[72:75]
	v_mfma_f32_16x16x32_bf16 v[68:71], v[172:175], v[212:215], v[68:71]
	v_mfma_f32_16x16x32_bf16 v[64:67], v[180:183], v[212:215], v[64:67]
	s_setprio 0
	s_barrier
	s_add_i32 s50, s41, s33
	v_lshl_add_u64 v[216:217], s[28:29], 0, v[132:133]
	s_mov_b32 m0, s50
	ds_read_b128 v[184:187], v150 offset:16384
	ds_read_b128 v[188:191], v150 offset:17408
	ds_read_b128 v[192:195], v150 offset:18432
	ds_read_b128 v[196:199], v150 offset:19456
	ds_read_b128 v[200:203], v150 offset:20480
	ds_read_b128 v[204:207], v150 offset:21504
	ds_read_b128 v[208:211], v150 offset:22528
	ds_read_b128 v[212:215], v150 offset:23552
	global_load_lds_dwordx4 v[216:217], off
	s_add_i32 m0, s50, 0x2000
	s_add_u32 s50, s28, 0x40000
	v_lshl_add_u64 v[218:219], s[28:29], 0, v[128:129]
	s_addc_u32 s51, s29, 0
	s_add_i32 s52, s42, s33
	global_load_lds_dwordx4 v[218:219], off
	v_lshl_add_u64 v[220:221], s[50:51], 0, v[132:133]
	s_mov_b32 m0, s52
	v_lshl_add_u64 v[222:223], s[30:31], 0, v[130:131]
	global_load_lds_dwordx4 v[220:221], off
	v_lshl_add_u64 v[220:221], s[50:51], 0, v[128:129]
	s_add_i32 m0, s52, 0x2000
	s_nop 0
	global_load_lds_dwordx4 v[220:221], off
	v_lshl_add_u64 v[220:221], s[30:31], 0, v[134:135]
	s_mov_b32 m0, s25
	s_nop 0
	global_load_lds_dwordx4 v[220:221], off
	s_mov_b32 m0, s35
	s_nop 0
	global_load_lds_dwordx4 v[222:223], off
	s_waitcnt vmcnt(8)
	s_waitcnt lgkmcnt(0)
	s_setprio 1
	s_barrier
	s_waitcnt lgkmcnt(0)
	v_mfma_f32_16x16x32_bf16 v[60:63], v[152:155], v[184:187], v[60:63]
	v_mfma_f32_16x16x32_bf16 v[56:59], v[160:163], v[184:187], v[56:59]
	v_mfma_f32_16x16x32_bf16 v[52:55], v[152:155], v[192:195], v[52:55]
	v_mfma_f32_16x16x32_bf16 v[44:47], v[160:163], v[192:195], v[44:47]
	v_mfma_f32_16x16x32_bf16 v[36:39], v[152:155], v[200:203], v[36:39]
	v_mfma_f32_16x16x32_bf16 v[28:31], v[160:163], v[200:203], v[28:31]
	v_mfma_f32_16x16x32_bf16 v[20:23], v[152:155], v[208:211], v[20:23]
	v_mfma_f32_16x16x32_bf16 v[12:15], v[160:163], v[208:211], v[12:15]
	v_mfma_f32_16x16x32_bf16 v[60:63], v[156:159], v[188:191], v[60:63]
	v_mfma_f32_16x16x32_bf16 v[56:59], v[164:167], v[188:191], v[56:59]
	v_mfma_f32_16x16x32_bf16 v[52:55], v[156:159], v[196:199], v[52:55]
	v_mfma_f32_16x16x32_bf16 v[44:47], v[164:167], v[196:199], v[44:47]
	v_mfma_f32_16x16x32_bf16 v[36:39], v[156:159], v[204:207], v[36:39]
	v_mfma_f32_16x16x32_bf16 v[28:31], v[164:167], v[204:207], v[28:31]
	v_mfma_f32_16x16x32_bf16 v[20:23], v[156:159], v[212:215], v[20:23]
	v_mfma_f32_16x16x32_bf16 v[12:15], v[164:167], v[212:215], v[12:15]
	s_setprio 0
	s_setprio 1
	v_mfma_f32_16x16x32_bf16 v[48:51], v[168:171], v[184:187], v[48:51]
	v_mfma_f32_16x16x32_bf16 v[40:43], v[176:179], v[184:187], v[40:43]
	v_mfma_f32_16x16x32_bf16 v[32:35], v[168:171], v[192:195], v[32:35]
	v_mfma_f32_16x16x32_bf16 v[24:27], v[176:179], v[192:195], v[24:27]
	v_mfma_f32_16x16x32_bf16 v[16:19], v[168:171], v[200:203], v[16:19]
	v_mfma_f32_16x16x32_bf16 v[8:11], v[176:179], v[200:203], v[8:11]
	v_mfma_f32_16x16x32_bf16 v[4:7], v[168:171], v[208:211], v[4:7]
	v_mfma_f32_16x16x32_bf16 v[0:3], v[176:179], v[208:211], v[0:3]
	v_mfma_f32_16x16x32_bf16 v[48:51], v[172:175], v[188:191], v[48:51]
	v_mfma_f32_16x16x32_bf16 v[40:43], v[180:183], v[188:191], v[40:43]
	v_mfma_f32_16x16x32_bf16 v[32:35], v[172:175], v[196:199], v[32:35]
	v_mfma_f32_16x16x32_bf16 v[24:27], v[180:183], v[196:199], v[24:27]
	v_mfma_f32_16x16x32_bf16 v[16:19], v[172:175], v[204:207], v[16:19]
	v_mfma_f32_16x16x32_bf16 v[8:11], v[180:183], v[204:207], v[8:11]
	v_mfma_f32_16x16x32_bf16 v[4:7], v[172:175], v[212:215], v[4:7]
	v_mfma_f32_16x16x32_bf16 v[0:3], v[180:183], v[212:215], v[0:3]
	s_setprio 0
	s_barrier
	s_add_i32 s50, 0, 0x18000
	v_add_u32_e32 v144, s50, v146
	s_add_i32 s51, 0, 0x1c000
	ds_read_b128 v[152:155], v144
	ds_read_b128 v[156:159], v144 offset:1024
	ds_read_b128 v[160:163], v144 offset:2048
	ds_read_b128 v[164:167], v144 offset:3072
	v_add_u32_e32 v144, s51, v146
	ds_read_b128 v[168:171], v144
	ds_read_b128 v[172:175], v144 offset:1024
	ds_read_b128 v[176:179], v144 offset:2048
	ds_read_b128 v[180:183], v144 offset:3072
	s_add_u32 s30, s30, 0x40000
	s_addc_u32 s31, s31, 0
	s_mov_b32 m0, s36
	v_lshl_add_u64 v[224:225], s[30:31], 0, v[134:135]
	ds_read_b128 v[184:187], v150 offset:32768
	ds_read_b128 v[188:191], v150 offset:33792
	ds_read_b128 v[192:195], v150 offset:34816
	ds_read_b128 v[196:199], v150 offset:35840
	ds_read_b128 v[200:203], v150 offset:36864
	ds_read_b128 v[204:207], v150 offset:37888
	ds_read_b128 v[208:211], v150 offset:38912
	ds_read_b128 v[212:215], v150 offset:39936
	global_load_lds_dwordx4 v[224:225], off
	v_lshl_add_u64 v[224:225], s[30:31], 0, v[130:131]
	s_mov_b32 m0, s37
	s_nop 0
	global_load_lds_dwordx4 v[224:225], off
	s_waitcnt vmcnt(8)
	s_waitcnt lgkmcnt(0)
	s_setprio 1
	s_barrier
	s_waitcnt lgkmcnt(0)
	v_mfma_f32_16x16x32_bf16 v[124:127], v[152:155], v[184:187], v[124:127]
	v_mfma_f32_16x16x32_bf16 v[120:123], v[160:163], v[184:187], v[120:123]
	v_mfma_f32_16x16x32_bf16 v[116:119], v[152:155], v[192:195], v[116:119]
	v_mfma_f32_16x16x32_bf16 v[108:111], v[160:163], v[192:195], v[108:111]
	v_mfma_f32_16x16x32_bf16 v[100:103], v[152:155], v[200:203], v[100:103]
	v_mfma_f32_16x16x32_bf16 v[92:95], v[160:163], v[200:203], v[92:95]
	v_mfma_f32_16x16x32_bf16 v[84:87], v[152:155], v[208:211], v[84:87]
	v_mfma_f32_16x16x32_bf16 v[76:79], v[160:163], v[208:211], v[76:79]
	v_mfma_f32_16x16x32_bf16 v[124:127], v[156:159], v[188:191], v[124:127]
	v_mfma_f32_16x16x32_bf16 v[120:123], v[164:167], v[188:191], v[120:123]
	v_mfma_f32_16x16x32_bf16 v[116:119], v[156:159], v[196:199], v[116:119]
	v_mfma_f32_16x16x32_bf16 v[108:111], v[164:167], v[196:199], v[108:111]
	v_mfma_f32_16x16x32_bf16 v[100:103], v[156:159], v[204:207], v[100:103]
	v_mfma_f32_16x16x32_bf16 v[92:95], v[164:167], v[204:207], v[92:95]
	v_mfma_f32_16x16x32_bf16 v[84:87], v[156:159], v[212:215], v[84:87]
	v_mfma_f32_16x16x32_bf16 v[76:79], v[164:167], v[212:215], v[76:79]
	s_setprio 0
	s_setprio 1
	v_mfma_f32_16x16x32_bf16 v[112:115], v[168:171], v[184:187], v[112:115]
	v_mfma_f32_16x16x32_bf16 v[104:107], v[176:179], v[184:187], v[104:107]
	v_mfma_f32_16x16x32_bf16 v[96:99], v[168:171], v[192:195], v[96:99]
	v_mfma_f32_16x16x32_bf16 v[88:91], v[176:179], v[192:195], v[88:91]
	v_mfma_f32_16x16x32_bf16 v[80:83], v[168:171], v[200:203], v[80:83]
	v_mfma_f32_16x16x32_bf16 v[72:75], v[176:179], v[200:203], v[72:75]
	v_mfma_f32_16x16x32_bf16 v[68:71], v[168:171], v[208:211], v[68:71]
	v_mfma_f32_16x16x32_bf16 v[64:67], v[176:179], v[208:211], v[64:67]
	v_mfma_f32_16x16x32_bf16 v[112:115], v[172:175], v[188:191], v[112:115]
	v_mfma_f32_16x16x32_bf16 v[104:107], v[180:183], v[188:191], v[104:107]
	v_mfma_f32_16x16x32_bf16 v[96:99], v[172:175], v[196:199], v[96:99]
	v_mfma_f32_16x16x32_bf16 v[88:91], v[180:183], v[196:199], v[88:91]
	v_mfma_f32_16x16x32_bf16 v[80:83], v[172:175], v[204:207], v[80:83]
	v_mfma_f32_16x16x32_bf16 v[72:75], v[180:183], v[204:207], v[72:75]
	v_mfma_f32_16x16x32_bf16 v[68:71], v[172:175], v[212:215], v[68:71]
	v_mfma_f32_16x16x32_bf16 v[64:67], v[180:183], v[212:215], v[64:67]
	s_setprio 0
	s_barrier
	s_add_i32 s30, s50, s33
	v_lshl_add_u64 v[216:217], v[216:217], 0, s[12:13]
	s_mov_b32 m0, s30
	ds_read_b128 v[184:187], v150 offset:49152
	ds_read_b128 v[188:191], v150 offset:50176
	ds_read_b128 v[192:195], v150 offset:51200
	ds_read_b128 v[196:199], v150 offset:52224
	ds_read_b128 v[200:203], v150 offset:53248
	ds_read_b128 v[204:207], v150 offset:54272
	ds_read_b128 v[208:211], v150 offset:55296
	ds_read_b128 v[212:215], v150 offset:56320
	global_load_lds_dwordx4 v[216:217], off
	s_add_i32 m0, s30, 0x2000
	s_add_u32 s28, s28, 0x40080
	v_lshl_add_u64 v[216:217], v[218:219], 0, s[12:13]
	s_addc_u32 s29, s29, 0
	s_add_i32 s30, s51, s33
	global_load_lds_dwordx4 v[216:217], off
	v_lshl_add_u64 v[216:217], s[28:29], 0, v[132:133]
	s_mov_b32 m0, s30
	s_nop 0
	global_load_lds_dwordx4 v[216:217], off
	v_lshl_add_u64 v[216:217], s[28:29], 0, v[128:129]
	s_add_i32 m0, s30, 0x2000
	s_nop 0
	global_load_lds_dwordx4 v[216:217], off
	v_lshl_add_u64 v[216:217], v[220:221], 0, s[12:13]
	s_mov_b32 m0, s39
	s_nop 0
	global_load_lds_dwordx4 v[216:217], off
	v_lshl_add_u64 v[216:217], v[222:223], 0, s[12:13]
	s_mov_b32 m0, s40
	s_nop 0
	global_load_lds_dwordx4 v[216:217], off
	s_waitcnt vmcnt(8)
	s_waitcnt lgkmcnt(0)
	s_setprio 1
	s_barrier
	s_waitcnt lgkmcnt(0)
	v_mfma_f32_16x16x32_bf16 v[60:63], v[152:155], v[184:187], v[60:63]
	v_mfma_f32_16x16x32_bf16 v[56:59], v[160:163], v[184:187], v[56:59]
	v_mfma_f32_16x16x32_bf16 v[52:55], v[152:155], v[192:195], v[52:55]
	v_mfma_f32_16x16x32_bf16 v[44:47], v[160:163], v[192:195], v[44:47]
	v_mfma_f32_16x16x32_bf16 v[36:39], v[152:155], v[200:203], v[36:39]
	v_mfma_f32_16x16x32_bf16 v[28:31], v[160:163], v[200:203], v[28:31]
	v_mfma_f32_16x16x32_bf16 v[20:23], v[152:155], v[208:211], v[20:23]
	v_mfma_f32_16x16x32_bf16 v[12:15], v[160:163], v[208:211], v[12:15]
	v_mfma_f32_16x16x32_bf16 v[60:63], v[156:159], v[188:191], v[60:63]
	v_mfma_f32_16x16x32_bf16 v[56:59], v[164:167], v[188:191], v[56:59]
	v_mfma_f32_16x16x32_bf16 v[52:55], v[156:159], v[196:199], v[52:55]
	v_mfma_f32_16x16x32_bf16 v[44:47], v[164:167], v[196:199], v[44:47]
	v_mfma_f32_16x16x32_bf16 v[36:39], v[156:159], v[204:207], v[36:39]
	v_mfma_f32_16x16x32_bf16 v[28:31], v[164:167], v[204:207], v[28:31]
	v_mfma_f32_16x16x32_bf16 v[20:23], v[156:159], v[212:215], v[20:23]
	v_mfma_f32_16x16x32_bf16 v[12:15], v[164:167], v[212:215], v[12:15]
	s_setprio 0
	s_setprio 1
	v_mfma_f32_16x16x32_bf16 v[48:51], v[168:171], v[184:187], v[48:51]
	v_mfma_f32_16x16x32_bf16 v[40:43], v[176:179], v[184:187], v[40:43]
	v_mfma_f32_16x16x32_bf16 v[32:35], v[168:171], v[192:195], v[32:35]
	v_mfma_f32_16x16x32_bf16 v[24:27], v[176:179], v[192:195], v[24:27]
	v_mfma_f32_16x16x32_bf16 v[16:19], v[168:171], v[200:203], v[16:19]
	v_mfma_f32_16x16x32_bf16 v[8:11], v[176:179], v[200:203], v[8:11]
	v_mfma_f32_16x16x32_bf16 v[4:7], v[168:171], v[208:211], v[4:7]
	v_mfma_f32_16x16x32_bf16 v[0:3], v[176:179], v[208:211], v[0:3]
	v_mfma_f32_16x16x32_bf16 v[48:51], v[172:175], v[188:191], v[48:51]
	v_mfma_f32_16x16x32_bf16 v[40:43], v[180:183], v[188:191], v[40:43]
	v_mfma_f32_16x16x32_bf16 v[32:35], v[172:175], v[196:199], v[32:35]
	v_mfma_f32_16x16x32_bf16 v[24:27], v[180:183], v[196:199], v[24:27]
	v_mfma_f32_16x16x32_bf16 v[16:19], v[172:175], v[204:207], v[16:19]
	v_mfma_f32_16x16x32_bf16 v[8:11], v[180:183], v[204:207], v[8:11]
	v_mfma_f32_16x16x32_bf16 v[4:7], v[172:175], v[212:215], v[4:7]
	v_mfma_f32_16x16x32_bf16 v[0:3], v[180:183], v[212:215], v[0:3]
	s_setprio 0
	s_barrier
	s_add_i32 s49, s49, 2
	s_add_u32 s47, s47, 0x100
	s_addc_u32 s48, s48, 0
	s_add_u32 s26, s26, 0x100
	s_addc_u32 s27, s27, 0
	s_cmp_gt_u32 s49, 13
	s_cbranch_scc0 .LBB0_356
	s_and_b64 vcc, exec, s[14:15]
	s_cbranch_vccz .LBB0_359
	s_barrier

.LBB0_729:
	ds_read_b128 v[150:153], v147
	ds_read_b128 v[154:157], v147 offset:1024
	ds_read_b128 v[158:161], v147 offset:2048
	ds_read_b128 v[162:165], v147 offset:3072
	ds_read_b128 v[166:169], v148
	ds_read_b128 v[170:173], v148 offset:1024
	ds_read_b128 v[174:177], v148 offset:2048
	ds_read_b128 v[178:181], v148 offset:3072
	s_add_u32 s36, s34, 0xfffc0080
	s_addc_u32 s37, s35, -1
	s_cmp_eq_u32 s59, 12
	s_cselect_b32 s39, s27, s37
	s_cselect_b32 s38, s55, s36
	s_cselect_b32 s37, s25, s58
	s_cselect_b32 s36, s56, s57
	v_lshl_add_u64 v[214:215], s[34:35], 0, v[138:139]
	s_add_i32 m0, s40, 0xc000
	ds_read_b128 v[182:185], v149
	ds_read_b128 v[186:189], v149 offset:1024
	ds_read_b128 v[190:193], v149 offset:2048
	ds_read_b128 v[194:197], v149 offset:3072
	ds_read_b128 v[198:201], v149 offset:4096
	ds_read_b128 v[202:205], v149 offset:5120
	ds_read_b128 v[206:209], v149 offset:6144
	ds_read_b128 v[210:213], v149 offset:7168
	global_load_lds_dwordx4 v[214:215], off
	v_lshl_add_u64 v[214:215], s[34:35], 0, v[136:137]
	s_add_i32 m0, s40, 0xe000
	s_nop 0
	global_load_lds_dwordx4 v[214:215], off
	s_waitcnt vmcnt(8)
	s_waitcnt lgkmcnt(0)
	s_setprio 1
	s_barrier
	s_waitcnt lgkmcnt(0)
	v_mfma_f32_16x16x32_bf16 v[124:127], v[150:153], v[182:185], v[124:127]
	v_mfma_f32_16x16x32_bf16 v[120:123], v[158:161], v[182:185], v[120:123]
	v_mfma_f32_16x16x32_bf16 v[116:119], v[150:153], v[190:193], v[116:119]
	v_mfma_f32_16x16x32_bf16 v[112:115], v[158:161], v[190:193], v[112:115]
	v_mfma_f32_16x16x32_bf16 v[100:103], v[150:153], v[198:201], v[100:103]
	v_mfma_f32_16x16x32_bf16 v[96:99], v[158:161], v[198:201], v[96:99]
	v_mfma_f32_16x16x32_bf16 v[84:87], v[150:153], v[206:209], v[84:87]
	v_mfma_f32_16x16x32_bf16 v[80:83], v[158:161], v[206:209], v[80:83]
	v_mfma_f32_16x16x32_bf16 v[124:127], v[154:157], v[186:189], v[124:127]
	v_mfma_f32_16x16x32_bf16 v[120:123], v[162:165], v[186:189], v[120:123]
	v_mfma_f32_16x16x32_bf16 v[116:119], v[154:157], v[194:197], v[116:119]
	v_mfma_f32_16x16x32_bf16 v[112:115], v[162:165], v[194:197], v[112:115]
	v_mfma_f32_16x16x32_bf16 v[100:103], v[154:157], v[202:205], v[100:103]
	v_mfma_f32_16x16x32_bf16 v[96:99], v[162:165], v[202:205], v[96:99]
	v_mfma_f32_16x16x32_bf16 v[84:87], v[154:157], v[210:213], v[84:87]
	v_mfma_f32_16x16x32_bf16 v[80:83], v[162:165], v[210:213], v[80:83]
	s_setprio 0
	s_setprio 1
	v_mfma_f32_16x16x32_bf16 v[108:111], v[166:169], v[182:185], v[108:111]
	v_mfma_f32_16x16x32_bf16 v[104:107], v[174:177], v[182:185], v[104:107]
	v_mfma_f32_16x16x32_bf16 v[92:95], v[166:169], v[190:193], v[92:95]
	v_mfma_f32_16x16x32_bf16 v[88:91], v[174:177], v[190:193], v[88:91]
	v_mfma_f32_16x16x32_bf16 v[76:79], v[166:169], v[198:201], v[76:79]
	v_mfma_f32_16x16x32_bf16 v[72:75], v[174:177], v[198:201], v[72:75]
	v_mfma_f32_16x16x32_bf16 v[68:71], v[166:169], v[206:209], v[68:71]
	v_mfma_f32_16x16x32_bf16 v[64:67], v[174:177], v[206:209], v[64:67]
	v_mfma_f32_16x16x32_bf16 v[108:111], v[170:173], v[186:189], v[108:111]
	v_mfma_f32_16x16x32_bf16 v[104:107], v[178:181], v[186:189], v[104:107]
	v_mfma_f32_16x16x32_bf16 v[92:95], v[170:173], v[194:197], v[92:95]
	v_mfma_f32_16x16x32_bf16 v[88:91], v[178:181], v[194:197], v[88:91]
	v_mfma_f32_16x16x32_bf16 v[76:79], v[170:173], v[202:205], v[76:79]
	v_mfma_f32_16x16x32_bf16 v[72:75], v[178:181], v[202:205], v[72:75]
	v_mfma_f32_16x16x32_bf16 v[68:71], v[170:173], v[210:213], v[68:71]
	v_mfma_f32_16x16x32_bf16 v[64:67], v[178:181], v[210:213], v[64:67]
	s_setprio 0
	s_barrier
	s_add_i32 s60, s47, s33
	v_lshl_add_u64 v[214:215], s[36:37], 0, v[132:133]
	s_mov_b32 m0, s60
	ds_read_b128 v[182:185], v149 offset:16384
	ds_read_b128 v[186:189], v149 offset:17408
	ds_read_b128 v[190:193], v149 offset:18432
	ds_read_b128 v[194:197], v149 offset:19456
	ds_read_b128 v[198:201], v149 offset:20480
	ds_read_b128 v[202:205], v149 offset:21504
	ds_read_b128 v[206:209], v149 offset:22528
	ds_read_b128 v[210:213], v149 offset:23552
	global_load_lds_dwordx4 v[214:215], off
	s_add_i32 m0, s60, 0x2000
	s_add_u32 s60, s36, 0x40000
	v_lshl_add_u64 v[216:217], s[36:37], 0, v[128:129]
	s_addc_u32 s61, s37, 0
	s_add_i32 s62, s48, s33
	global_load_lds_dwordx4 v[216:217], off
	v_lshl_add_u64 v[218:219], s[60:61], 0, v[132:133]
	s_mov_b32 m0, s62
	v_lshl_add_u64 v[220:221], s[38:39], 0, v[130:131]
	global_load_lds_dwordx4 v[218:219], off
	v_lshl_add_u64 v[218:219], s[60:61], 0, v[128:129]
	s_add_i32 m0, s62, 0x2000
	s_nop 0
	global_load_lds_dwordx4 v[218:219], off
	v_lshl_add_u64 v[218:219], s[38:39], 0, v[134:135]
	s_mov_b32 m0, s40
	s_nop 0
	global_load_lds_dwordx4 v[218:219], off
	s_mov_b32 m0, s41
	s_nop 0
	global_load_lds_dwordx4 v[220:221], off
	s_waitcnt vmcnt(8)
	s_waitcnt lgkmcnt(0)
	s_setprio 1
	s_barrier
	s_waitcnt lgkmcnt(0)
	v_mfma_f32_16x16x32_bf16 v[60:63], v[150:153], v[182:185], v[60:63]
	v_mfma_f32_16x16x32_bf16 v[56:59], v[158:161], v[182:185], v[56:59]
	v_mfma_f32_16x16x32_bf16 v[52:55], v[150:153], v[190:193], v[52:55]
	v_mfma_f32_16x16x32_bf16 v[48:51], v[158:161], v[190:193], v[48:51]
	v_mfma_f32_16x16x32_bf16 v[36:39], v[150:153], v[198:201], v[36:39]
	v_mfma_f32_16x16x32_bf16 v[32:35], v[158:161], v[198:201], v[32:35]
	v_mfma_f32_16x16x32_bf16 v[20:23], v[150:153], v[206:209], v[20:23]
	v_mfma_f32_16x16x32_bf16 v[16:19], v[158:161], v[206:209], v[16:19]
	v_mfma_f32_16x16x32_bf16 v[60:63], v[154:157], v[186:189], v[60:63]
	v_mfma_f32_16x16x32_bf16 v[56:59], v[162:165], v[186:189], v[56:59]
	v_mfma_f32_16x16x32_bf16 v[52:55], v[154:157], v[194:197], v[52:55]
	v_mfma_f32_16x16x32_bf16 v[48:51], v[162:165], v[194:197], v[48:51]
	v_mfma_f32_16x16x32_bf16 v[36:39], v[154:157], v[202:205], v[36:39]
	v_mfma_f32_16x16x32_bf16 v[32:35], v[162:165], v[202:205], v[32:35]
	v_mfma_f32_16x16x32_bf16 v[20:23], v[154:157], v[210:213], v[20:23]
	v_mfma_f32_16x16x32_bf16 v[16:19], v[162:165], v[210:213], v[16:19]
	s_setprio 0
	s_setprio 1
	v_mfma_f32_16x16x32_bf16 v[44:47], v[166:169], v[182:185], v[44:47]
	v_mfma_f32_16x16x32_bf16 v[40:43], v[174:177], v[182:185], v[40:43]
	v_mfma_f32_16x16x32_bf16 v[28:31], v[166:169], v[190:193], v[28:31]
	v_mfma_f32_16x16x32_bf16 v[24:27], v[174:177], v[190:193], v[24:27]
	v_mfma_f32_16x16x32_bf16 v[12:15], v[166:169], v[198:201], v[12:15]
	v_mfma_f32_16x16x32_bf16 v[8:11], v[174:177], v[198:201], v[8:11]
	v_mfma_f32_16x16x32_bf16 v[4:7], v[166:169], v[206:209], v[4:7]
	v_mfma_f32_16x16x32_bf16 v[0:3], v[174:177], v[206:209], v[0:3]
	v_mfma_f32_16x16x32_bf16 v[44:47], v[170:173], v[186:189], v[44:47]
	v_mfma_f32_16x16x32_bf16 v[40:43], v[178:181], v[186:189], v[40:43]
	v_mfma_f32_16x16x32_bf16 v[28:31], v[170:173], v[194:197], v[28:31]
	v_mfma_f32_16x16x32_bf16 v[24:27], v[178:181], v[194:197], v[24:27]
	v_mfma_f32_16x16x32_bf16 v[12:15], v[170:173], v[202:205], v[12:15]
	v_mfma_f32_16x16x32_bf16 v[8:11], v[178:181], v[202:205], v[8:11]
	v_mfma_f32_16x16x32_bf16 v[4:7], v[170:173], v[210:213], v[4:7]
	v_mfma_f32_16x16x32_bf16 v[0:3], v[178:181], v[210:213], v[0:3]
	s_setprio 0
	s_barrier
	s_add_i32 s60, 0, 0x18000
	s_add_i32 s61, 0, 0x1c000
	v_add_u32_e32 v162, s60, v145
	v_add_u32_e32 v178, s61, v145
	ds_read_b128 v[150:153], v162
	ds_read_b128 v[154:157], v162 offset:1024
	ds_read_b128 v[158:161], v162 offset:2048
	ds_read_b128 v[162:165], v162 offset:3072
	ds_read_b128 v[166:169], v178
	ds_read_b128 v[170:173], v178 offset:1024
	ds_read_b128 v[174:177], v178 offset:2048
	ds_read_b128 v[178:181], v178 offset:3072
	s_add_u32 s38, s38, 0x40000
	s_addc_u32 s39, s39, 0
	s_mov_b32 m0, s42
	v_lshl_add_u64 v[222:223], s[38:39], 0, v[134:135]
	ds_read_b128 v[182:185], v149 offset:32768
	ds_read_b128 v[186:189], v149 offset:33792
	ds_read_b128 v[190:193], v149 offset:34816
	ds_read_b128 v[194:197], v149 offset:35840
	ds_read_b128 v[198:201], v149 offset:36864
	ds_read_b128 v[202:205], v149 offset:37888
	ds_read_b128 v[206:209], v149 offset:38912
	ds_read_b128 v[210:213], v149 offset:39936
	global_load_lds_dwordx4 v[222:223], off
	v_lshl_add_u64 v[222:223], s[38:39], 0, v[130:131]
	s_mov_b32 m0, s43
	s_nop 0
	global_load_lds_dwordx4 v[222:223], off
	s_waitcnt vmcnt(8)
	s_waitcnt lgkmcnt(0)
	s_setprio 1
	s_barrier
	s_waitcnt lgkmcnt(0)
	v_mfma_f32_16x16x32_bf16 v[124:127], v[150:153], v[182:185], v[124:127]
	v_mfma_f32_16x16x32_bf16 v[120:123], v[158:161], v[182:185], v[120:123]
	v_mfma_f32_16x16x32_bf16 v[116:119], v[150:153], v[190:193], v[116:119]
	v_mfma_f32_16x16x32_bf16 v[112:115], v[158:161], v[190:193], v[112:115]
	v_mfma_f32_16x16x32_bf16 v[100:103], v[150:153], v[198:201], v[100:103]
	v_mfma_f32_16x16x32_bf16 v[96:99], v[158:161], v[198:201], v[96:99]
	v_mfma_f32_16x16x32_bf16 v[84:87], v[150:153], v[206:209], v[84:87]
	v_mfma_f32_16x16x32_bf16 v[80:83], v[158:161], v[206:209], v[80:83]
	v_mfma_f32_16x16x32_bf16 v[124:127], v[154:157], v[186:189], v[124:127]
	v_mfma_f32_16x16x32_bf16 v[120:123], v[162:165], v[186:189], v[120:123]
	v_mfma_f32_16x16x32_bf16 v[116:119], v[154:157], v[194:197], v[116:119]
	v_mfma_f32_16x16x32_bf16 v[112:115], v[162:165], v[194:197], v[112:115]
	v_mfma_f32_16x16x32_bf16 v[100:103], v[154:157], v[202:205], v[100:103]
	v_mfma_f32_16x16x32_bf16 v[96:99], v[162:165], v[202:205], v[96:99]
	v_mfma_f32_16x16x32_bf16 v[84:87], v[154:157], v[210:213], v[84:87]
	v_mfma_f32_16x16x32_bf16 v[80:83], v[162:165], v[210:213], v[80:83]
	s_setprio 0
	s_setprio 1
	v_mfma_f32_16x16x32_bf16 v[108:111], v[166:169], v[182:185], v[108:111]
	v_mfma_f32_16x16x32_bf16 v[104:107], v[174:177], v[182:185], v[104:107]
	v_mfma_f32_16x16x32_bf16 v[92:95], v[166:169], v[190:193], v[92:95]
	v_mfma_f32_16x16x32_bf16 v[88:91], v[174:177], v[190:193], v[88:91]
	v_mfma_f32_16x16x32_bf16 v[76:79], v[166:169], v[198:201], v[76:79]
	v_mfma_f32_16x16x32_bf16 v[72:75], v[174:177], v[198:201], v[72:75]
	v_mfma_f32_16x16x32_bf16 v[68:71], v[166:169], v[206:209], v[68:71]
	v_mfma_f32_16x16x32_bf16 v[64:67], v[174:177], v[206:209], v[64:67]
	v_mfma_f32_16x16x32_bf16 v[108:111], v[170:173], v[186:189], v[108:111]
	v_mfma_f32_16x16x32_bf16 v[104:107], v[178:181], v[186:189], v[104:107]
	v_mfma_f32_16x16x32_bf16 v[92:95], v[170:173], v[194:197], v[92:95]
	v_mfma_f32_16x16x32_bf16 v[88:91], v[178:181], v[194:197], v[88:91]
	v_mfma_f32_16x16x32_bf16 v[76:79], v[170:173], v[202:205], v[76:79]
	v_mfma_f32_16x16x32_bf16 v[72:75], v[178:181], v[202:205], v[72:75]
	v_mfma_f32_16x16x32_bf16 v[68:71], v[170:173], v[210:213], v[68:71]
	v_mfma_f32_16x16x32_bf16 v[64:67], v[178:181], v[210:213], v[64:67]
	s_setprio 0
	s_barrier
	s_add_i32 s38, s60, s33
	v_lshl_add_u64 v[214:215], v[214:215], 0, s[14:15]
	s_mov_b32 m0, s38
	ds_read_b128 v[182:185], v149 offset:49152
	ds_read_b128 v[186:189], v149 offset:50176
	ds_read_b128 v[190:193], v149 offset:51200
	ds_read_b128 v[194:197], v149 offset:52224
	ds_read_b128 v[198:201], v149 offset:53248
	ds_read_b128 v[202:205], v149 offset:54272
	ds_read_b128 v[206:209], v149 offset:55296
	ds_read_b128 v[210:213], v149 offset:56320
	global_load_lds_dwordx4 v[214:215], off
	s_add_i32 m0, s38, 0x2000
	s_add_u32 s36, s36, 0x40080
	v_lshl_add_u64 v[214:215], v[216:217], 0, s[14:15]
	s_addc_u32 s37, s37, 0
	s_add_i32 s38, s61, s33
	global_load_lds_dwordx4 v[214:215], off
	v_lshl_add_u64 v[214:215], s[36:37], 0, v[132:133]
	s_mov_b32 m0, s38
	s_nop 0
	global_load_lds_dwordx4 v[214:215], off
	v_lshl_add_u64 v[214:215], s[36:37], 0, v[128:129]
	s_add_i32 m0, s38, 0x2000
	s_nop 0
	global_load_lds_dwordx4 v[214:215], off
	v_lshl_add_u64 v[214:215], v[218:219], 0, s[14:15]
	s_mov_b32 m0, s45
	s_nop 0
	global_load_lds_dwordx4 v[214:215], off
	v_lshl_add_u64 v[214:215], v[220:221], 0, s[14:15]
	s_mov_b32 m0, s46
	s_nop 0
	global_load_lds_dwordx4 v[214:215], off
	s_waitcnt vmcnt(8)
	s_waitcnt lgkmcnt(0)
	s_setprio 1
	s_barrier
	s_waitcnt lgkmcnt(0)
	v_mfma_f32_16x16x32_bf16 v[60:63], v[150:153], v[182:185], v[60:63]
	v_mfma_f32_16x16x32_bf16 v[56:59], v[158:161], v[182:185], v[56:59]
	v_mfma_f32_16x16x32_bf16 v[52:55], v[150:153], v[190:193], v[52:55]
	v_mfma_f32_16x16x32_bf16 v[48:51], v[158:161], v[190:193], v[48:51]
	v_mfma_f32_16x16x32_bf16 v[36:39], v[150:153], v[198:201], v[36:39]
	v_mfma_f32_16x16x32_bf16 v[32:35], v[158:161], v[198:201], v[32:35]
	v_mfma_f32_16x16x32_bf16 v[20:23], v[150:153], v[206:209], v[20:23]
	v_mfma_f32_16x16x32_bf16 v[16:19], v[158:161], v[206:209], v[16:19]
	v_mfma_f32_16x16x32_bf16 v[60:63], v[154:157], v[186:189], v[60:63]
	v_mfma_f32_16x16x32_bf16 v[56:59], v[162:165], v[186:189], v[56:59]
	v_mfma_f32_16x16x32_bf16 v[52:55], v[154:157], v[194:197], v[52:55]
	v_mfma_f32_16x16x32_bf16 v[48:51], v[162:165], v[194:197], v[48:51]
	v_mfma_f32_16x16x32_bf16 v[36:39], v[154:157], v[202:205], v[36:39]
	v_mfma_f32_16x16x32_bf16 v[32:35], v[162:165], v[202:205], v[32:35]
	v_mfma_f32_16x16x32_bf16 v[20:23], v[154:157], v[210:213], v[20:23]
	v_mfma_f32_16x16x32_bf16 v[16:19], v[162:165], v[210:213], v[16:19]
	s_setprio 0
	s_setprio 1
	v_mfma_f32_16x16x32_bf16 v[44:47], v[166:169], v[182:185], v[44:47]
	v_mfma_f32_16x16x32_bf16 v[40:43], v[174:177], v[182:185], v[40:43]
	v_mfma_f32_16x16x32_bf16 v[28:31], v[166:169], v[190:193], v[28:31]
	v_mfma_f32_16x16x32_bf16 v[24:27], v[174:177], v[190:193], v[24:27]
	v_mfma_f32_16x16x32_bf16 v[12:15], v[166:169], v[198:201], v[12:15]
	v_mfma_f32_16x16x32_bf16 v[8:11], v[174:177], v[198:201], v[8:11]
	v_mfma_f32_16x16x32_bf16 v[4:7], v[166:169], v[206:209], v[4:7]
	v_mfma_f32_16x16x32_bf16 v[0:3], v[174:177], v[206:209], v[0:3]
	v_mfma_f32_16x16x32_bf16 v[44:47], v[170:173], v[186:189], v[44:47]
	v_mfma_f32_16x16x32_bf16 v[40:43], v[178:181], v[186:189], v[40:43]
	v_mfma_f32_16x16x32_bf16 v[28:31], v[170:173], v[194:197], v[28:31]
	v_mfma_f32_16x16x32_bf16 v[24:27], v[178:181], v[194:197], v[24:27]
	v_mfma_f32_16x16x32_bf16 v[12:15], v[170:173], v[202:205], v[12:15]
	v_mfma_f32_16x16x32_bf16 v[8:11], v[178:181], v[202:205], v[8:11]
	v_mfma_f32_16x16x32_bf16 v[4:7], v[170:173], v[210:213], v[4:7]
	v_mfma_f32_16x16x32_bf16 v[0:3], v[178:181], v[210:213], v[0:3]
	s_setprio 0
	s_barrier
	s_add_i32 s59, s59, 2
	s_add_u32 s57, s57, 0x100
	s_addc_u32 s58, s58, 0
	s_add_u32 s34, s34, 0x100
	s_addc_u32 s35, s35, 0
	s_cmp_gt_u32 s59, 13
	s_cbranch_scc0 .LBB0_729
	s_and_b64 vcc, exec, s[16:17]
	s_cbranch_vccz .LBB0_732
	s_barrier

.LBB0_877:
	ds_read_b128 v[152:155], v149
	ds_read_b128 v[156:159], v149 offset:1024
	ds_read_b128 v[160:163], v149 offset:2048
	ds_read_b128 v[164:167], v149 offset:3072
	ds_read_b128 v[168:171], v150
	ds_read_b128 v[172:175], v150 offset:1024
	ds_read_b128 v[176:179], v150 offset:2048
	ds_read_b128 v[180:183], v150 offset:3072
	s_add_u32 s26, s24, 0xfffc0080
	s_addc_u32 s27, s25, -1
	s_cmp_eq_u32 s49, 12
	s_cselect_b32 s29, s19, s27
	s_cselect_b32 s28, s45, s26
	s_cselect_b32 s27, s17, s48
	s_cselect_b32 s26, s46, s47
	v_lshl_add_u64 v[144:145], s[24:25], 0, v[138:139]
	s_add_i32 m0, s31, 0xc000
	ds_read_b128 v[184:187], v151
	ds_read_b128 v[188:191], v151 offset:1024
	ds_read_b128 v[192:195], v151 offset:2048
	ds_read_b128 v[196:199], v151 offset:3072
	ds_read_b128 v[200:203], v151 offset:4096
	ds_read_b128 v[204:207], v151 offset:5120
	ds_read_b128 v[208:211], v151 offset:6144
	ds_read_b128 v[212:215], v151 offset:7168
	global_load_lds_dwordx4 v[144:145], off
	v_lshl_add_u64 v[144:145], s[24:25], 0, v[136:137]
	s_add_i32 m0, s31, 0xe000
	s_nop 0
	global_load_lds_dwordx4 v[144:145], off
	s_waitcnt vmcnt(8)
	s_waitcnt lgkmcnt(0)
	s_setprio 1
	s_barrier
	s_waitcnt lgkmcnt(0)
	v_mfma_f32_16x16x32_bf16 v[124:127], v[152:155], v[184:187], v[124:127]
	v_mfma_f32_16x16x32_bf16 v[120:123], v[160:163], v[184:187], v[120:123]
	v_mfma_f32_16x16x32_bf16 v[108:111], v[152:155], v[192:195], v[108:111]
	v_mfma_f32_16x16x32_bf16 v[104:107], v[160:163], v[192:195], v[104:107]
	v_mfma_f32_16x16x32_bf16 v[92:95], v[152:155], v[200:203], v[92:95]
	v_mfma_f32_16x16x32_bf16 v[88:91], v[160:163], v[200:203], v[88:91]
	v_mfma_f32_16x16x32_bf16 v[76:79], v[152:155], v[208:211], v[76:79]
	v_mfma_f32_16x16x32_bf16 v[72:75], v[160:163], v[208:211], v[72:75]
	v_mfma_f32_16x16x32_bf16 v[124:127], v[156:159], v[188:191], v[124:127]
	v_mfma_f32_16x16x32_bf16 v[120:123], v[164:167], v[188:191], v[120:123]
	v_mfma_f32_16x16x32_bf16 v[108:111], v[156:159], v[196:199], v[108:111]
	v_mfma_f32_16x16x32_bf16 v[104:107], v[164:167], v[196:199], v[104:107]
	v_mfma_f32_16x16x32_bf16 v[92:95], v[156:159], v[204:207], v[92:95]
	v_mfma_f32_16x16x32_bf16 v[88:91], v[164:167], v[204:207], v[88:91]
	v_mfma_f32_16x16x32_bf16 v[76:79], v[156:159], v[212:215], v[76:79]
	v_mfma_f32_16x16x32_bf16 v[72:75], v[164:167], v[212:215], v[72:75]
	s_setprio 0
	s_setprio 1
	v_mfma_f32_16x16x32_bf16 v[116:119], v[168:171], v[184:187], v[116:119]
	v_mfma_f32_16x16x32_bf16 v[112:115], v[176:179], v[184:187], v[112:115]
	v_mfma_f32_16x16x32_bf16 v[100:103], v[168:171], v[192:195], v[100:103]
	v_mfma_f32_16x16x32_bf16 v[96:99], v[176:179], v[192:195], v[96:99]
	v_mfma_f32_16x16x32_bf16 v[84:87], v[168:171], v[200:203], v[84:87]
	v_mfma_f32_16x16x32_bf16 v[80:83], v[176:179], v[200:203], v[80:83]
	v_mfma_f32_16x16x32_bf16 v[68:71], v[168:171], v[208:211], v[68:71]
	v_mfma_f32_16x16x32_bf16 v[64:67], v[176:179], v[208:211], v[64:67]
	v_mfma_f32_16x16x32_bf16 v[116:119], v[172:175], v[188:191], v[116:119]
	v_mfma_f32_16x16x32_bf16 v[112:115], v[180:183], v[188:191], v[112:115]
	v_mfma_f32_16x16x32_bf16 v[100:103], v[172:175], v[196:199], v[100:103]
	v_mfma_f32_16x16x32_bf16 v[96:99], v[180:183], v[196:199], v[96:99]
	v_mfma_f32_16x16x32_bf16 v[84:87], v[172:175], v[204:207], v[84:87]
	v_mfma_f32_16x16x32_bf16 v[80:83], v[180:183], v[204:207], v[80:83]
	v_mfma_f32_16x16x32_bf16 v[68:71], v[172:175], v[212:215], v[68:71]
	v_mfma_f32_16x16x32_bf16 v[64:67], v[180:183], v[212:215], v[64:67]
	s_setprio 0
	s_barrier
	s_add_i32 s50, s40, s30
	v_lshl_add_u64 v[144:145], s[26:27], 0, v[132:133]
	s_mov_b32 m0, s50
	ds_read_b128 v[184:187], v151 offset:16384
	ds_read_b128 v[188:191], v151 offset:17408
	ds_read_b128 v[192:195], v151 offset:18432
	ds_read_b128 v[196:199], v151 offset:19456
	ds_read_b128 v[200:203], v151 offset:20480
	ds_read_b128 v[204:207], v151 offset:21504
	ds_read_b128 v[208:211], v151 offset:22528
	ds_read_b128 v[212:215], v151 offset:23552
	global_load_lds_dwordx4 v[144:145], off
	s_add_i32 m0, s50, 0x2000
	s_add_u32 s50, s26, 0x40000
	v_lshl_add_u64 v[216:217], s[26:27], 0, v[128:129]
	s_addc_u32 s51, s27, 0
	s_add_i32 s52, s41, s30
	global_load_lds_dwordx4 v[216:217], off
	v_lshl_add_u64 v[218:219], s[50:51], 0, v[132:133]
	s_mov_b32 m0, s52
	v_lshl_add_u64 v[220:221], s[28:29], 0, v[130:131]
	global_load_lds_dwordx4 v[218:219], off
	v_lshl_add_u64 v[218:219], s[50:51], 0, v[128:129]
	s_add_i32 m0, s52, 0x2000
	s_nop 0
	global_load_lds_dwordx4 v[218:219], off
	v_lshl_add_u64 v[218:219], s[28:29], 0, v[134:135]
	s_mov_b32 m0, s31
	s_nop 0
	global_load_lds_dwordx4 v[218:219], off
	s_mov_b32 m0, s33
	s_nop 0
	global_load_lds_dwordx4 v[220:221], off
	s_waitcnt vmcnt(8)
	s_waitcnt lgkmcnt(0)
	s_setprio 1
	s_barrier
	s_waitcnt lgkmcnt(0)
	v_mfma_f32_16x16x32_bf16 v[60:63], v[152:155], v[184:187], v[60:63]
	v_mfma_f32_16x16x32_bf16 v[56:59], v[160:163], v[184:187], v[56:59]
	v_mfma_f32_16x16x32_bf16 v[44:47], v[152:155], v[192:195], v[44:47]
	v_mfma_f32_16x16x32_bf16 v[40:43], v[160:163], v[192:195], v[40:43]
	v_mfma_f32_16x16x32_bf16 v[28:31], v[152:155], v[200:203], v[28:31]
	v_mfma_f32_16x16x32_bf16 v[24:27], v[160:163], v[200:203], v[24:27]
	v_mfma_f32_16x16x32_bf16 v[12:15], v[152:155], v[208:211], v[12:15]
	v_mfma_f32_16x16x32_bf16 v[8:11], v[160:163], v[208:211], v[8:11]
	v_mfma_f32_16x16x32_bf16 v[60:63], v[156:159], v[188:191], v[60:63]
	v_mfma_f32_16x16x32_bf16 v[56:59], v[164:167], v[188:191], v[56:59]
	v_mfma_f32_16x16x32_bf16 v[44:47], v[156:159], v[196:199], v[44:47]
	v_mfma_f32_16x16x32_bf16 v[40:43], v[164:167], v[196:199], v[40:43]
	v_mfma_f32_16x16x32_bf16 v[28:31], v[156:159], v[204:207], v[28:31]
	v_mfma_f32_16x16x32_bf16 v[24:27], v[164:167], v[204:207], v[24:27]
	v_mfma_f32_16x16x32_bf16 v[12:15], v[156:159], v[212:215], v[12:15]
	v_mfma_f32_16x16x32_bf16 v[8:11], v[164:167], v[212:215], v[8:11]
	s_setprio 0
	s_setprio 1
	v_mfma_f32_16x16x32_bf16 v[52:55], v[168:171], v[184:187], v[52:55]
	v_mfma_f32_16x16x32_bf16 v[48:51], v[176:179], v[184:187], v[48:51]
	v_mfma_f32_16x16x32_bf16 v[36:39], v[168:171], v[192:195], v[36:39]
	v_mfma_f32_16x16x32_bf16 v[32:35], v[176:179], v[192:195], v[32:35]
	v_mfma_f32_16x16x32_bf16 v[20:23], v[168:171], v[200:203], v[20:23]
	v_mfma_f32_16x16x32_bf16 v[16:19], v[176:179], v[200:203], v[16:19]
	v_mfma_f32_16x16x32_bf16 v[4:7], v[168:171], v[208:211], v[4:7]
	v_mfma_f32_16x16x32_bf16 v[0:3], v[176:179], v[208:211], v[0:3]
	v_mfma_f32_16x16x32_bf16 v[52:55], v[172:175], v[188:191], v[52:55]
	v_mfma_f32_16x16x32_bf16 v[48:51], v[180:183], v[188:191], v[48:51]
	v_mfma_f32_16x16x32_bf16 v[36:39], v[172:175], v[196:199], v[36:39]
	v_mfma_f32_16x16x32_bf16 v[32:35], v[180:183], v[196:199], v[32:35]
	v_mfma_f32_16x16x32_bf16 v[20:23], v[172:175], v[204:207], v[20:23]
	v_mfma_f32_16x16x32_bf16 v[16:19], v[180:183], v[204:207], v[16:19]
	v_mfma_f32_16x16x32_bf16 v[4:7], v[172:175], v[212:215], v[4:7]
	v_mfma_f32_16x16x32_bf16 v[0:3], v[180:183], v[212:215], v[0:3]
	s_setprio 0
	s_barrier
	s_add_i32 s50, 0, 0x18000
	s_add_i32 s51, 0, 0x1c000
	v_add_u32_e32 v164, s50, v147
	v_add_u32_e32 v180, s51, v147
	ds_read_b128 v[152:155], v164
	ds_read_b128 v[156:159], v164 offset:1024
	ds_read_b128 v[160:163], v164 offset:2048
	ds_read_b128 v[164:167], v164 offset:3072
	ds_read_b128 v[168:171], v180
	ds_read_b128 v[172:175], v180 offset:1024
	ds_read_b128 v[176:179], v180 offset:2048
	ds_read_b128 v[180:183], v180 offset:3072
	s_add_u32 s28, s28, 0x40000
	s_addc_u32 s29, s29, 0
	s_mov_b32 m0, s34
	v_lshl_add_u64 v[222:223], s[28:29], 0, v[134:135]
	ds_read_b128 v[184:187], v151 offset:32768
	ds_read_b128 v[188:191], v151 offset:33792
	ds_read_b128 v[192:195], v151 offset:34816
	ds_read_b128 v[196:199], v151 offset:35840
	ds_read_b128 v[200:203], v151 offset:36864
	ds_read_b128 v[204:207], v151 offset:37888
	ds_read_b128 v[208:211], v151 offset:38912
	ds_read_b128 v[212:215], v151 offset:39936
	global_load_lds_dwordx4 v[222:223], off
	v_lshl_add_u64 v[222:223], s[28:29], 0, v[130:131]
	s_mov_b32 m0, s35
	s_nop 0
	global_load_lds_dwordx4 v[222:223], off
	s_waitcnt vmcnt(8)
	s_waitcnt lgkmcnt(0)
	s_setprio 1
	s_barrier
	s_waitcnt lgkmcnt(0)
	v_mfma_f32_16x16x32_bf16 v[124:127], v[152:155], v[184:187], v[124:127]
	v_mfma_f32_16x16x32_bf16 v[120:123], v[160:163], v[184:187], v[120:123]
	v_mfma_f32_16x16x32_bf16 v[108:111], v[152:155], v[192:195], v[108:111]
	v_mfma_f32_16x16x32_bf16 v[104:107], v[160:163], v[192:195], v[104:107]
	v_mfma_f32_16x16x32_bf16 v[92:95], v[152:155], v[200:203], v[92:95]
	v_mfma_f32_16x16x32_bf16 v[88:91], v[160:163], v[200:203], v[88:91]
	v_mfma_f32_16x16x32_bf16 v[76:79], v[152:155], v[208:211], v[76:79]
	v_mfma_f32_16x16x32_bf16 v[72:75], v[160:163], v[208:211], v[72:75]
	v_mfma_f32_16x16x32_bf16 v[124:127], v[156:159], v[188:191], v[124:127]
	v_mfma_f32_16x16x32_bf16 v[120:123], v[164:167], v[188:191], v[120:123]
	v_mfma_f32_16x16x32_bf16 v[108:111], v[156:159], v[196:199], v[108:111]
	v_mfma_f32_16x16x32_bf16 v[104:107], v[164:167], v[196:199], v[104:107]
	v_mfma_f32_16x16x32_bf16 v[92:95], v[156:159], v[204:207], v[92:95]
	v_mfma_f32_16x16x32_bf16 v[88:91], v[164:167], v[204:207], v[88:91]
	v_mfma_f32_16x16x32_bf16 v[76:79], v[156:159], v[212:215], v[76:79]
	v_mfma_f32_16x16x32_bf16 v[72:75], v[164:167], v[212:215], v[72:75]
	s_setprio 0
	s_setprio 1
	v_mfma_f32_16x16x32_bf16 v[116:119], v[168:171], v[184:187], v[116:119]
	v_mfma_f32_16x16x32_bf16 v[112:115], v[176:179], v[184:187], v[112:115]
	v_mfma_f32_16x16x32_bf16 v[100:103], v[168:171], v[192:195], v[100:103]
	v_mfma_f32_16x16x32_bf16 v[96:99], v[176:179], v[192:195], v[96:99]
	v_mfma_f32_16x16x32_bf16 v[84:87], v[168:171], v[200:203], v[84:87]
	v_mfma_f32_16x16x32_bf16 v[80:83], v[176:179], v[200:203], v[80:83]
	v_mfma_f32_16x16x32_bf16 v[68:71], v[168:171], v[208:211], v[68:71]
	v_mfma_f32_16x16x32_bf16 v[64:67], v[176:179], v[208:211], v[64:67]
	v_mfma_f32_16x16x32_bf16 v[116:119], v[172:175], v[188:191], v[116:119]
	v_mfma_f32_16x16x32_bf16 v[112:115], v[180:183], v[188:191], v[112:115]
	v_mfma_f32_16x16x32_bf16 v[100:103], v[172:175], v[196:199], v[100:103]
	v_mfma_f32_16x16x32_bf16 v[96:99], v[180:183], v[196:199], v[96:99]
	v_mfma_f32_16x16x32_bf16 v[84:87], v[172:175], v[204:207], v[84:87]
	v_mfma_f32_16x16x32_bf16 v[80:83], v[180:183], v[204:207], v[80:83]
	v_mfma_f32_16x16x32_bf16 v[68:71], v[172:175], v[212:215], v[68:71]
	v_mfma_f32_16x16x32_bf16 v[64:67], v[180:183], v[212:215], v[64:67]
	s_setprio 0
	s_barrier
	s_add_i32 s28, s50, s30
	v_lshl_add_u64 v[144:145], v[144:145], 0, s[12:13]
	s_mov_b32 m0, s28
	ds_read_b128 v[184:187], v151 offset:49152
	ds_read_b128 v[188:191], v151 offset:50176
	ds_read_b128 v[192:195], v151 offset:51200
	ds_read_b128 v[196:199], v151 offset:52224
	ds_read_b128 v[200:203], v151 offset:53248
	ds_read_b128 v[204:207], v151 offset:54272
	ds_read_b128 v[208:211], v151 offset:55296
	ds_read_b128 v[212:215], v151 offset:56320
	global_load_lds_dwordx4 v[144:145], off
	s_add_i32 m0, s28, 0x2000
	s_add_u32 s26, s26, 0x40080
	v_lshl_add_u64 v[144:145], v[216:217], 0, s[12:13]
	s_addc_u32 s27, s27, 0
	s_add_i32 s28, s51, s30
	global_load_lds_dwordx4 v[144:145], off
	v_lshl_add_u64 v[144:145], s[26:27], 0, v[132:133]
	s_mov_b32 m0, s28
	s_nop 0
	global_load_lds_dwordx4 v[144:145], off
	v_lshl_add_u64 v[144:145], s[26:27], 0, v[128:129]
	s_add_i32 m0, s28, 0x2000
	s_nop 0
	global_load_lds_dwordx4 v[144:145], off
	v_lshl_add_u64 v[144:145], v[218:219], 0, s[12:13]
	s_mov_b32 m0, s37
	s_nop 0
	global_load_lds_dwordx4 v[144:145], off
	v_lshl_add_u64 v[144:145], v[220:221], 0, s[12:13]
	s_mov_b32 m0, s38
	s_nop 0
	global_load_lds_dwordx4 v[144:145], off
	s_waitcnt vmcnt(8)
	s_waitcnt lgkmcnt(0)
	s_setprio 1
	s_barrier
	s_waitcnt lgkmcnt(0)
	v_mfma_f32_16x16x32_bf16 v[60:63], v[152:155], v[184:187], v[60:63]
	v_mfma_f32_16x16x32_bf16 v[56:59], v[160:163], v[184:187], v[56:59]
	v_mfma_f32_16x16x32_bf16 v[44:47], v[152:155], v[192:195], v[44:47]
	v_mfma_f32_16x16x32_bf16 v[40:43], v[160:163], v[192:195], v[40:43]
	v_mfma_f32_16x16x32_bf16 v[28:31], v[152:155], v[200:203], v[28:31]
	v_mfma_f32_16x16x32_bf16 v[24:27], v[160:163], v[200:203], v[24:27]
	v_mfma_f32_16x16x32_bf16 v[12:15], v[152:155], v[208:211], v[12:15]
	v_mfma_f32_16x16x32_bf16 v[8:11], v[160:163], v[208:211], v[8:11]
	v_mfma_f32_16x16x32_bf16 v[60:63], v[156:159], v[188:191], v[60:63]
	v_mfma_f32_16x16x32_bf16 v[56:59], v[164:167], v[188:191], v[56:59]
	v_mfma_f32_16x16x32_bf16 v[44:47], v[156:159], v[196:199], v[44:47]
	v_mfma_f32_16x16x32_bf16 v[40:43], v[164:167], v[196:199], v[40:43]
	v_mfma_f32_16x16x32_bf16 v[28:31], v[156:159], v[204:207], v[28:31]
	v_mfma_f32_16x16x32_bf16 v[24:27], v[164:167], v[204:207], v[24:27]
	v_mfma_f32_16x16x32_bf16 v[12:15], v[156:159], v[212:215], v[12:15]
	v_mfma_f32_16x16x32_bf16 v[8:11], v[164:167], v[212:215], v[8:11]
	s_setprio 0
	s_setprio 1
	v_mfma_f32_16x16x32_bf16 v[52:55], v[168:171], v[184:187], v[52:55]
	v_mfma_f32_16x16x32_bf16 v[48:51], v[176:179], v[184:187], v[48:51]
	v_mfma_f32_16x16x32_bf16 v[36:39], v[168:171], v[192:195], v[36:39]
	v_mfma_f32_16x16x32_bf16 v[32:35], v[176:179], v[192:195], v[32:35]
	v_mfma_f32_16x16x32_bf16 v[20:23], v[168:171], v[200:203], v[20:23]
	v_mfma_f32_16x16x32_bf16 v[16:19], v[176:179], v[200:203], v[16:19]
	v_mfma_f32_16x16x32_bf16 v[4:7], v[168:171], v[208:211], v[4:7]
	v_mfma_f32_16x16x32_bf16 v[0:3], v[176:179], v[208:211], v[0:3]
	v_mfma_f32_16x16x32_bf16 v[52:55], v[172:175], v[188:191], v[52:55]
	v_mfma_f32_16x16x32_bf16 v[48:51], v[180:183], v[188:191], v[48:51]
	v_mfma_f32_16x16x32_bf16 v[36:39], v[172:175], v[196:199], v[36:39]
	v_mfma_f32_16x16x32_bf16 v[32:35], v[180:183], v[196:199], v[32:35]
	v_mfma_f32_16x16x32_bf16 v[20:23], v[172:175], v[204:207], v[20:23]
	v_mfma_f32_16x16x32_bf16 v[16:19], v[180:183], v[204:207], v[16:19]
	v_mfma_f32_16x16x32_bf16 v[4:7], v[172:175], v[212:215], v[4:7]
	v_mfma_f32_16x16x32_bf16 v[0:3], v[180:183], v[212:215], v[0:3]
	s_setprio 0
	s_barrier
	s_add_i32 s49, s49, 2
	s_add_u32 s47, s47, 0x100
	s_addc_u32 s48, s48, 0
	s_add_u32 s24, s24, 0x100
	s_addc_u32 s25, s25, 0
	s_cmp_gt_u32 s49, 13
	s_cbranch_scc0 .LBB0_877
	s_and_b64 vcc, exec, s[14:15]
	s_cbranch_vccz .LBB0_880
	s_barrier

.LBB0_949:
	ds_read_b128 v[150:153], v147
	ds_read_b128 v[154:157], v147 offset:1024
	ds_read_b128 v[158:161], v147 offset:2048
	ds_read_b128 v[162:165], v147 offset:3072
	ds_read_b128 v[166:169], v148
	ds_read_b128 v[170:173], v148 offset:1024
	ds_read_b128 v[174:177], v148 offset:2048
	ds_read_b128 v[178:181], v148 offset:3072
	s_add_u32 s34, s30, 0x100
	s_addc_u32 s35, s31, 0
	s_cmp_eq_u32 s59, 40
	s_cselect_b32 s39, s11, s35
	s_cselect_b32 s38, s10, s34
	s_cselect_b32 s37, s29, s58
	s_cselect_b32 s36, s28, s57
	v_lshl_add_u64 v[214:215], s[30:31], 0, v[138:139]
	s_add_i32 m0, s40, 0xc000
	ds_read_b128 v[182:185], v149
	ds_read_b128 v[186:189], v149 offset:1024
	ds_read_b128 v[190:193], v149 offset:2048
	ds_read_b128 v[194:197], v149 offset:3072
	ds_read_b128 v[198:201], v149 offset:4096
	ds_read_b128 v[202:205], v149 offset:5120
	ds_read_b128 v[206:209], v149 offset:6144
	ds_read_b128 v[210:213], v149 offset:7168
	global_load_lds_dwordx4 v[214:215], off
	v_lshl_add_u64 v[214:215], s[30:31], 0, v[136:137]
	s_add_i32 m0, s40, 0xe000
	s_nop 0
	global_load_lds_dwordx4 v[214:215], off
	s_waitcnt vmcnt(8)
	s_waitcnt lgkmcnt(0)
	s_setprio 1
	s_barrier
	s_waitcnt lgkmcnt(0)
	v_mfma_f32_16x16x32_bf16 v[124:127], v[150:153], v[182:185], v[124:127]
	v_mfma_f32_16x16x32_bf16 v[120:123], v[158:161], v[182:185], v[120:123]
	v_mfma_f32_16x16x32_bf16 v[116:119], v[150:153], v[190:193], v[116:119]
	v_mfma_f32_16x16x32_bf16 v[112:115], v[158:161], v[190:193], v[112:115]
	v_mfma_f32_16x16x32_bf16 v[100:103], v[150:153], v[198:201], v[100:103]
	v_mfma_f32_16x16x32_bf16 v[96:99], v[158:161], v[198:201], v[96:99]
	v_mfma_f32_16x16x32_bf16 v[84:87], v[150:153], v[206:209], v[84:87]
	v_mfma_f32_16x16x32_bf16 v[80:83], v[158:161], v[206:209], v[80:83]
	v_mfma_f32_16x16x32_bf16 v[124:127], v[154:157], v[186:189], v[124:127]
	v_mfma_f32_16x16x32_bf16 v[120:123], v[162:165], v[186:189], v[120:123]
	v_mfma_f32_16x16x32_bf16 v[116:119], v[154:157], v[194:197], v[116:119]
	v_mfma_f32_16x16x32_bf16 v[112:115], v[162:165], v[194:197], v[112:115]
	v_mfma_f32_16x16x32_bf16 v[100:103], v[154:157], v[202:205], v[100:103]
	v_mfma_f32_16x16x32_bf16 v[96:99], v[162:165], v[202:205], v[96:99]
	v_mfma_f32_16x16x32_bf16 v[84:87], v[154:157], v[210:213], v[84:87]
	v_mfma_f32_16x16x32_bf16 v[80:83], v[162:165], v[210:213], v[80:83]
	s_setprio 0
	s_setprio 1
	v_mfma_f32_16x16x32_bf16 v[108:111], v[166:169], v[182:185], v[108:111]
	v_mfma_f32_16x16x32_bf16 v[104:107], v[174:177], v[182:185], v[104:107]
	v_mfma_f32_16x16x32_bf16 v[92:95], v[166:169], v[190:193], v[92:95]
	v_mfma_f32_16x16x32_bf16 v[88:91], v[174:177], v[190:193], v[88:91]
	v_mfma_f32_16x16x32_bf16 v[76:79], v[166:169], v[198:201], v[76:79]
	v_mfma_f32_16x16x32_bf16 v[72:75], v[174:177], v[198:201], v[72:75]
	v_mfma_f32_16x16x32_bf16 v[68:71], v[166:169], v[206:209], v[68:71]
	v_mfma_f32_16x16x32_bf16 v[64:67], v[174:177], v[206:209], v[64:67]
	v_mfma_f32_16x16x32_bf16 v[108:111], v[170:173], v[186:189], v[108:111]
	v_mfma_f32_16x16x32_bf16 v[104:107], v[178:181], v[186:189], v[104:107]
	v_mfma_f32_16x16x32_bf16 v[92:95], v[170:173], v[194:197], v[92:95]
	v_mfma_f32_16x16x32_bf16 v[88:91], v[178:181], v[194:197], v[88:91]
	v_mfma_f32_16x16x32_bf16 v[76:79], v[170:173], v[202:205], v[76:79]
	v_mfma_f32_16x16x32_bf16 v[72:75], v[178:181], v[202:205], v[72:75]
	v_mfma_f32_16x16x32_bf16 v[68:71], v[170:173], v[210:213], v[68:71]
	v_mfma_f32_16x16x32_bf16 v[64:67], v[178:181], v[210:213], v[64:67]
	s_setprio 0
	s_barrier
	s_add_i32 s30, s47, s33
	v_lshl_add_u64 v[214:215], s[36:37], 0, v[132:133]
	s_mov_b32 m0, s30
	ds_read_b128 v[182:185], v149 offset:16384
	ds_read_b128 v[186:189], v149 offset:17408
	ds_read_b128 v[190:193], v149 offset:18432
	ds_read_b128 v[194:197], v149 offset:19456
	ds_read_b128 v[198:201], v149 offset:20480
	ds_read_b128 v[202:205], v149 offset:21504
	ds_read_b128 v[206:209], v149 offset:22528
	ds_read_b128 v[210:213], v149 offset:23552
	global_load_lds_dwordx4 v[214:215], off
	s_add_i32 m0, s30, 0x2000
	s_add_u32 s30, s36, 0xb0000
	v_lshl_add_u64 v[216:217], s[36:37], 0, v[128:129]
	s_addc_u32 s31, s37, 0
	s_add_i32 s60, s48, s33
	global_load_lds_dwordx4 v[216:217], off
	v_lshl_add_u64 v[218:219], s[30:31], 0, v[132:133]
	s_mov_b32 m0, s60
	v_lshl_add_u64 v[220:221], s[38:39], 0, v[130:131]
	global_load_lds_dwordx4 v[218:219], off
	v_lshl_add_u64 v[218:219], s[30:31], 0, v[128:129]
	s_add_i32 m0, s60, 0x2000
	s_nop 0
	global_load_lds_dwordx4 v[218:219], off
	v_lshl_add_u64 v[218:219], s[38:39], 0, v[134:135]
	s_mov_b32 m0, s40
	s_nop 0
	global_load_lds_dwordx4 v[218:219], off
	s_mov_b32 m0, s41
	s_nop 0
	global_load_lds_dwordx4 v[220:221], off
	s_waitcnt vmcnt(8)
	s_waitcnt lgkmcnt(0)
	s_setprio 1
	s_barrier
	s_waitcnt lgkmcnt(0)
	v_mfma_f32_16x16x32_bf16 v[60:63], v[150:153], v[182:185], v[60:63]
	v_mfma_f32_16x16x32_bf16 v[56:59], v[158:161], v[182:185], v[56:59]
	v_mfma_f32_16x16x32_bf16 v[52:55], v[150:153], v[190:193], v[52:55]
	v_mfma_f32_16x16x32_bf16 v[48:51], v[158:161], v[190:193], v[48:51]
	v_mfma_f32_16x16x32_bf16 v[36:39], v[150:153], v[198:201], v[36:39]
	v_mfma_f32_16x16x32_bf16 v[32:35], v[158:161], v[198:201], v[32:35]
	v_mfma_f32_16x16x32_bf16 v[20:23], v[150:153], v[206:209], v[20:23]
	v_mfma_f32_16x16x32_bf16 v[16:19], v[158:161], v[206:209], v[16:19]
	v_mfma_f32_16x16x32_bf16 v[60:63], v[154:157], v[186:189], v[60:63]
	v_mfma_f32_16x16x32_bf16 v[56:59], v[162:165], v[186:189], v[56:59]
	v_mfma_f32_16x16x32_bf16 v[52:55], v[154:157], v[194:197], v[52:55]
	v_mfma_f32_16x16x32_bf16 v[48:51], v[162:165], v[194:197], v[48:51]
	v_mfma_f32_16x16x32_bf16 v[36:39], v[154:157], v[202:205], v[36:39]
	v_mfma_f32_16x16x32_bf16 v[32:35], v[162:165], v[202:205], v[32:35]
	v_mfma_f32_16x16x32_bf16 v[20:23], v[154:157], v[210:213], v[20:23]
	v_mfma_f32_16x16x32_bf16 v[16:19], v[162:165], v[210:213], v[16:19]
	s_setprio 0
	s_setprio 1
	v_mfma_f32_16x16x32_bf16 v[44:47], v[166:169], v[182:185], v[44:47]
	v_mfma_f32_16x16x32_bf16 v[40:43], v[174:177], v[182:185], v[40:43]
	v_mfma_f32_16x16x32_bf16 v[28:31], v[166:169], v[190:193], v[28:31]
	v_mfma_f32_16x16x32_bf16 v[24:27], v[174:177], v[190:193], v[24:27]
	v_mfma_f32_16x16x32_bf16 v[12:15], v[166:169], v[198:201], v[12:15]
	v_mfma_f32_16x16x32_bf16 v[8:11], v[174:177], v[198:201], v[8:11]
	v_mfma_f32_16x16x32_bf16 v[4:7], v[166:169], v[206:209], v[4:7]
	v_mfma_f32_16x16x32_bf16 v[0:3], v[174:177], v[206:209], v[0:3]
	v_mfma_f32_16x16x32_bf16 v[44:47], v[170:173], v[186:189], v[44:47]
	v_mfma_f32_16x16x32_bf16 v[40:43], v[178:181], v[186:189], v[40:43]
	v_mfma_f32_16x16x32_bf16 v[28:31], v[170:173], v[194:197], v[28:31]
	v_mfma_f32_16x16x32_bf16 v[24:27], v[178:181], v[194:197], v[24:27]
	v_mfma_f32_16x16x32_bf16 v[12:15], v[170:173], v[202:205], v[12:15]
	v_mfma_f32_16x16x32_bf16 v[8:11], v[178:181], v[202:205], v[8:11]
	v_mfma_f32_16x16x32_bf16 v[4:7], v[170:173], v[210:213], v[4:7]
	v_mfma_f32_16x16x32_bf16 v[0:3], v[178:181], v[210:213], v[0:3]
	s_setprio 0
	s_barrier
	s_add_i32 s60, 0, 0x18000
	s_add_i32 s61, 0, 0x1c000
	v_add_u32_e32 v162, s60, v145
	v_add_u32_e32 v178, s61, v145
	ds_read_b128 v[150:153], v162
	ds_read_b128 v[154:157], v162 offset:1024
	ds_read_b128 v[158:161], v162 offset:2048
	ds_read_b128 v[162:165], v162 offset:3072
	ds_read_b128 v[166:169], v178
	ds_read_b128 v[170:173], v178 offset:1024
	ds_read_b128 v[174:177], v178 offset:2048
	ds_read_b128 v[178:181], v178 offset:3072
	s_add_u32 s30, s38, 0xb0000
	s_addc_u32 s31, s39, 0
	s_mov_b32 m0, s42
	v_lshl_add_u64 v[222:223], s[30:31], 0, v[134:135]
	ds_read_b128 v[182:185], v149 offset:32768
	ds_read_b128 v[186:189], v149 offset:33792
	ds_read_b128 v[190:193], v149 offset:34816
	ds_read_b128 v[194:197], v149 offset:35840
	ds_read_b128 v[198:201], v149 offset:36864
	ds_read_b128 v[202:205], v149 offset:37888
	ds_read_b128 v[206:209], v149 offset:38912
	ds_read_b128 v[210:213], v149 offset:39936
	global_load_lds_dwordx4 v[222:223], off
	v_lshl_add_u64 v[222:223], s[30:31], 0, v[130:131]
	s_mov_b32 m0, s43
	s_nop 0
	global_load_lds_dwordx4 v[222:223], off
	s_waitcnt vmcnt(8)
	s_waitcnt lgkmcnt(0)
	s_setprio 1
	s_barrier
	s_waitcnt lgkmcnt(0)
	v_mfma_f32_16x16x32_bf16 v[124:127], v[150:153], v[182:185], v[124:127]
	v_mfma_f32_16x16x32_bf16 v[120:123], v[158:161], v[182:185], v[120:123]
	v_mfma_f32_16x16x32_bf16 v[116:119], v[150:153], v[190:193], v[116:119]
	v_mfma_f32_16x16x32_bf16 v[112:115], v[158:161], v[190:193], v[112:115]
	v_mfma_f32_16x16x32_bf16 v[100:103], v[150:153], v[198:201], v[100:103]
	v_mfma_f32_16x16x32_bf16 v[96:99], v[158:161], v[198:201], v[96:99]
	v_mfma_f32_16x16x32_bf16 v[84:87], v[150:153], v[206:209], v[84:87]
	v_mfma_f32_16x16x32_bf16 v[80:83], v[158:161], v[206:209], v[80:83]
	v_mfma_f32_16x16x32_bf16 v[124:127], v[154:157], v[186:189], v[124:127]
	v_mfma_f32_16x16x32_bf16 v[120:123], v[162:165], v[186:189], v[120:123]
	v_mfma_f32_16x16x32_bf16 v[116:119], v[154:157], v[194:197], v[116:119]
	v_mfma_f32_16x16x32_bf16 v[112:115], v[162:165], v[194:197], v[112:115]
	v_mfma_f32_16x16x32_bf16 v[100:103], v[154:157], v[202:205], v[100:103]
	v_mfma_f32_16x16x32_bf16 v[96:99], v[162:165], v[202:205], v[96:99]
	v_mfma_f32_16x16x32_bf16 v[84:87], v[154:157], v[210:213], v[84:87]
	v_mfma_f32_16x16x32_bf16 v[80:83], v[162:165], v[210:213], v[80:83]
	s_setprio 0
	s_setprio 1
	v_mfma_f32_16x16x32_bf16 v[108:111], v[166:169], v[182:185], v[108:111]
	v_mfma_f32_16x16x32_bf16 v[104:107], v[174:177], v[182:185], v[104:107]
	v_mfma_f32_16x16x32_bf16 v[92:95], v[166:169], v[190:193], v[92:95]
	v_mfma_f32_16x16x32_bf16 v[88:91], v[174:177], v[190:193], v[88:91]
	v_mfma_f32_16x16x32_bf16 v[76:79], v[166:169], v[198:201], v[76:79]
	v_mfma_f32_16x16x32_bf16 v[72:75], v[174:177], v[198:201], v[72:75]
	v_mfma_f32_16x16x32_bf16 v[68:71], v[166:169], v[206:209], v[68:71]
	v_mfma_f32_16x16x32_bf16 v[64:67], v[174:177], v[206:209], v[64:67]
	v_mfma_f32_16x16x32_bf16 v[108:111], v[170:173], v[186:189], v[108:111]
	v_mfma_f32_16x16x32_bf16 v[104:107], v[178:181], v[186:189], v[104:107]
	v_mfma_f32_16x16x32_bf16 v[92:95], v[170:173], v[194:197], v[92:95]
	v_mfma_f32_16x16x32_bf16 v[88:91], v[178:181], v[194:197], v[88:91]
	v_mfma_f32_16x16x32_bf16 v[76:79], v[170:173], v[202:205], v[76:79]
	v_mfma_f32_16x16x32_bf16 v[72:75], v[178:181], v[202:205], v[72:75]
	v_mfma_f32_16x16x32_bf16 v[68:71], v[170:173], v[210:213], v[68:71]
	v_mfma_f32_16x16x32_bf16 v[64:67], v[178:181], v[210:213], v[64:67]
	s_setprio 0
	s_barrier
	s_add_i32 s30, s60, s33
	v_lshl_add_u64 v[214:215], v[214:215], 0, s[16:17]
	s_mov_b32 m0, s30
	ds_read_b128 v[182:185], v149 offset:49152
	ds_read_b128 v[186:189], v149 offset:50176
	ds_read_b128 v[190:193], v149 offset:51200
	ds_read_b128 v[194:197], v149 offset:52224
	ds_read_b128 v[198:201], v149 offset:53248
	ds_read_b128 v[202:205], v149 offset:54272
	ds_read_b128 v[206:209], v149 offset:55296
	ds_read_b128 v[210:213], v149 offset:56320
	global_load_lds_dwordx4 v[214:215], off
	s_add_i32 m0, s30, 0x2000
	s_add_u32 s30, s36, 0xb0080
	v_lshl_add_u64 v[214:215], v[216:217], 0, s[16:17]
	s_addc_u32 s31, s37, 0
	s_add_i32 s36, s61, s33
	global_load_lds_dwordx4 v[214:215], off
	v_lshl_add_u64 v[214:215], s[30:31], 0, v[132:133]
	s_mov_b32 m0, s36
	s_nop 0
	global_load_lds_dwordx4 v[214:215], off
	v_lshl_add_u64 v[214:215], s[30:31], 0, v[128:129]
	s_add_i32 m0, s36, 0x2000
	s_nop 0
	global_load_lds_dwordx4 v[214:215], off
	v_lshl_add_u64 v[214:215], v[218:219], 0, s[16:17]
	s_mov_b32 m0, s45
	s_nop 0
	global_load_lds_dwordx4 v[214:215], off
	v_lshl_add_u64 v[214:215], v[220:221], 0, s[16:17]
	s_mov_b32 m0, s46
	s_nop 0
	global_load_lds_dwordx4 v[214:215], off
	s_waitcnt vmcnt(8)
	s_waitcnt lgkmcnt(0)
	s_setprio 1
	s_barrier
	s_waitcnt lgkmcnt(0)
	v_mfma_f32_16x16x32_bf16 v[60:63], v[150:153], v[182:185], v[60:63]
	v_mfma_f32_16x16x32_bf16 v[56:59], v[158:161], v[182:185], v[56:59]
	v_mfma_f32_16x16x32_bf16 v[52:55], v[150:153], v[190:193], v[52:55]
	v_mfma_f32_16x16x32_bf16 v[48:51], v[158:161], v[190:193], v[48:51]
	v_mfma_f32_16x16x32_bf16 v[36:39], v[150:153], v[198:201], v[36:39]
	v_mfma_f32_16x16x32_bf16 v[32:35], v[158:161], v[198:201], v[32:35]
	v_mfma_f32_16x16x32_bf16 v[20:23], v[150:153], v[206:209], v[20:23]
	v_mfma_f32_16x16x32_bf16 v[16:19], v[158:161], v[206:209], v[16:19]
	v_mfma_f32_16x16x32_bf16 v[60:63], v[154:157], v[186:189], v[60:63]
	v_mfma_f32_16x16x32_bf16 v[56:59], v[162:165], v[186:189], v[56:59]
	v_mfma_f32_16x16x32_bf16 v[52:55], v[154:157], v[194:197], v[52:55]
	v_mfma_f32_16x16x32_bf16 v[48:51], v[162:165], v[194:197], v[48:51]
	v_mfma_f32_16x16x32_bf16 v[36:39], v[154:157], v[202:205], v[36:39]
	v_mfma_f32_16x16x32_bf16 v[32:35], v[162:165], v[202:205], v[32:35]
	v_mfma_f32_16x16x32_bf16 v[20:23], v[154:157], v[210:213], v[20:23]
	v_mfma_f32_16x16x32_bf16 v[16:19], v[162:165], v[210:213], v[16:19]
	s_setprio 0
	s_setprio 1
	v_mfma_f32_16x16x32_bf16 v[44:47], v[166:169], v[182:185], v[44:47]
	v_mfma_f32_16x16x32_bf16 v[40:43], v[174:177], v[182:185], v[40:43]
	v_mfma_f32_16x16x32_bf16 v[28:31], v[166:169], v[190:193], v[28:31]
	v_mfma_f32_16x16x32_bf16 v[24:27], v[174:177], v[190:193], v[24:27]
	v_mfma_f32_16x16x32_bf16 v[12:15], v[166:169], v[198:201], v[12:15]
	v_mfma_f32_16x16x32_bf16 v[8:11], v[174:177], v[198:201], v[8:11]
	v_mfma_f32_16x16x32_bf16 v[4:7], v[166:169], v[206:209], v[4:7]
	v_mfma_f32_16x16x32_bf16 v[0:3], v[174:177], v[206:209], v[0:3]
	v_mfma_f32_16x16x32_bf16 v[44:47], v[170:173], v[186:189], v[44:47]
	v_mfma_f32_16x16x32_bf16 v[40:43], v[178:181], v[186:189], v[40:43]
	v_mfma_f32_16x16x32_bf16 v[28:31], v[170:173], v[194:197], v[28:31]
	v_mfma_f32_16x16x32_bf16 v[24:27], v[178:181], v[194:197], v[24:27]
	v_mfma_f32_16x16x32_bf16 v[12:15], v[170:173], v[202:205], v[12:15]
	v_mfma_f32_16x16x32_bf16 v[8:11], v[178:181], v[202:205], v[8:11]
	v_mfma_f32_16x16x32_bf16 v[4:7], v[170:173], v[210:213], v[4:7]
	v_mfma_f32_16x16x32_bf16 v[0:3], v[178:181], v[210:213], v[0:3]
	s_setprio 0
	s_barrier
	s_add_i32 s59, s59, 2
	s_add_u32 s57, s57, 0x100
	s_addc_u32 s58, s58, 0
	s_cmp_gt_u32 s59, 41
	s_mov_b64 s[30:31], s[34:35]
	s_cbranch_scc0 .LBB0_949
	s_and_b64 vcc, exec, s[18:19]
	s_cbranch_vccz .LBB0_952
	s_barrier

.LBB0_1111:
	ds_read_b128 v[144:147], v153
	ds_read_b128 v[156:159], v153 offset:1024
	ds_read_b128 v[160:163], v153 offset:2048
	ds_read_b128 v[164:167], v153 offset:3072
	ds_read_b128 v[168:171], v154
	ds_read_b128 v[172:175], v154 offset:1024
	ds_read_b128 v[176:179], v154 offset:2048
	ds_read_b128 v[180:183], v154 offset:3072
	s_add_u32 s42, s40, 0xfffc0080
	s_addc_u32 s43, s41, -1
	s_cmp_eq_u32 s63, 12
	s_cselect_b32 s45, s31, s43
	s_cselect_b32 s44, s59, s42
	s_cselect_b32 s43, s29, s62
	s_cselect_b32 s42, s60, s61
	v_lshl_add_u64 v[148:149], s[40:41], 0, v[138:139]
	s_add_i32 m0, s39, 0xc000
	ds_read_b128 v[184:187], v155
	ds_read_b128 v[188:191], v155 offset:1024
	ds_read_b128 v[192:195], v155 offset:2048
	ds_read_b128 v[196:199], v155 offset:3072
	ds_read_b128 v[200:203], v155 offset:4096
	ds_read_b128 v[204:207], v155 offset:5120
	ds_read_b128 v[208:211], v155 offset:6144
	ds_read_b128 v[212:215], v155 offset:7168
	global_load_lds_dwordx4 v[148:149], off
	v_lshl_add_u64 v[148:149], s[40:41], 0, v[136:137]
	s_add_i32 m0, s39, 0xe000
	s_nop 0
	global_load_lds_dwordx4 v[148:149], off
	s_waitcnt vmcnt(8)
	s_waitcnt lgkmcnt(0)
	s_setprio 1
	s_barrier
	s_waitcnt lgkmcnt(0)
	v_mfma_f32_16x16x32_bf16 v[124:127], v[144:147], v[184:187], v[124:127]
	v_mfma_f32_16x16x32_bf16 v[120:123], v[160:163], v[184:187], v[120:123]
	v_mfma_f32_16x16x32_bf16 v[108:111], v[144:147], v[192:195], v[108:111]
	v_mfma_f32_16x16x32_bf16 v[104:107], v[160:163], v[192:195], v[104:107]
	v_mfma_f32_16x16x32_bf16 v[92:95], v[144:147], v[200:203], v[92:95]
	v_mfma_f32_16x16x32_bf16 v[88:91], v[160:163], v[200:203], v[88:91]
	v_mfma_f32_16x16x32_bf16 v[76:79], v[144:147], v[208:211], v[76:79]
	v_mfma_f32_16x16x32_bf16 v[72:75], v[160:163], v[208:211], v[72:75]
	v_mfma_f32_16x16x32_bf16 v[124:127], v[156:159], v[188:191], v[124:127]
	v_mfma_f32_16x16x32_bf16 v[120:123], v[164:167], v[188:191], v[120:123]
	v_mfma_f32_16x16x32_bf16 v[108:111], v[156:159], v[196:199], v[108:111]
	v_mfma_f32_16x16x32_bf16 v[104:107], v[164:167], v[196:199], v[104:107]
	v_mfma_f32_16x16x32_bf16 v[92:95], v[156:159], v[204:207], v[92:95]
	v_mfma_f32_16x16x32_bf16 v[88:91], v[164:167], v[204:207], v[88:91]
	v_mfma_f32_16x16x32_bf16 v[76:79], v[156:159], v[212:215], v[76:79]
	v_mfma_f32_16x16x32_bf16 v[72:75], v[164:167], v[212:215], v[72:75]
	s_setprio 0
	s_setprio 1
	v_mfma_f32_16x16x32_bf16 v[116:119], v[168:171], v[184:187], v[116:119]
	v_mfma_f32_16x16x32_bf16 v[112:115], v[176:179], v[184:187], v[112:115]
	v_mfma_f32_16x16x32_bf16 v[100:103], v[168:171], v[192:195], v[100:103]
	v_mfma_f32_16x16x32_bf16 v[96:99], v[176:179], v[192:195], v[96:99]
	v_mfma_f32_16x16x32_bf16 v[84:87], v[168:171], v[200:203], v[84:87]
	v_mfma_f32_16x16x32_bf16 v[80:83], v[176:179], v[200:203], v[80:83]
	v_mfma_f32_16x16x32_bf16 v[68:71], v[168:171], v[208:211], v[68:71]
	v_mfma_f32_16x16x32_bf16 v[64:67], v[176:179], v[208:211], v[64:67]
	v_mfma_f32_16x16x32_bf16 v[116:119], v[172:175], v[188:191], v[116:119]
	v_mfma_f32_16x16x32_bf16 v[112:115], v[180:183], v[188:191], v[112:115]
	v_mfma_f32_16x16x32_bf16 v[100:103], v[172:175], v[196:199], v[100:103]
	v_mfma_f32_16x16x32_bf16 v[96:99], v[180:183], v[196:199], v[96:99]
	v_mfma_f32_16x16x32_bf16 v[84:87], v[172:175], v[204:207], v[84:87]
	v_mfma_f32_16x16x32_bf16 v[80:83], v[180:183], v[204:207], v[80:83]
	v_mfma_f32_16x16x32_bf16 v[68:71], v[172:175], v[212:215], v[68:71]
	v_mfma_f32_16x16x32_bf16 v[64:67], v[180:183], v[212:215], v[64:67]
	s_setprio 0
	s_barrier
	s_add_i32 s64, s52, s33
	v_lshl_add_u64 v[148:149], s[42:43], 0, v[130:131]
	s_mov_b32 m0, s64
	ds_read_b128 v[184:187], v155 offset:16384
	ds_read_b128 v[188:191], v155 offset:17408
	ds_read_b128 v[192:195], v155 offset:18432
	ds_read_b128 v[196:199], v155 offset:19456
	ds_read_b128 v[200:203], v155 offset:20480
	ds_read_b128 v[204:207], v155 offset:21504
	ds_read_b128 v[208:211], v155 offset:22528
	ds_read_b128 v[212:215], v155 offset:23552
	global_load_lds_dwordx4 v[148:149], off
	s_add_i32 m0, s64, 0x2000
	s_add_u32 s64, s42, 0x40000
	v_lshl_add_u64 v[216:217], s[42:43], 0, v[134:135]
	s_addc_u32 s65, s43, 0
	s_add_i32 s66, s53, s33
	global_load_lds_dwordx4 v[216:217], off
	v_lshl_add_u64 v[218:219], s[64:65], 0, v[130:131]
	s_mov_b32 m0, s66
	v_lshl_add_u64 v[220:221], s[44:45], 0, v[132:133]
	global_load_lds_dwordx4 v[218:219], off
	v_lshl_add_u64 v[218:219], s[64:65], 0, v[134:135]
	s_add_i32 m0, s66, 0x2000
	s_nop 0
	global_load_lds_dwordx4 v[218:219], off
	v_lshl_add_u64 v[218:219], s[44:45], 0, v[128:129]
	s_mov_b32 m0, s39
	s_nop 0
	global_load_lds_dwordx4 v[218:219], off
	s_mov_b32 m0, s46
	s_nop 0
	global_load_lds_dwordx4 v[220:221], off
	s_waitcnt vmcnt(8)
	s_waitcnt lgkmcnt(0)
	s_setprio 1
	s_barrier
	s_waitcnt lgkmcnt(0)
	v_mfma_f32_16x16x32_bf16 v[60:63], v[144:147], v[184:187], v[60:63]
	v_mfma_f32_16x16x32_bf16 v[56:59], v[160:163], v[184:187], v[56:59]
	v_mfma_f32_16x16x32_bf16 v[44:47], v[144:147], v[192:195], v[44:47]
	v_mfma_f32_16x16x32_bf16 v[40:43], v[160:163], v[192:195], v[40:43]
	v_mfma_f32_16x16x32_bf16 v[28:31], v[144:147], v[200:203], v[28:31]
	v_mfma_f32_16x16x32_bf16 v[24:27], v[160:163], v[200:203], v[24:27]
	v_mfma_f32_16x16x32_bf16 v[12:15], v[144:147], v[208:211], v[12:15]
	v_mfma_f32_16x16x32_bf16 v[8:11], v[160:163], v[208:211], v[8:11]
	v_mfma_f32_16x16x32_bf16 v[60:63], v[156:159], v[188:191], v[60:63]
	v_mfma_f32_16x16x32_bf16 v[56:59], v[164:167], v[188:191], v[56:59]
	v_mfma_f32_16x16x32_bf16 v[44:47], v[156:159], v[196:199], v[44:47]
	v_mfma_f32_16x16x32_bf16 v[40:43], v[164:167], v[196:199], v[40:43]
	v_mfma_f32_16x16x32_bf16 v[28:31], v[156:159], v[204:207], v[28:31]
	v_mfma_f32_16x16x32_bf16 v[24:27], v[164:167], v[204:207], v[24:27]
	v_mfma_f32_16x16x32_bf16 v[12:15], v[156:159], v[212:215], v[12:15]
	v_mfma_f32_16x16x32_bf16 v[8:11], v[164:167], v[212:215], v[8:11]
	s_setprio 0
	s_setprio 1
	v_mfma_f32_16x16x32_bf16 v[52:55], v[168:171], v[184:187], v[52:55]
	v_mfma_f32_16x16x32_bf16 v[48:51], v[176:179], v[184:187], v[48:51]
	v_mfma_f32_16x16x32_bf16 v[36:39], v[168:171], v[192:195], v[36:39]
	v_mfma_f32_16x16x32_bf16 v[32:35], v[176:179], v[192:195], v[32:35]
	v_mfma_f32_16x16x32_bf16 v[20:23], v[168:171], v[200:203], v[20:23]
	v_mfma_f32_16x16x32_bf16 v[16:19], v[176:179], v[200:203], v[16:19]
	v_mfma_f32_16x16x32_bf16 v[4:7], v[168:171], v[208:211], v[4:7]
	v_mfma_f32_16x16x32_bf16 v[0:3], v[176:179], v[208:211], v[0:3]
	v_mfma_f32_16x16x32_bf16 v[52:55], v[172:175], v[188:191], v[52:55]
	v_mfma_f32_16x16x32_bf16 v[48:51], v[180:183], v[188:191], v[48:51]
	v_mfma_f32_16x16x32_bf16 v[36:39], v[172:175], v[196:199], v[36:39]
	v_mfma_f32_16x16x32_bf16 v[32:35], v[180:183], v[196:199], v[32:35]
	v_mfma_f32_16x16x32_bf16 v[20:23], v[172:175], v[204:207], v[20:23]
	v_mfma_f32_16x16x32_bf16 v[16:19], v[180:183], v[204:207], v[16:19]
	v_mfma_f32_16x16x32_bf16 v[4:7], v[172:175], v[212:215], v[4:7]
	v_mfma_f32_16x16x32_bf16 v[0:3], v[180:183], v[212:215], v[0:3]
	s_setprio 0
	s_barrier
	s_add_i32 s64, 0, 0x18000
	s_add_i32 s65, 0, 0x1c000
	v_add_u32_e32 v164, s64, v151
	v_add_u32_e32 v180, s65, v151
	ds_read_b128 v[144:147], v164
	ds_read_b128 v[156:159], v164 offset:1024
	ds_read_b128 v[160:163], v164 offset:2048
	ds_read_b128 v[164:167], v164 offset:3072
	ds_read_b128 v[168:171], v180
	ds_read_b128 v[172:175], v180 offset:1024
	ds_read_b128 v[176:179], v180 offset:2048
	ds_read_b128 v[180:183], v180 offset:3072
	s_add_u32 s44, s44, 0x40000
	s_addc_u32 s45, s45, 0
	s_mov_b32 m0, s47
	v_lshl_add_u64 v[222:223], s[44:45], 0, v[128:129]
	ds_read_b128 v[184:187], v155 offset:32768
	ds_read_b128 v[188:191], v155 offset:33792
	ds_read_b128 v[192:195], v155 offset:34816
	ds_read_b128 v[196:199], v155 offset:35840
	ds_read_b128 v[200:203], v155 offset:36864
	ds_read_b128 v[204:207], v155 offset:37888
	ds_read_b128 v[208:211], v155 offset:38912
	ds_read_b128 v[212:215], v155 offset:39936
	global_load_lds_dwordx4 v[222:223], off
	v_lshl_add_u64 v[222:223], s[44:45], 0, v[132:133]
	s_mov_b32 m0, s48
	s_nop 0
	global_load_lds_dwordx4 v[222:223], off
	s_waitcnt vmcnt(8)
	s_waitcnt lgkmcnt(0)
	s_setprio 1
	s_barrier
	s_waitcnt lgkmcnt(0)
	v_mfma_f32_16x16x32_bf16 v[124:127], v[144:147], v[184:187], v[124:127]
	v_mfma_f32_16x16x32_bf16 v[120:123], v[160:163], v[184:187], v[120:123]
	v_mfma_f32_16x16x32_bf16 v[108:111], v[144:147], v[192:195], v[108:111]
	v_mfma_f32_16x16x32_bf16 v[104:107], v[160:163], v[192:195], v[104:107]
	v_mfma_f32_16x16x32_bf16 v[92:95], v[144:147], v[200:203], v[92:95]
	v_mfma_f32_16x16x32_bf16 v[88:91], v[160:163], v[200:203], v[88:91]
	v_mfma_f32_16x16x32_bf16 v[76:79], v[144:147], v[208:211], v[76:79]
	v_mfma_f32_16x16x32_bf16 v[72:75], v[160:163], v[208:211], v[72:75]
	v_mfma_f32_16x16x32_bf16 v[124:127], v[156:159], v[188:191], v[124:127]
	v_mfma_f32_16x16x32_bf16 v[120:123], v[164:167], v[188:191], v[120:123]
	v_mfma_f32_16x16x32_bf16 v[108:111], v[156:159], v[196:199], v[108:111]
	v_mfma_f32_16x16x32_bf16 v[104:107], v[164:167], v[196:199], v[104:107]
	v_mfma_f32_16x16x32_bf16 v[92:95], v[156:159], v[204:207], v[92:95]
	v_mfma_f32_16x16x32_bf16 v[88:91], v[164:167], v[204:207], v[88:91]
	v_mfma_f32_16x16x32_bf16 v[76:79], v[156:159], v[212:215], v[76:79]
	v_mfma_f32_16x16x32_bf16 v[72:75], v[164:167], v[212:215], v[72:75]
	s_setprio 0
	s_setprio 1
	v_mfma_f32_16x16x32_bf16 v[116:119], v[168:171], v[184:187], v[116:119]
	v_mfma_f32_16x16x32_bf16 v[112:115], v[176:179], v[184:187], v[112:115]
	v_mfma_f32_16x16x32_bf16 v[100:103], v[168:171], v[192:195], v[100:103]
	v_mfma_f32_16x16x32_bf16 v[96:99], v[176:179], v[192:195], v[96:99]
	v_mfma_f32_16x16x32_bf16 v[84:87], v[168:171], v[200:203], v[84:87]
	v_mfma_f32_16x16x32_bf16 v[80:83], v[176:179], v[200:203], v[80:83]
	v_mfma_f32_16x16x32_bf16 v[68:71], v[168:171], v[208:211], v[68:71]
	v_mfma_f32_16x16x32_bf16 v[64:67], v[176:179], v[208:211], v[64:67]
	v_mfma_f32_16x16x32_bf16 v[116:119], v[172:175], v[188:191], v[116:119]
	v_mfma_f32_16x16x32_bf16 v[112:115], v[180:183], v[188:191], v[112:115]
	v_mfma_f32_16x16x32_bf16 v[100:103], v[172:175], v[196:199], v[100:103]
	v_mfma_f32_16x16x32_bf16 v[96:99], v[180:183], v[196:199], v[96:99]
	v_mfma_f32_16x16x32_bf16 v[84:87], v[172:175], v[204:207], v[84:87]
	v_mfma_f32_16x16x32_bf16 v[80:83], v[180:183], v[204:207], v[80:83]
	v_mfma_f32_16x16x32_bf16 v[68:71], v[172:175], v[212:215], v[68:71]
	v_mfma_f32_16x16x32_bf16 v[64:67], v[180:183], v[212:215], v[64:67]
	s_setprio 0
	s_barrier
	s_add_i32 s44, s64, s33
	v_lshl_add_u64 v[148:149], v[148:149], 0, s[18:19]
	s_mov_b32 m0, s44
	ds_read_b128 v[184:187], v155 offset:49152
	ds_read_b128 v[188:191], v155 offset:50176
	ds_read_b128 v[192:195], v155 offset:51200
	ds_read_b128 v[196:199], v155 offset:52224
	ds_read_b128 v[200:203], v155 offset:53248
	ds_read_b128 v[204:207], v155 offset:54272
	ds_read_b128 v[208:211], v155 offset:55296
	ds_read_b128 v[212:215], v155 offset:56320
	global_load_lds_dwordx4 v[148:149], off
	s_add_i32 m0, s44, 0x2000
	s_add_u32 s42, s42, 0x40080
	v_lshl_add_u64 v[148:149], v[216:217], 0, s[18:19]
	s_addc_u32 s43, s43, 0
	s_add_i32 s44, s65, s33
	global_load_lds_dwordx4 v[148:149], off
	v_lshl_add_u64 v[148:149], s[42:43], 0, v[130:131]
	s_mov_b32 m0, s44
	s_nop 0
	global_load_lds_dwordx4 v[148:149], off
	v_lshl_add_u64 v[148:149], s[42:43], 0, v[134:135]
	s_add_i32 m0, s44, 0x2000
	s_nop 0
	global_load_lds_dwordx4 v[148:149], off
	v_lshl_add_u64 v[148:149], v[218:219], 0, s[18:19]
	s_mov_b32 m0, s50
	s_nop 0
	global_load_lds_dwordx4 v[148:149], off
	v_lshl_add_u64 v[148:149], v[220:221], 0, s[18:19]
	s_mov_b32 m0, s51
	s_nop 0
	global_load_lds_dwordx4 v[148:149], off
	s_waitcnt vmcnt(8)
	s_waitcnt lgkmcnt(0)
	s_setprio 1
	s_barrier
	s_waitcnt lgkmcnt(0)
	v_mfma_f32_16x16x32_bf16 v[60:63], v[144:147], v[184:187], v[60:63]
	v_mfma_f32_16x16x32_bf16 v[56:59], v[160:163], v[184:187], v[56:59]
	v_mfma_f32_16x16x32_bf16 v[44:47], v[144:147], v[192:195], v[44:47]
	v_mfma_f32_16x16x32_bf16 v[40:43], v[160:163], v[192:195], v[40:43]
	v_mfma_f32_16x16x32_bf16 v[28:31], v[144:147], v[200:203], v[28:31]
	v_mfma_f32_16x16x32_bf16 v[24:27], v[160:163], v[200:203], v[24:27]
	v_mfma_f32_16x16x32_bf16 v[12:15], v[144:147], v[208:211], v[12:15]
	v_mfma_f32_16x16x32_bf16 v[8:11], v[160:163], v[208:211], v[8:11]
	v_mfma_f32_16x16x32_bf16 v[60:63], v[156:159], v[188:191], v[60:63]
	v_mfma_f32_16x16x32_bf16 v[56:59], v[164:167], v[188:191], v[56:59]
	v_mfma_f32_16x16x32_bf16 v[44:47], v[156:159], v[196:199], v[44:47]
	v_mfma_f32_16x16x32_bf16 v[40:43], v[164:167], v[196:199], v[40:43]
	v_mfma_f32_16x16x32_bf16 v[28:31], v[156:159], v[204:207], v[28:31]
	v_mfma_f32_16x16x32_bf16 v[24:27], v[164:167], v[204:207], v[24:27]
	v_mfma_f32_16x16x32_bf16 v[12:15], v[156:159], v[212:215], v[12:15]
	v_mfma_f32_16x16x32_bf16 v[8:11], v[164:167], v[212:215], v[8:11]
	s_setprio 0
	s_setprio 1
	v_mfma_f32_16x16x32_bf16 v[52:55], v[168:171], v[184:187], v[52:55]
	v_mfma_f32_16x16x32_bf16 v[48:51], v[176:179], v[184:187], v[48:51]
	v_mfma_f32_16x16x32_bf16 v[36:39], v[168:171], v[192:195], v[36:39]
	v_mfma_f32_16x16x32_bf16 v[32:35], v[176:179], v[192:195], v[32:35]
	v_mfma_f32_16x16x32_bf16 v[20:23], v[168:171], v[200:203], v[20:23]
	v_mfma_f32_16x16x32_bf16 v[16:19], v[176:179], v[200:203], v[16:19]
	v_mfma_f32_16x16x32_bf16 v[4:7], v[168:171], v[208:211], v[4:7]
	v_mfma_f32_16x16x32_bf16 v[0:3], v[176:179], v[208:211], v[0:3]
	v_mfma_f32_16x16x32_bf16 v[52:55], v[172:175], v[188:191], v[52:55]
	v_mfma_f32_16x16x32_bf16 v[48:51], v[180:183], v[188:191], v[48:51]
	v_mfma_f32_16x16x32_bf16 v[36:39], v[172:175], v[196:199], v[36:39]
	v_mfma_f32_16x16x32_bf16 v[32:35], v[180:183], v[196:199], v[32:35]
	v_mfma_f32_16x16x32_bf16 v[20:23], v[172:175], v[204:207], v[20:23]
	v_mfma_f32_16x16x32_bf16 v[16:19], v[180:183], v[204:207], v[16:19]
	v_mfma_f32_16x16x32_bf16 v[4:7], v[172:175], v[212:215], v[4:7]
	v_mfma_f32_16x16x32_bf16 v[0:3], v[180:183], v[212:215], v[0:3]
	s_setprio 0
	s_barrier
	s_add_i32 s63, s63, 2
	s_add_u32 s61, s61, 0x100
	s_addc_u32 s62, s62, 0
	s_add_u32 s40, s40, 0x100
	s_addc_u32 s41, s41, 0
	s_cmp_gt_u32 s63, 13
	s_cbranch_scc0 .LBB0_1111
	s_and_b64 vcc, exec, s[20:21]
	s_cbranch_vccz .LBB0_1114
	s_barrier

.LBB0_1134:
	ds_read_b128 v[0:3], v161
	ds_read_b128 v[4:7], v161 offset:1024
	ds_read_b128 v[8:11], v161 offset:2048
	ds_read_b128 v[12:15], v161 offset:3072
	ds_read_b128 v[16:19], v162
	ds_read_b128 v[20:23], v162 offset:1024
	ds_read_b128 v[24:27], v162 offset:2048
	ds_read_b128 v[28:31], v162 offset:3072
	s_ashr_i32 s37, s36, 31
	s_lshl_b64 s[38:39], s[36:37], 17
	s_add_u32 s38, s10, s38
	s_addc_u32 s39, s11, s39
	s_and_b64 s[40:41], s[8:9], exec
	s_cselect_b32 s51, s39, s45
	s_cselect_b32 s50, s38, s44
	s_ashr_i32 s35, s34, 31
	s_lshl_b64 s[40:41], s[34:35], 17
	s_add_u32 s40, s4, s40
	s_addc_u32 s41, s5, s41
	s_and_b64 s[48:49], s[8:9], exec
	s_cselect_b32 s49, s41, s47
	s_cselect_b32 s48, s40, s46
	s_add_u32 s66, s44, 0x10080
	s_addc_u32 s67, s45, 0
	s_mov_b32 m0, s59
	v_lshl_add_u64 v[64:65], s[66:67], 0, v[140:141]
	ds_read_b128 v[32:35], v163
	ds_read_b128 v[36:39], v163 offset:1024
	ds_read_b128 v[40:43], v163 offset:2048
	ds_read_b128 v[44:47], v163 offset:3072
	ds_read_b128 v[48:51], v163 offset:4096
	ds_read_b128 v[52:55], v163 offset:5120
	ds_read_b128 v[56:59], v163 offset:6144
	ds_read_b128 v[60:63], v163 offset:7168
	global_load_lds_dwordx4 v[64:65], off
	v_lshl_add_u64 v[64:65], s[66:67], 0, v[144:145]
	s_mov_b32 m0, s60
	s_nop 0
	global_load_lds_dwordx4 v[64:65], off
	s_waitcnt vmcnt(8)
	s_waitcnt lgkmcnt(0)
	s_setprio 1
	s_barrier
	s_waitcnt lgkmcnt(0)
	v_mfma_f32_16x16x32_bf16 v[64:67], v[0:3], v[32:35], 0
	v_mfma_f32_16x16x32_bf16 v[68:71], v[8:11], v[32:35], 0
	v_mfma_f32_16x16x32_bf16 v[72:75], v[0:3], v[40:43], 0
	v_mfma_f32_16x16x32_bf16 v[76:79], v[8:11], v[40:43], 0
	v_mfma_f32_16x16x32_bf16 v[80:83], v[0:3], v[48:51], 0
	v_mfma_f32_16x16x32_bf16 v[84:87], v[8:11], v[48:51], 0
	v_mfma_f32_16x16x32_bf16 v[88:91], v[0:3], v[56:59], 0
	v_mfma_f32_16x16x32_bf16 v[92:95], v[8:11], v[56:59], 0
	v_mfma_f32_16x16x32_bf16 v[64:67], v[4:7], v[36:39], v[64:67]
	v_mfma_f32_16x16x32_bf16 v[68:71], v[12:15], v[36:39], v[68:71]
	v_mfma_f32_16x16x32_bf16 v[72:75], v[4:7], v[44:47], v[72:75]
	v_mfma_f32_16x16x32_bf16 v[76:79], v[12:15], v[44:47], v[76:79]
	v_mfma_f32_16x16x32_bf16 v[80:83], v[4:7], v[52:55], v[80:83]
	v_mfma_f32_16x16x32_bf16 v[84:87], v[12:15], v[52:55], v[84:87]
	v_mfma_f32_16x16x32_bf16 v[88:91], v[4:7], v[60:63], v[88:91]
	v_mfma_f32_16x16x32_bf16 v[92:95], v[12:15], v[60:63], v[92:95]
	s_setprio 0
	s_setprio 1
	v_mfma_f32_16x16x32_bf16 v[96:99], v[16:19], v[32:35], 0
	v_mfma_f32_16x16x32_bf16 v[32:35], v[24:27], v[32:35], 0
	v_mfma_f32_16x16x32_bf16 v[96:99], v[20:23], v[36:39], v[96:99]
	v_mfma_f32_16x16x32_bf16 v[32:35], v[28:31], v[36:39], v[32:35]
	v_mfma_f32_16x16x32_bf16 v[36:39], v[16:19], v[40:43], 0
	v_mfma_f32_16x16x32_bf16 v[40:43], v[24:27], v[40:43], 0
	v_mfma_f32_16x16x32_bf16 v[36:39], v[20:23], v[44:47], v[36:39]
	v_mfma_f32_16x16x32_bf16 v[40:43], v[28:31], v[44:47], v[40:43]
	v_mfma_f32_16x16x32_bf16 v[44:47], v[16:19], v[48:51], 0
	v_mfma_f32_16x16x32_bf16 v[48:51], v[24:27], v[48:51], 0
	v_mfma_f32_16x16x32_bf16 v[44:47], v[20:23], v[52:55], v[44:47]
	v_mfma_f32_16x16x32_bf16 v[48:51], v[28:31], v[52:55], v[48:51]
	v_mfma_f32_16x16x32_bf16 v[52:55], v[16:19], v[56:59], 0
	v_mfma_f32_16x16x32_bf16 v[56:59], v[24:27], v[56:59], 0
	v_mfma_f32_16x16x32_bf16 v[52:55], v[20:23], v[60:63], v[52:55]
	v_mfma_f32_16x16x32_bf16 v[56:59], v[28:31], v[60:63], v[56:59]
	s_setprio 0
	s_barrier
	s_add_i32 s67, s57, s33
	v_lshl_add_u64 v[156:157], s[46:47], 0, v[142:143]
	s_add_i32 s35, s67, 0x2000
	v_lshl_add_u64 v[128:129], v[156:157], 0, s[20:21]
	s_mov_b32 m0, s67
	v_lshl_add_u64 v[212:213], s[46:47], 0, v[146:147]
	s_add_u32 s68, s46, 0x10100
	ds_read_b128 v[60:63], v163 offset:16384
	ds_read_b128 v[100:103], v163 offset:17408
	ds_read_b128 v[104:107], v163 offset:18432
	ds_read_b128 v[108:111], v163 offset:19456
	ds_read_b128 v[112:115], v163 offset:20480
	ds_read_b128 v[116:119], v163 offset:21504
	ds_read_b128 v[120:123], v163 offset:22528
	ds_read_b128 v[124:127], v163 offset:23552
	global_load_lds_dwordx4 v[128:129], off
	v_lshl_add_u64 v[128:129], v[212:213], 0, s[20:21]
	s_mov_b32 m0, s35
	s_addc_u32 s69, s47, 0
	s_add_i32 s37, s58, s33
	global_load_lds_dwordx4 v[128:129], off
	v_lshl_add_u64 v[128:129], s[68:69], 0, v[142:143]
	s_mov_b32 m0, s37
	s_add_i32 s66, s37, 0x2000
	global_load_lds_dwordx4 v[128:129], off
	v_lshl_add_u64 v[128:129], s[68:69], 0, v[146:147]
	s_mov_b32 m0, s66
	v_lshl_add_u64 v[214:215], s[44:45], 0, v[140:141]
	global_load_lds_dwordx4 v[128:129], off
	v_lshl_add_u64 v[128:129], v[214:215], 0, s[20:21]
	s_mov_b32 m0, s43
	v_lshl_add_u64 v[216:217], s[44:45], 0, v[144:145]
	global_load_lds_dwordx4 v[128:129], off
	v_lshl_add_u64 v[128:129], v[216:217], 0, s[20:21]
	s_mov_b32 m0, s52
	s_nop 0
	global_load_lds_dwordx4 v[128:129], off
	s_waitcnt vmcnt(8)
	s_waitcnt lgkmcnt(0)
	s_setprio 1
	s_barrier
	s_waitcnt lgkmcnt(0)
	v_mfma_f32_16x16x32_bf16 v[128:131], v[0:3], v[60:63], 0
	v_mfma_f32_16x16x32_bf16 v[136:139], v[0:3], v[104:107], 0
	v_mfma_f32_16x16x32_bf16 v[164:167], v[0:3], v[112:115], 0
	v_mfma_f32_16x16x32_bf16 v[0:3], v[0:3], v[120:123], 0
	v_mfma_f32_16x16x32_bf16 v[128:131], v[4:7], v[100:103], v[128:131]
	v_mfma_f32_16x16x32_bf16 v[136:139], v[4:7], v[108:111], v[136:139]
	v_mfma_f32_16x16x32_bf16 v[164:167], v[4:7], v[116:119], v[164:167]
	v_mfma_f32_16x16x32_bf16 v[0:3], v[4:7], v[124:127], v[0:3]
	v_mfma_f32_16x16x32_bf16 v[4:7], v[8:11], v[120:123], 0
	v_mfma_f32_16x16x32_bf16 v[132:135], v[8:11], v[60:63], 0
	v_mfma_f32_16x16x32_bf16 v[152:155], v[8:11], v[104:107], 0
	v_mfma_f32_16x16x32_bf16 v[168:171], v[8:11], v[112:115], 0
	v_mfma_f32_16x16x32_bf16 v[4:7], v[12:15], v[124:127], v[4:7]
	v_mfma_f32_16x16x32_bf16 v[132:135], v[12:15], v[100:103], v[132:135]
	v_mfma_f32_16x16x32_bf16 v[152:155], v[12:15], v[108:111], v[152:155]
	v_mfma_f32_16x16x32_bf16 v[168:171], v[12:15], v[116:119], v[168:171]
	s_setprio 0
	s_setprio 1
	v_mfma_f32_16x16x32_bf16 v[8:11], v[16:19], v[60:63], 0
	v_mfma_f32_16x16x32_bf16 v[12:15], v[24:27], v[60:63], 0
	v_mfma_f32_16x16x32_bf16 v[8:11], v[20:23], v[100:103], v[8:11]
	v_mfma_f32_16x16x32_bf16 v[12:15], v[28:31], v[100:103], v[12:15]
	v_mfma_f32_16x16x32_bf16 v[60:63], v[16:19], v[104:107], 0
	v_mfma_f32_16x16x32_bf16 v[100:103], v[24:27], v[104:107], 0
	v_mfma_f32_16x16x32_bf16 v[104:107], v[16:19], v[112:115], 0
	v_mfma_f32_16x16x32_bf16 v[16:19], v[16:19], v[120:123], 0
	v_mfma_f32_16x16x32_bf16 v[60:63], v[20:23], v[108:111], v[60:63]
	v_mfma_f32_16x16x32_bf16 v[100:103], v[28:31], v[108:111], v[100:103]
	v_mfma_f32_16x16x32_bf16 v[104:107], v[20:23], v[116:119], v[104:107]
	v_mfma_f32_16x16x32_bf16 v[108:111], v[24:27], v[112:115], 0
	v_mfma_f32_16x16x32_bf16 v[16:19], v[20:23], v[124:127], v[16:19]
	v_mfma_f32_16x16x32_bf16 v[20:23], v[24:27], v[120:123], 0
	v_mfma_f32_16x16x32_bf16 v[108:111], v[28:31], v[116:119], v[108:111]
	v_mfma_f32_16x16x32_bf16 v[20:23], v[28:31], v[124:127], v[20:23]
	s_setprio 0
	s_barrier
	s_add_i32 s70, 0, 0x18000
	s_add_i32 s72, 0, 0x1c000
	v_add_u32_e32 v224, s70, v159
	v_add_u32_e32 v228, s72, v159
	ds_read_b128 v[24:27], v224
	ds_read_b128 v[28:31], v224 offset:1024
	ds_read_b128 v[112:115], v224 offset:2048
	ds_read_b128 v[116:119], v224 offset:3072
	ds_read_b128 v[120:123], v228
	ds_read_b128 v[124:127], v228 offset:1024
	ds_read_b128 v[172:175], v228 offset:2048
	ds_read_b128 v[176:179], v228 offset:3072
	s_add_u32 s68, s44, 0x10100
	s_addc_u32 s69, s45, 0
	s_mov_b32 m0, s53
	v_lshl_add_u64 v[218:219], s[68:69], 0, v[140:141]
	ds_read_b128 v[180:183], v163 offset:32768
	ds_read_b128 v[184:187], v163 offset:33792
	ds_read_b128 v[188:191], v163 offset:34816
	ds_read_b128 v[192:195], v163 offset:35840
	ds_read_b128 v[196:199], v163 offset:36864
	ds_read_b128 v[200:203], v163 offset:37888
	ds_read_b128 v[204:207], v163 offset:38912
	ds_read_b128 v[208:211], v163 offset:39936
	global_load_lds_dwordx4 v[218:219], off
	v_lshl_add_u64 v[218:219], s[68:69], 0, v[144:145]
	s_mov_b32 m0, s54
	s_nop 0
	global_load_lds_dwordx4 v[218:219], off
	s_waitcnt vmcnt(8)
	s_waitcnt lgkmcnt(0)
	s_setprio 1
	s_barrier
	s_waitcnt lgkmcnt(0)
	v_mfma_f32_16x16x32_bf16 v[64:67], v[24:27], v[180:183], v[64:67]
	v_mfma_f32_16x16x32_bf16 v[68:71], v[112:115], v[180:183], v[68:71]
	v_mfma_f32_16x16x32_bf16 v[72:75], v[24:27], v[188:191], v[72:75]
	v_mfma_f32_16x16x32_bf16 v[76:79], v[112:115], v[188:191], v[76:79]
	v_mfma_f32_16x16x32_bf16 v[80:83], v[24:27], v[196:199], v[80:83]
	v_mfma_f32_16x16x32_bf16 v[84:87], v[112:115], v[196:199], v[84:87]
	v_mfma_f32_16x16x32_bf16 v[88:91], v[24:27], v[204:207], v[88:91]
	v_mfma_f32_16x16x32_bf16 v[92:95], v[112:115], v[204:207], v[92:95]
	v_mfma_f32_16x16x32_bf16 v[64:67], v[28:31], v[184:187], v[64:67]
	v_mfma_f32_16x16x32_bf16 v[68:71], v[116:119], v[184:187], v[68:71]
	v_mfma_f32_16x16x32_bf16 v[72:75], v[28:31], v[192:195], v[72:75]
	v_mfma_f32_16x16x32_bf16 v[76:79], v[116:119], v[192:195], v[76:79]
	v_mfma_f32_16x16x32_bf16 v[80:83], v[28:31], v[200:203], v[80:83]
	v_mfma_f32_16x16x32_bf16 v[84:87], v[116:119], v[200:203], v[84:87]
	v_mfma_f32_16x16x32_bf16 v[88:91], v[28:31], v[208:211], v[88:91]
	v_mfma_f32_16x16x32_bf16 v[92:95], v[116:119], v[208:211], v[92:95]
	s_setprio 0
	s_setprio 1
	v_mfma_f32_16x16x32_bf16 v[96:99], v[120:123], v[180:183], v[96:99]
	v_mfma_f32_16x16x32_bf16 v[32:35], v[172:175], v[180:183], v[32:35]
	v_mfma_f32_16x16x32_bf16 v[36:39], v[120:123], v[188:191], v[36:39]
	v_mfma_f32_16x16x32_bf16 v[40:43], v[172:175], v[188:191], v[40:43]
	v_mfma_f32_16x16x32_bf16 v[44:47], v[120:123], v[196:199], v[44:47]
	v_mfma_f32_16x16x32_bf16 v[48:51], v[172:175], v[196:199], v[48:51]
	v_mfma_f32_16x16x32_bf16 v[52:55], v[120:123], v[204:207], v[52:55]
	v_mfma_f32_16x16x32_bf16 v[56:59], v[172:175], v[204:207], v[56:59]
	v_mfma_f32_16x16x32_bf16 v[96:99], v[124:127], v[184:187], v[96:99]
	v_mfma_f32_16x16x32_bf16 v[32:35], v[176:179], v[184:187], v[32:35]
	v_mfma_f32_16x16x32_bf16 v[36:39], v[124:127], v[192:195], v[36:39]
	v_mfma_f32_16x16x32_bf16 v[40:43], v[176:179], v[192:195], v[40:43]
	v_mfma_f32_16x16x32_bf16 v[44:47], v[124:127], v[200:203], v[44:47]
	v_mfma_f32_16x16x32_bf16 v[48:51], v[176:179], v[200:203], v[48:51]
	v_mfma_f32_16x16x32_bf16 v[52:55], v[124:127], v[208:211], v[52:55]
	v_mfma_f32_16x16x32_bf16 v[56:59], v[176:179], v[208:211], v[56:59]
	s_setprio 0
	s_barrier
	s_add_i32 s69, s70, s33
	s_add_i32 s68, s69, 0x2000
	v_lshl_add_u64 v[156:157], v[156:157], 0, s[22:23]
	s_mov_b32 m0, s69
	s_add_u32 s70, s46, 0x10180
	ds_read_b128 v[180:183], v163 offset:49152
	ds_read_b128 v[184:187], v163 offset:50176
	ds_read_b128 v[188:191], v163 offset:51200
	ds_read_b128 v[192:195], v163 offset:52224
	ds_read_b128 v[196:199], v163 offset:53248
	ds_read_b128 v[200:203], v163 offset:54272
	ds_read_b128 v[204:207], v163 offset:55296
	ds_read_b128 v[208:211], v163 offset:56320
	global_load_lds_dwordx4 v[156:157], off
	v_lshl_add_u64 v[156:157], v[212:213], 0, s[22:23]
	s_mov_b32 m0, s68
	s_addc_u32 s71, s47, 0
	s_add_i32 s46, s72, s33
	global_load_lds_dwordx4 v[156:157], off
	v_lshl_add_u64 v[156:157], s[70:71], 0, v[142:143]
	s_mov_b32 m0, s46
	s_add_i32 s47, s46, 0x2000
	global_load_lds_dwordx4 v[156:157], off
	v_lshl_add_u64 v[156:157], s[70:71], 0, v[146:147]
	s_mov_b32 m0, s47
	s_nop 0
	global_load_lds_dwordx4 v[156:157], off
	v_lshl_add_u64 v[156:157], v[214:215], 0, s[22:23]
	s_mov_b32 m0, s55
	s_nop 0
	global_load_lds_dwordx4 v[156:157], off
	v_lshl_add_u64 v[156:157], v[216:217], 0, s[22:23]
	s_mov_b32 m0, s56
	s_nop 0
	global_load_lds_dwordx4 v[156:157], off
	s_waitcnt vmcnt(8)
	s_waitcnt lgkmcnt(0)
	s_setprio 1
	s_barrier
	s_waitcnt lgkmcnt(0)
	v_mfma_f32_16x16x32_bf16 v[0:3], v[24:27], v[204:207], v[0:3]
	v_mfma_f32_16x16x32_bf16 v[4:7], v[112:115], v[204:207], v[4:7]
	v_mfma_f32_16x16x32_bf16 v[128:131], v[24:27], v[180:183], v[128:131]
	v_mfma_f32_16x16x32_bf16 v[132:135], v[112:115], v[180:183], v[132:135]
	v_mfma_f32_16x16x32_bf16 v[136:139], v[24:27], v[188:191], v[136:139]
	v_mfma_f32_16x16x32_bf16 v[152:155], v[112:115], v[188:191], v[152:155]
	v_mfma_f32_16x16x32_bf16 v[164:167], v[24:27], v[196:199], v[164:167]
	v_mfma_f32_16x16x32_bf16 v[168:171], v[112:115], v[196:199], v[168:171]
	v_mfma_f32_16x16x32_bf16 v[0:3], v[28:31], v[208:211], v[0:3]
	v_mfma_f32_16x16x32_bf16 v[4:7], v[116:119], v[208:211], v[4:7]
	v_mfma_f32_16x16x32_bf16 v[128:131], v[28:31], v[184:187], v[128:131]
	v_mfma_f32_16x16x32_bf16 v[132:135], v[116:119], v[184:187], v[132:135]
	v_mfma_f32_16x16x32_bf16 v[136:139], v[28:31], v[192:195], v[136:139]
	v_mfma_f32_16x16x32_bf16 v[152:155], v[116:119], v[192:195], v[152:155]
	v_mfma_f32_16x16x32_bf16 v[164:167], v[28:31], v[200:203], v[164:167]
	v_mfma_f32_16x16x32_bf16 v[168:171], v[116:119], v[200:203], v[168:171]
	s_setprio 0
	s_setprio 1
	v_mfma_f32_16x16x32_bf16 v[8:11], v[120:123], v[180:183], v[8:11]
	v_mfma_f32_16x16x32_bf16 v[12:15], v[172:175], v[180:183], v[12:15]
	v_mfma_f32_16x16x32_bf16 v[24:27], v[120:123], v[188:191], v[60:63]
	v_mfma_f32_16x16x32_bf16 v[28:31], v[172:175], v[188:191], v[100:103]
	v_mfma_f32_16x16x32_bf16 v[60:63], v[120:123], v[196:199], v[104:107]
	v_mfma_f32_16x16x32_bf16 v[100:103], v[172:175], v[196:199], v[108:111]
	v_mfma_f32_16x16x32_bf16 v[16:19], v[120:123], v[204:207], v[16:19]
	v_mfma_f32_16x16x32_bf16 v[20:23], v[172:175], v[204:207], v[20:23]
	v_mfma_f32_16x16x32_bf16 v[8:11], v[124:127], v[184:187], v[8:11]
	v_mfma_f32_16x16x32_bf16 v[12:15], v[176:179], v[184:187], v[12:15]
	v_mfma_f32_16x16x32_bf16 v[24:27], v[124:127], v[192:195], v[24:27]
	v_mfma_f32_16x16x32_bf16 v[28:31], v[176:179], v[192:195], v[28:31]
	v_mfma_f32_16x16x32_bf16 v[60:63], v[124:127], v[200:203], v[60:63]
	v_mfma_f32_16x16x32_bf16 v[100:103], v[176:179], v[200:203], v[100:103]
	v_mfma_f32_16x16x32_bf16 v[16:19], v[124:127], v[208:211], v[16:19]
	v_mfma_f32_16x16x32_bf16 v[20:23], v[176:179], v[208:211], v[20:23]
	s_setprio 0
	s_barrier
	ds_read_b128 v[104:107], v161
	ds_read_b128 v[108:111], v161 offset:1024
	ds_read_b128 v[112:115], v161 offset:2048
	ds_read_b128 v[116:119], v161 offset:3072
	ds_read_b128 v[120:123], v162
	ds_read_b128 v[124:127], v162 offset:1024
	ds_read_b128 v[172:175], v162 offset:2048
	ds_read_b128 v[176:179], v162 offset:3072
	s_add_u32 s44, s44, 0x10180
	s_addc_u32 s45, s45, 0
	s_mov_b32 m0, s59
	v_lshl_add_u64 v[156:157], s[44:45], 0, v[140:141]
	ds_read_b128 v[180:183], v163
	ds_read_b128 v[184:187], v163 offset:1024
	ds_read_b128 v[188:191], v163 offset:2048
	ds_read_b128 v[192:195], v163 offset:3072
	ds_read_b128 v[196:199], v163 offset:4096
	ds_read_b128 v[200:203], v163 offset:5120
	ds_read_b128 v[204:207], v163 offset:6144
	ds_read_b128 v[208:211], v163 offset:7168
	global_load_lds_dwordx4 v[156:157], off
	v_lshl_add_u64 v[156:157], s[44:45], 0, v[144:145]
	s_mov_b32 m0, s60
	s_nop 0
	global_load_lds_dwordx4 v[156:157], off
	s_waitcnt vmcnt(8)
	s_waitcnt lgkmcnt(0)
	s_setprio 1
	s_barrier
	s_waitcnt lgkmcnt(0)
	v_mfma_f32_16x16x32_bf16 v[64:67], v[104:107], v[180:183], v[64:67]
	v_mfma_f32_16x16x32_bf16 v[68:71], v[112:115], v[180:183], v[68:71]
	v_mfma_f32_16x16x32_bf16 v[72:75], v[104:107], v[188:191], v[72:75]
	v_mfma_f32_16x16x32_bf16 v[76:79], v[112:115], v[188:191], v[76:79]
	v_mfma_f32_16x16x32_bf16 v[80:83], v[104:107], v[196:199], v[80:83]
	v_mfma_f32_16x16x32_bf16 v[84:87], v[112:115], v[196:199], v[84:87]
	v_mfma_f32_16x16x32_bf16 v[88:91], v[104:107], v[204:207], v[88:91]
	v_mfma_f32_16x16x32_bf16 v[64:67], v[108:111], v[184:187], v[64:67]
	v_mfma_f32_16x16x32_bf16 v[68:71], v[116:119], v[184:187], v[68:71]
	v_mfma_f32_16x16x32_bf16 v[72:75], v[108:111], v[192:195], v[72:75]
	v_mfma_f32_16x16x32_bf16 v[76:79], v[116:119], v[192:195], v[76:79]
	v_mfma_f32_16x16x32_bf16 v[80:83], v[108:111], v[200:203], v[80:83]
	v_mfma_f32_16x16x32_bf16 v[84:87], v[116:119], v[200:203], v[84:87]
	v_mfma_f32_16x16x32_bf16 v[212:215], v[108:111], v[208:211], v[88:91]
	v_mfma_f32_16x16x32_bf16 v[88:91], v[112:115], v[204:207], v[92:95]
	v_mfma_f32_16x16x32_bf16 v[216:219], v[116:119], v[208:211], v[88:91]
	s_setprio 0
	s_setprio 1
	v_mfma_f32_16x16x32_bf16 v[32:35], v[172:175], v[180:183], v[32:35]
	v_mfma_f32_16x16x32_bf16 v[36:39], v[120:123], v[188:191], v[36:39]
	v_mfma_f32_16x16x32_bf16 v[40:43], v[172:175], v[188:191], v[40:43]
	v_mfma_f32_16x16x32_bf16 v[44:47], v[120:123], v[196:199], v[44:47]
	v_mfma_f32_16x16x32_bf16 v[48:51], v[172:175], v[196:199], v[48:51]
	v_mfma_f32_16x16x32_bf16 v[52:55], v[120:123], v[204:207], v[52:55]
	v_mfma_f32_16x16x32_bf16 v[56:59], v[172:175], v[204:207], v[56:59]
	v_mfma_f32_16x16x32_bf16 v[88:91], v[120:123], v[180:183], v[96:99]
	v_mfma_f32_16x16x32_bf16 v[32:35], v[176:179], v[184:187], v[32:35]
	v_mfma_f32_16x16x32_bf16 v[36:39], v[124:127], v[192:195], v[36:39]
	v_mfma_f32_16x16x32_bf16 v[40:43], v[176:179], v[192:195], v[40:43]
	v_mfma_f32_16x16x32_bf16 v[44:47], v[124:127], v[200:203], v[44:47]
	v_mfma_f32_16x16x32_bf16 v[48:51], v[176:179], v[200:203], v[48:51]
	v_mfma_f32_16x16x32_bf16 v[52:55], v[124:127], v[208:211], v[52:55]
	v_mfma_f32_16x16x32_bf16 v[56:59], v[176:179], v[208:211], v[56:59]
	v_mfma_f32_16x16x32_bf16 v[220:223], v[124:127], v[184:187], v[88:91]
	s_setprio 0
	s_barrier
	s_mov_b32 m0, s67
	v_lshl_add_u64 v[156:157], s[48:49], 0, v[142:143]
	s_add_u32 s44, s48, 0x10000
	ds_read_b128 v[88:91], v163 offset:16384
	ds_read_b128 v[92:95], v163 offset:17408
	ds_read_b128 v[96:99], v163 offset:18432
	ds_read_b128 v[180:183], v163 offset:19456
	ds_read_b128 v[184:187], v163 offset:20480
	ds_read_b128 v[188:191], v163 offset:21504
	ds_read_b128 v[192:195], v163 offset:22528
	ds_read_b128 v[196:199], v163 offset:23552
	global_load_lds_dwordx4 v[156:157], off
	v_lshl_add_u64 v[250:251], s[48:49], 0, v[146:147]
	s_mov_b32 m0, s35
	s_addc_u32 s45, s49, 0
	global_load_lds_dwordx4 v[250:251], off
	v_lshl_add_u64 v[200:201], s[44:45], 0, v[142:143]
	s_mov_b32 m0, s37
	v_lshl_add_u64 v[252:253], s[50:51], 0, v[140:141]
	global_load_lds_dwordx4 v[200:201], off
	v_lshl_add_u64 v[200:201], s[44:45], 0, v[146:147]
	s_mov_b32 m0, s66
	v_lshl_add_u64 v[148:149], s[50:51], 0, v[144:145]
	global_load_lds_dwordx4 v[200:201], off
	s_mov_b32 m0, s43
	s_nop 0
	global_load_lds_dwordx4 v[252:253], off
	s_mov_b32 m0, s52
	s_nop 0
	global_load_lds_dwordx4 v[148:149], off
	s_waitcnt vmcnt(8)
	s_waitcnt lgkmcnt(0)
	s_setprio 1
	s_barrier
	s_waitcnt lgkmcnt(0)
	v_mfma_f32_16x16x32_bf16 v[0:3], v[104:107], v[192:195], v[0:3]
	v_mfma_f32_16x16x32_bf16 v[4:7], v[112:115], v[192:195], v[4:7]
	v_mfma_f32_16x16x32_bf16 v[128:131], v[104:107], v[88:91], v[128:131]
	v_mfma_f32_16x16x32_bf16 v[132:135], v[112:115], v[88:91], v[132:135]
	v_mfma_f32_16x16x32_bf16 v[136:139], v[104:107], v[96:99], v[136:139]
	v_mfma_f32_16x16x32_bf16 v[152:155], v[112:115], v[96:99], v[152:155]
	v_mfma_f32_16x16x32_bf16 v[164:167], v[104:107], v[184:187], v[164:167]
	v_mfma_f32_16x16x32_bf16 v[168:171], v[112:115], v[184:187], v[168:171]
	v_mfma_f32_16x16x32_bf16 v[0:3], v[108:111], v[196:199], v[0:3]
	v_mfma_f32_16x16x32_bf16 v[4:7], v[116:119], v[196:199], v[4:7]
	v_mfma_f32_16x16x32_bf16 v[128:131], v[108:111], v[92:95], v[128:131]
	v_mfma_f32_16x16x32_bf16 v[132:135], v[116:119], v[92:95], v[132:135]
	v_mfma_f32_16x16x32_bf16 v[136:139], v[108:111], v[180:183], v[136:139]
	v_mfma_f32_16x16x32_bf16 v[152:155], v[116:119], v[180:183], v[152:155]
	v_mfma_f32_16x16x32_bf16 v[164:167], v[108:111], v[188:191], v[164:167]
	v_mfma_f32_16x16x32_bf16 v[168:171], v[116:119], v[188:191], v[168:171]
	s_setprio 0
	s_setprio 1
	v_mfma_f32_16x16x32_bf16 v[8:11], v[120:123], v[88:91], v[8:11]
	v_mfma_f32_16x16x32_bf16 v[200:203], v[124:127], v[92:95], v[8:11]
	v_mfma_f32_16x16x32_bf16 v[8:11], v[172:175], v[88:91], v[12:15]
	v_mfma_f32_16x16x32_bf16 v[204:207], v[176:179], v[92:95], v[8:11]
	v_mfma_f32_16x16x32_bf16 v[8:11], v[120:123], v[96:99], v[24:27]
	v_mfma_f32_16x16x32_bf16 v[208:211], v[124:127], v[180:183], v[8:11]
	v_mfma_f32_16x16x32_bf16 v[8:11], v[172:175], v[96:99], v[28:31]
	v_mfma_f32_16x16x32_bf16 v[28:31], v[176:179], v[180:183], v[8:11]
	v_mfma_f32_16x16x32_bf16 v[8:11], v[120:123], v[184:187], v[60:63]
	v_mfma_f32_16x16x32_bf16 v[180:183], v[124:127], v[188:191], v[8:11]
	v_mfma_f32_16x16x32_bf16 v[8:11], v[172:175], v[184:187], v[100:103]
	v_mfma_f32_16x16x32_bf16 v[184:187], v[176:179], v[188:191], v[8:11]
	v_mfma_f32_16x16x32_bf16 v[8:11], v[120:123], v[192:195], v[16:19]
	v_mfma_f32_16x16x32_bf16 v[188:191], v[124:127], v[196:199], v[8:11]
	v_mfma_f32_16x16x32_bf16 v[8:11], v[172:175], v[192:195], v[20:23]
	v_mfma_f32_16x16x32_bf16 v[172:175], v[176:179], v[196:199], v[8:11]
	s_setprio 0
	s_barrier
	s_nop 4
	ds_read_b128 v[8:11], v224
	ds_read_b128 v[12:15], v224 offset:1024
	ds_read_b128 v[20:23], v224 offset:2048
	ds_read_b128 v[176:179], v224 offset:3072
	ds_read_b128 v[192:195], v228
	ds_read_b128 v[196:199], v228 offset:1024
	ds_read_b128 v[224:227], v228 offset:2048
	ds_read_b128 v[230:233], v228 offset:3072
	s_add_u32 s44, s50, 0x10000
	s_addc_u32 s45, s51, 0
	s_mov_b32 m0, s53
	v_lshl_add_u64 v[88:89], s[44:45], 0, v[140:141]
	ds_read_b128 v[16:19], v163 offset:32768
	ds_read_b128 v[24:27], v163 offset:33792
	ds_read_b128 v[60:63], v163 offset:34816
	ds_read_b128 v[104:107], v163 offset:35840
	ds_read_b128 v[234:237], v163 offset:36864
	ds_read_b128 v[238:241], v163 offset:37888
	ds_read_b128 v[242:245], v163 offset:38912
	ds_read_b128 v[246:249], v163 offset:39936
	global_load_lds_dwordx4 v[88:89], off
	v_lshl_add_u64 v[88:89], s[44:45], 0, v[144:145]
	s_mov_b32 m0, s54
	s_nop 0
	global_load_lds_dwordx4 v[88:89], off
	s_waitcnt vmcnt(8)
	s_waitcnt lgkmcnt(0)
	s_setprio 1
	s_barrier
	s_waitcnt lgkmcnt(0)
	v_mfma_f32_16x16x32_bf16 v[64:67], v[8:11], v[16:19], v[64:67]
	v_mfma_f32_16x16x32_bf16 v[112:115], v[12:15], v[24:27], v[64:67]
	v_mfma_f32_16x16x32_bf16 v[64:67], v[20:23], v[16:19], v[68:71]
	v_mfma_f32_16x16x32_bf16 v[116:119], v[176:179], v[24:27], v[64:67]
	v_mfma_f32_16x16x32_bf16 v[64:67], v[8:11], v[60:63], v[72:75]
	v_mfma_f32_16x16x32_bf16 v[96:99], v[12:15], v[104:107], v[64:67]
	v_mfma_f32_16x16x32_bf16 v[64:67], v[20:23], v[60:63], v[76:79]
	v_mfma_f32_16x16x32_bf16 v[100:103], v[176:179], v[104:107], v[64:67]
	v_mfma_f32_16x16x32_bf16 v[64:67], v[8:11], v[234:237], v[80:83]
	v_mfma_f32_16x16x32_bf16 v[92:95], v[12:15], v[238:241], v[64:67]
	v_mfma_f32_16x16x32_bf16 v[64:67], v[20:23], v[234:237], v[84:87]
	v_mfma_f32_16x16x32_bf16 v[88:91], v[176:179], v[238:241], v[64:67]
	v_mfma_f32_16x16x32_bf16 v[64:67], v[8:11], v[242:245], v[212:215]
	v_mfma_f32_16x16x32_bf16 v[76:79], v[12:15], v[246:249], v[64:67]
	v_mfma_f32_16x16x32_bf16 v[64:67], v[20:23], v[242:245], v[216:219]
	v_mfma_f32_16x16x32_bf16 v[72:75], v[176:179], v[246:249], v[64:67]
	s_setprio 0
	s_setprio 1
	v_mfma_f32_16x16x32_bf16 v[64:67], v[192:195], v[16:19], v[220:223]
	v_mfma_f32_16x16x32_bf16 v[16:19], v[224:227], v[16:19], v[32:35]
	v_mfma_f32_16x16x32_bf16 v[124:127], v[230:233], v[24:27], v[16:19]
	v_mfma_f32_16x16x32_bf16 v[16:19], v[192:195], v[60:63], v[36:39]
	v_mfma_f32_16x16x32_bf16 v[108:111], v[196:199], v[104:107], v[16:19]
	v_mfma_f32_16x16x32_bf16 v[16:19], v[224:227], v[60:63], v[40:43]
	v_mfma_f32_16x16x32_bf16 v[104:107], v[230:233], v[104:107], v[16:19]
	v_mfma_f32_16x16x32_bf16 v[16:19], v[192:195], v[234:237], v[44:47]
	v_mfma_f32_16x16x32_bf16 v[84:87], v[196:199], v[238:241], v[16:19]
	v_mfma_f32_16x16x32_bf16 v[16:19], v[224:227], v[234:237], v[48:51]
	v_mfma_f32_16x16x32_bf16 v[80:83], v[230:233], v[238:241], v[16:19]
	v_mfma_f32_16x16x32_bf16 v[16:19], v[192:195], v[242:245], v[52:55]
	v_mfma_f32_16x16x32_bf16 v[68:71], v[196:199], v[246:249], v[16:19]
	v_mfma_f32_16x16x32_bf16 v[16:19], v[224:227], v[242:245], v[56:59]
	v_mfma_f32_16x16x32_bf16 v[120:123], v[196:199], v[24:27], v[64:67]
	v_mfma_f32_16x16x32_bf16 v[64:67], v[230:233], v[246:249], v[16:19]
	s_setprio 0
	s_barrier
	s_mov_b32 m0, s69
	s_nop 2
	v_lshl_add_u64 v[16:17], v[156:157], 0, s[14:15]
	s_add_u32 s44, s48, 0x10080
	ds_read_b128 v[36:39], v163 offset:49152
	ds_read_b128 v[40:43], v163 offset:50176
	ds_read_b128 v[212:215], v163 offset:51200
	ds_read_b128 v[216:219], v163 offset:52224
	ds_read_b128 v[220:223], v163 offset:53248
	ds_read_b128 v[234:237], v163 offset:54272
	ds_read_b128 v[238:241], v163 offset:55296
	ds_read_b128 v[242:245], v163 offset:56320
	global_load_lds_dwordx4 v[16:17], off
	v_lshl_add_u64 v[16:17], v[250:251], 0, s[14:15]
	s_mov_b32 m0, s68
	s_addc_u32 s45, s49, 0
	global_load_lds_dwordx4 v[16:17], off
	v_lshl_add_u64 v[16:17], s[44:45], 0, v[142:143]
	s_mov_b32 m0, s46
	s_nop 0
	global_load_lds_dwordx4 v[16:17], off
	v_lshl_add_u64 v[16:17], s[44:45], 0, v[146:147]
	s_mov_b32 m0, s47
	s_nop 0
	global_load_lds_dwordx4 v[16:17], off
	v_lshl_add_u64 v[16:17], v[252:253], 0, s[14:15]
	s_mov_b32 m0, s55
	s_nop 0
	global_load_lds_dwordx4 v[16:17], off
	v_lshl_add_u64 v[16:17], v[148:149], 0, s[14:15]
	s_mov_b32 m0, s56
	s_nop 0
	global_load_lds_dwordx4 v[16:17], off
	s_waitcnt vmcnt(8)
	s_waitcnt lgkmcnt(0)
	s_setprio 1
	s_barrier
	s_waitcnt lgkmcnt(0)
	v_mfma_f32_16x16x32_bf16 v[16:19], v[8:11], v[36:39], v[128:131]
	v_mfma_f32_16x16x32_bf16 v[60:63], v[12:15], v[40:43], v[16:19]
	v_mfma_f32_16x16x32_bf16 v[16:19], v[20:23], v[36:39], v[132:135]
	v_mfma_f32_16x16x32_bf16 v[56:59], v[176:179], v[40:43], v[16:19]
	v_mfma_f32_16x16x32_bf16 v[16:19], v[8:11], v[212:215], v[136:139]
	v_mfma_f32_16x16x32_bf16 v[44:47], v[12:15], v[216:219], v[16:19]
	v_mfma_f32_16x16x32_bf16 v[16:19], v[20:23], v[212:215], v[152:155]
	v_mfma_f32_16x16x32_bf16 v[32:35], v[176:179], v[216:219], v[16:19]
	v_mfma_f32_16x16x32_bf16 v[16:19], v[8:11], v[220:223], v[164:167]
	v_mfma_f32_16x16x32_bf16 v[0:3], v[8:11], v[238:241], v[0:3]
	v_mfma_f32_16x16x32_bf16 v[24:27], v[12:15], v[234:237], v[16:19]
	v_mfma_f32_16x16x32_bf16 v[16:19], v[20:23], v[220:223], v[168:171]
	v_mfma_f32_16x16x32_bf16 v[12:15], v[12:15], v[242:245], v[0:3]
	v_mfma_f32_16x16x32_bf16 v[0:3], v[20:23], v[238:241], v[4:7]
	v_mfma_f32_16x16x32_bf16 v[16:19], v[176:179], v[234:237], v[16:19]
	v_mfma_f32_16x16x32_bf16 v[8:11], v[176:179], v[242:245], v[0:3]
	s_setprio 0
	s_setprio 1
	v_mfma_f32_16x16x32_bf16 v[0:3], v[192:195], v[36:39], v[200:203]
	v_mfma_f32_16x16x32_bf16 v[52:55], v[196:199], v[40:43], v[0:3]
	v_mfma_f32_16x16x32_bf16 v[0:3], v[224:227], v[36:39], v[204:207]
	v_mfma_f32_16x16x32_bf16 v[48:51], v[230:233], v[40:43], v[0:3]
	v_mfma_f32_16x16x32_bf16 v[0:3], v[192:195], v[212:215], v[208:211]
	v_mfma_f32_16x16x32_bf16 v[40:43], v[196:199], v[216:219], v[0:3]
	v_mfma_f32_16x16x32_bf16 v[0:3], v[224:227], v[212:215], v[28:31]
	v_mfma_f32_16x16x32_bf16 v[36:39], v[230:233], v[216:219], v[0:3]
	v_mfma_f32_16x16x32_bf16 v[0:3], v[192:195], v[220:223], v[180:183]
	v_mfma_f32_16x16x32_bf16 v[28:31], v[196:199], v[234:237], v[0:3]
	v_mfma_f32_16x16x32_bf16 v[0:3], v[224:227], v[220:223], v[184:187]
	v_mfma_f32_16x16x32_bf16 v[20:23], v[230:233], v[234:237], v[0:3]
	v_mfma_f32_16x16x32_bf16 v[0:3], v[192:195], v[238:241], v[188:191]
	v_mfma_f32_16x16x32_bf16 v[4:7], v[196:199], v[242:245], v[0:3]
	v_mfma_f32_16x16x32_bf16 v[0:3], v[224:227], v[238:241], v[172:175]
	v_mfma_f32_16x16x32_bf16 v[0:3], v[230:233], v[242:245], v[0:3]
	s_setprio 0
	s_barrier
	s_andn2_b64 vcc, exec, s[16:17]
	s_cbranch_vccnz .LBB0_1136
	s_barrier

.LBB0_1281:
	ds_read_b128 v[152:155], v149
	ds_read_b128 v[156:159], v149 offset:1024
	ds_read_b128 v[160:163], v149 offset:2048
	ds_read_b128 v[164:167], v149 offset:3072
	ds_read_b128 v[168:171], v150
	ds_read_b128 v[172:175], v150 offset:1024
	ds_read_b128 v[176:179], v150 offset:2048
	ds_read_b128 v[180:183], v150 offset:3072
	s_add_u32 s28, s26, 0xfffc0080
	s_addc_u32 s29, s27, -1
	s_cmp_eq_u32 s51, 12
	s_cselect_b32 s31, s21, s29
	s_cselect_b32 s30, s47, s28
	s_cselect_b32 s29, s19, s50
	s_cselect_b32 s28, s48, s49
	v_lshl_add_u64 v[144:145], s[26:27], 0, v[138:139]
	s_add_i32 m0, s34, 0xc000
	ds_read_b128 v[184:187], v151
	ds_read_b128 v[188:191], v151 offset:1024
	ds_read_b128 v[192:195], v151 offset:2048
	ds_read_b128 v[196:199], v151 offset:3072
	ds_read_b128 v[200:203], v151 offset:4096
	ds_read_b128 v[204:207], v151 offset:5120
	ds_read_b128 v[208:211], v151 offset:6144
	ds_read_b128 v[212:215], v151 offset:7168
	global_load_lds_dwordx4 v[144:145], off
	v_lshl_add_u64 v[144:145], s[26:27], 0, v[136:137]
	s_add_i32 m0, s34, 0xe000
	s_nop 0
	global_load_lds_dwordx4 v[144:145], off
	s_waitcnt vmcnt(8)
	s_waitcnt lgkmcnt(0)
	s_setprio 1
	s_barrier
	s_waitcnt lgkmcnt(0)
	v_mfma_f32_16x16x32_bf16 v[124:127], v[152:155], v[184:187], v[124:127]
	v_mfma_f32_16x16x32_bf16 v[120:123], v[160:163], v[184:187], v[120:123]
	v_mfma_f32_16x16x32_bf16 v[108:111], v[152:155], v[192:195], v[108:111]
	v_mfma_f32_16x16x32_bf16 v[104:107], v[160:163], v[192:195], v[104:107]
	v_mfma_f32_16x16x32_bf16 v[92:95], v[152:155], v[200:203], v[92:95]
	v_mfma_f32_16x16x32_bf16 v[88:91], v[160:163], v[200:203], v[88:91]
	v_mfma_f32_16x16x32_bf16 v[76:79], v[152:155], v[208:211], v[76:79]
	v_mfma_f32_16x16x32_bf16 v[72:75], v[160:163], v[208:211], v[72:75]
	v_mfma_f32_16x16x32_bf16 v[124:127], v[156:159], v[188:191], v[124:127]
	v_mfma_f32_16x16x32_bf16 v[120:123], v[164:167], v[188:191], v[120:123]
	v_mfma_f32_16x16x32_bf16 v[108:111], v[156:159], v[196:199], v[108:111]
	v_mfma_f32_16x16x32_bf16 v[104:107], v[164:167], v[196:199], v[104:107]
	v_mfma_f32_16x16x32_bf16 v[92:95], v[156:159], v[204:207], v[92:95]
	v_mfma_f32_16x16x32_bf16 v[88:91], v[164:167], v[204:207], v[88:91]
	v_mfma_f32_16x16x32_bf16 v[76:79], v[156:159], v[212:215], v[76:79]
	v_mfma_f32_16x16x32_bf16 v[72:75], v[164:167], v[212:215], v[72:75]
	s_setprio 0
	s_setprio 1
	v_mfma_f32_16x16x32_bf16 v[116:119], v[168:171], v[184:187], v[116:119]
	v_mfma_f32_16x16x32_bf16 v[112:115], v[176:179], v[184:187], v[112:115]
	v_mfma_f32_16x16x32_bf16 v[100:103], v[168:171], v[192:195], v[100:103]
	v_mfma_f32_16x16x32_bf16 v[96:99], v[176:179], v[192:195], v[96:99]
	v_mfma_f32_16x16x32_bf16 v[84:87], v[168:171], v[200:203], v[84:87]
	v_mfma_f32_16x16x32_bf16 v[80:83], v[176:179], v[200:203], v[80:83]
	v_mfma_f32_16x16x32_bf16 v[68:71], v[168:171], v[208:211], v[68:71]
	v_mfma_f32_16x16x32_bf16 v[64:67], v[176:179], v[208:211], v[64:67]
	v_mfma_f32_16x16x32_bf16 v[116:119], v[172:175], v[188:191], v[116:119]
	v_mfma_f32_16x16x32_bf16 v[112:115], v[180:183], v[188:191], v[112:115]
	v_mfma_f32_16x16x32_bf16 v[100:103], v[172:175], v[196:199], v[100:103]
	v_mfma_f32_16x16x32_bf16 v[96:99], v[180:183], v[196:199], v[96:99]
	v_mfma_f32_16x16x32_bf16 v[84:87], v[172:175], v[204:207], v[84:87]
	v_mfma_f32_16x16x32_bf16 v[80:83], v[180:183], v[204:207], v[80:83]
	v_mfma_f32_16x16x32_bf16 v[68:71], v[172:175], v[212:215], v[68:71]
	v_mfma_f32_16x16x32_bf16 v[64:67], v[180:183], v[212:215], v[64:67]
	s_setprio 0
	s_barrier
	s_add_i32 s52, s42, s33
	v_lshl_add_u64 v[144:145], s[28:29], 0, v[132:133]
	s_mov_b32 m0, s52
	ds_read_b128 v[184:187], v151 offset:16384
	ds_read_b128 v[188:191], v151 offset:17408
	ds_read_b128 v[192:195], v151 offset:18432
	ds_read_b128 v[196:199], v151 offset:19456
	ds_read_b128 v[200:203], v151 offset:20480
	ds_read_b128 v[204:207], v151 offset:21504
	ds_read_b128 v[208:211], v151 offset:22528
	ds_read_b128 v[212:215], v151 offset:23552
	global_load_lds_dwordx4 v[144:145], off
	s_add_i32 m0, s52, 0x2000
	s_add_u32 s52, s28, 0x40000
	v_lshl_add_u64 v[216:217], s[28:29], 0, v[128:129]
	s_addc_u32 s53, s29, 0
	s_add_i32 s54, s43, s33
	global_load_lds_dwordx4 v[216:217], off
	v_lshl_add_u64 v[218:219], s[52:53], 0, v[132:133]
	s_mov_b32 m0, s54
	v_lshl_add_u64 v[220:221], s[30:31], 0, v[130:131]
	global_load_lds_dwordx4 v[218:219], off
	v_lshl_add_u64 v[218:219], s[52:53], 0, v[128:129]
	s_add_i32 m0, s54, 0x2000
	s_nop 0
	global_load_lds_dwordx4 v[218:219], off
	v_lshl_add_u64 v[218:219], s[30:31], 0, v[134:135]
	s_mov_b32 m0, s34
	s_nop 0
	global_load_lds_dwordx4 v[218:219], off
	s_mov_b32 m0, s35
	s_nop 0
	global_load_lds_dwordx4 v[220:221], off
	s_waitcnt vmcnt(8)
	s_waitcnt lgkmcnt(0)
	s_setprio 1
	s_barrier
	s_waitcnt lgkmcnt(0)
	v_mfma_f32_16x16x32_bf16 v[60:63], v[152:155], v[184:187], v[60:63]
	v_mfma_f32_16x16x32_bf16 v[56:59], v[160:163], v[184:187], v[56:59]
	v_mfma_f32_16x16x32_bf16 v[44:47], v[152:155], v[192:195], v[44:47]
	v_mfma_f32_16x16x32_bf16 v[40:43], v[160:163], v[192:195], v[40:43]
	v_mfma_f32_16x16x32_bf16 v[28:31], v[152:155], v[200:203], v[28:31]
	v_mfma_f32_16x16x32_bf16 v[24:27], v[160:163], v[200:203], v[24:27]
	v_mfma_f32_16x16x32_bf16 v[12:15], v[152:155], v[208:211], v[12:15]
	v_mfma_f32_16x16x32_bf16 v[8:11], v[160:163], v[208:211], v[8:11]
	v_mfma_f32_16x16x32_bf16 v[60:63], v[156:159], v[188:191], v[60:63]
	v_mfma_f32_16x16x32_bf16 v[56:59], v[164:167], v[188:191], v[56:59]
	v_mfma_f32_16x16x32_bf16 v[44:47], v[156:159], v[196:199], v[44:47]
	v_mfma_f32_16x16x32_bf16 v[40:43], v[164:167], v[196:199], v[40:43]
	v_mfma_f32_16x16x32_bf16 v[28:31], v[156:159], v[204:207], v[28:31]
	v_mfma_f32_16x16x32_bf16 v[24:27], v[164:167], v[204:207], v[24:27]
	v_mfma_f32_16x16x32_bf16 v[12:15], v[156:159], v[212:215], v[12:15]
	v_mfma_f32_16x16x32_bf16 v[8:11], v[164:167], v[212:215], v[8:11]
	s_setprio 0
	s_setprio 1
	v_mfma_f32_16x16x32_bf16 v[52:55], v[168:171], v[184:187], v[52:55]
	v_mfma_f32_16x16x32_bf16 v[48:51], v[176:179], v[184:187], v[48:51]
	v_mfma_f32_16x16x32_bf16 v[36:39], v[168:171], v[192:195], v[36:39]
	v_mfma_f32_16x16x32_bf16 v[32:35], v[176:179], v[192:195], v[32:35]
	v_mfma_f32_16x16x32_bf16 v[20:23], v[168:171], v[200:203], v[20:23]
	v_mfma_f32_16x16x32_bf16 v[16:19], v[176:179], v[200:203], v[16:19]
	v_mfma_f32_16x16x32_bf16 v[4:7], v[168:171], v[208:211], v[4:7]
	v_mfma_f32_16x16x32_bf16 v[0:3], v[176:179], v[208:211], v[0:3]
	v_mfma_f32_16x16x32_bf16 v[52:55], v[172:175], v[188:191], v[52:55]
	v_mfma_f32_16x16x32_bf16 v[48:51], v[180:183], v[188:191], v[48:51]
	v_mfma_f32_16x16x32_bf16 v[36:39], v[172:175], v[196:199], v[36:39]
	v_mfma_f32_16x16x32_bf16 v[32:35], v[180:183], v[196:199], v[32:35]
	v_mfma_f32_16x16x32_bf16 v[20:23], v[172:175], v[204:207], v[20:23]
	v_mfma_f32_16x16x32_bf16 v[16:19], v[180:183], v[204:207], v[16:19]
	v_mfma_f32_16x16x32_bf16 v[4:7], v[172:175], v[212:215], v[4:7]
	v_mfma_f32_16x16x32_bf16 v[0:3], v[180:183], v[212:215], v[0:3]
	s_setprio 0
	s_barrier
	s_add_i32 s52, 0, 0x18000
	s_add_i32 s53, 0, 0x1c000
	v_add_u32_e32 v164, s52, v147
	v_add_u32_e32 v180, s53, v147
	ds_read_b128 v[152:155], v164
	ds_read_b128 v[156:159], v164 offset:1024
	ds_read_b128 v[160:163], v164 offset:2048
	ds_read_b128 v[164:167], v164 offset:3072
	ds_read_b128 v[168:171], v180
	ds_read_b128 v[172:175], v180 offset:1024
	ds_read_b128 v[176:179], v180 offset:2048
	ds_read_b128 v[180:183], v180 offset:3072
	s_add_u32 s30, s30, 0x40000
	s_addc_u32 s31, s31, 0
	s_mov_b32 m0, s36
	v_lshl_add_u64 v[222:223], s[30:31], 0, v[134:135]
	ds_read_b128 v[184:187], v151 offset:32768
	ds_read_b128 v[188:191], v151 offset:33792
	ds_read_b128 v[192:195], v151 offset:34816
	ds_read_b128 v[196:199], v151 offset:35840
	ds_read_b128 v[200:203], v151 offset:36864
	ds_read_b128 v[204:207], v151 offset:37888
	ds_read_b128 v[208:211], v151 offset:38912
	ds_read_b128 v[212:215], v151 offset:39936
	global_load_lds_dwordx4 v[222:223], off
	v_lshl_add_u64 v[222:223], s[30:31], 0, v[130:131]
	s_mov_b32 m0, s37
	s_nop 0
	global_load_lds_dwordx4 v[222:223], off
	s_waitcnt vmcnt(8)
	s_waitcnt lgkmcnt(0)
	s_setprio 1
	s_barrier
	s_waitcnt lgkmcnt(0)
	v_mfma_f32_16x16x32_bf16 v[124:127], v[152:155], v[184:187], v[124:127]
	v_mfma_f32_16x16x32_bf16 v[120:123], v[160:163], v[184:187], v[120:123]
	v_mfma_f32_16x16x32_bf16 v[108:111], v[152:155], v[192:195], v[108:111]
	v_mfma_f32_16x16x32_bf16 v[104:107], v[160:163], v[192:195], v[104:107]
	v_mfma_f32_16x16x32_bf16 v[92:95], v[152:155], v[200:203], v[92:95]
	v_mfma_f32_16x16x32_bf16 v[88:91], v[160:163], v[200:203], v[88:91]
	v_mfma_f32_16x16x32_bf16 v[76:79], v[152:155], v[208:211], v[76:79]
	v_mfma_f32_16x16x32_bf16 v[72:75], v[160:163], v[208:211], v[72:75]
	v_mfma_f32_16x16x32_bf16 v[124:127], v[156:159], v[188:191], v[124:127]
	v_mfma_f32_16x16x32_bf16 v[120:123], v[164:167], v[188:191], v[120:123]
	v_mfma_f32_16x16x32_bf16 v[108:111], v[156:159], v[196:199], v[108:111]
	v_mfma_f32_16x16x32_bf16 v[104:107], v[164:167], v[196:199], v[104:107]
	v_mfma_f32_16x16x32_bf16 v[92:95], v[156:159], v[204:207], v[92:95]
	v_mfma_f32_16x16x32_bf16 v[88:91], v[164:167], v[204:207], v[88:91]
	v_mfma_f32_16x16x32_bf16 v[76:79], v[156:159], v[212:215], v[76:79]
	v_mfma_f32_16x16x32_bf16 v[72:75], v[164:167], v[212:215], v[72:75]
	s_setprio 0
	s_setprio 1
	v_mfma_f32_16x16x32_bf16 v[116:119], v[168:171], v[184:187], v[116:119]
	v_mfma_f32_16x16x32_bf16 v[112:115], v[176:179], v[184:187], v[112:115]
	v_mfma_f32_16x16x32_bf16 v[100:103], v[168:171], v[192:195], v[100:103]
	v_mfma_f32_16x16x32_bf16 v[96:99], v[176:179], v[192:195], v[96:99]
	v_mfma_f32_16x16x32_bf16 v[84:87], v[168:171], v[200:203], v[84:87]
	v_mfma_f32_16x16x32_bf16 v[80:83], v[176:179], v[200:203], v[80:83]
	v_mfma_f32_16x16x32_bf16 v[68:71], v[168:171], v[208:211], v[68:71]
	v_mfma_f32_16x16x32_bf16 v[64:67], v[176:179], v[208:211], v[64:67]
	v_mfma_f32_16x16x32_bf16 v[116:119], v[172:175], v[188:191], v[116:119]
	v_mfma_f32_16x16x32_bf16 v[112:115], v[180:183], v[188:191], v[112:115]
	v_mfma_f32_16x16x32_bf16 v[100:103], v[172:175], v[196:199], v[100:103]
	v_mfma_f32_16x16x32_bf16 v[96:99], v[180:183], v[196:199], v[96:99]
	v_mfma_f32_16x16x32_bf16 v[84:87], v[172:175], v[204:207], v[84:87]
	v_mfma_f32_16x16x32_bf16 v[80:83], v[180:183], v[204:207], v[80:83]
	v_mfma_f32_16x16x32_bf16 v[68:71], v[172:175], v[212:215], v[68:71]
	v_mfma_f32_16x16x32_bf16 v[64:67], v[180:183], v[212:215], v[64:67]
	s_setprio 0
	s_barrier
	s_add_i32 s30, s52, s33
	v_lshl_add_u64 v[144:145], v[144:145], 0, s[14:15]
	s_mov_b32 m0, s30
	ds_read_b128 v[184:187], v151 offset:49152
	ds_read_b128 v[188:191], v151 offset:50176
	ds_read_b128 v[192:195], v151 offset:51200
	ds_read_b128 v[196:199], v151 offset:52224
	ds_read_b128 v[200:203], v151 offset:53248
	ds_read_b128 v[204:207], v151 offset:54272
	ds_read_b128 v[208:211], v151 offset:55296
	ds_read_b128 v[212:215], v151 offset:56320
	global_load_lds_dwordx4 v[144:145], off
	s_add_i32 m0, s30, 0x2000
	s_add_u32 s28, s28, 0x40080
	v_lshl_add_u64 v[144:145], v[216:217], 0, s[14:15]
	s_addc_u32 s29, s29, 0
	s_add_i32 s30, s53, s33
	global_load_lds_dwordx4 v[144:145], off
	v_lshl_add_u64 v[144:145], s[28:29], 0, v[132:133]
	s_mov_b32 m0, s30
	s_nop 0
	global_load_lds_dwordx4 v[144:145], off
	v_lshl_add_u64 v[144:145], s[28:29], 0, v[128:129]
	s_add_i32 m0, s30, 0x2000
	s_nop 0
	global_load_lds_dwordx4 v[144:145], off
	v_lshl_add_u64 v[144:145], v[218:219], 0, s[14:15]
	s_mov_b32 m0, s39
	s_nop 0
	global_load_lds_dwordx4 v[144:145], off
	v_lshl_add_u64 v[144:145], v[220:221], 0, s[14:15]
	s_mov_b32 m0, s40
	s_nop 0
	global_load_lds_dwordx4 v[144:145], off
	s_waitcnt vmcnt(8)
	s_waitcnt lgkmcnt(0)
	s_setprio 1
	s_barrier
	s_waitcnt lgkmcnt(0)
	v_mfma_f32_16x16x32_bf16 v[60:63], v[152:155], v[184:187], v[60:63]
	v_mfma_f32_16x16x32_bf16 v[56:59], v[160:163], v[184:187], v[56:59]
	v_mfma_f32_16x16x32_bf16 v[44:47], v[152:155], v[192:195], v[44:47]
	v_mfma_f32_16x16x32_bf16 v[40:43], v[160:163], v[192:195], v[40:43]
	v_mfma_f32_16x16x32_bf16 v[28:31], v[152:155], v[200:203], v[28:31]
	v_mfma_f32_16x16x32_bf16 v[24:27], v[160:163], v[200:203], v[24:27]
	v_mfma_f32_16x16x32_bf16 v[12:15], v[152:155], v[208:211], v[12:15]
	v_mfma_f32_16x16x32_bf16 v[8:11], v[160:163], v[208:211], v[8:11]
	v_mfma_f32_16x16x32_bf16 v[60:63], v[156:159], v[188:191], v[60:63]
	v_mfma_f32_16x16x32_bf16 v[56:59], v[164:167], v[188:191], v[56:59]
	v_mfma_f32_16x16x32_bf16 v[44:47], v[156:159], v[196:199], v[44:47]
	v_mfma_f32_16x16x32_bf16 v[40:43], v[164:167], v[196:199], v[40:43]
	v_mfma_f32_16x16x32_bf16 v[28:31], v[156:159], v[204:207], v[28:31]
	v_mfma_f32_16x16x32_bf16 v[24:27], v[164:167], v[204:207], v[24:27]
	v_mfma_f32_16x16x32_bf16 v[12:15], v[156:159], v[212:215], v[12:15]
	v_mfma_f32_16x16x32_bf16 v[8:11], v[164:167], v[212:215], v[8:11]
	s_setprio 0
	s_setprio 1
	v_mfma_f32_16x16x32_bf16 v[52:55], v[168:171], v[184:187], v[52:55]
	v_mfma_f32_16x16x32_bf16 v[48:51], v[176:179], v[184:187], v[48:51]
	v_mfma_f32_16x16x32_bf16 v[36:39], v[168:171], v[192:195], v[36:39]
	v_mfma_f32_16x16x32_bf16 v[32:35], v[176:179], v[192:195], v[32:35]
	v_mfma_f32_16x16x32_bf16 v[20:23], v[168:171], v[200:203], v[20:23]
	v_mfma_f32_16x16x32_bf16 v[16:19], v[176:179], v[200:203], v[16:19]
	v_mfma_f32_16x16x32_bf16 v[4:7], v[168:171], v[208:211], v[4:7]
	v_mfma_f32_16x16x32_bf16 v[0:3], v[176:179], v[208:211], v[0:3]
	v_mfma_f32_16x16x32_bf16 v[52:55], v[172:175], v[188:191], v[52:55]
	v_mfma_f32_16x16x32_bf16 v[48:51], v[180:183], v[188:191], v[48:51]
	v_mfma_f32_16x16x32_bf16 v[36:39], v[172:175], v[196:199], v[36:39]
	v_mfma_f32_16x16x32_bf16 v[32:35], v[180:183], v[196:199], v[32:35]
	v_mfma_f32_16x16x32_bf16 v[20:23], v[172:175], v[204:207], v[20:23]
	v_mfma_f32_16x16x32_bf16 v[16:19], v[180:183], v[204:207], v[16:19]
	v_mfma_f32_16x16x32_bf16 v[4:7], v[172:175], v[212:215], v[4:7]
	v_mfma_f32_16x16x32_bf16 v[0:3], v[180:183], v[212:215], v[0:3]
	s_setprio 0
	s_barrier
	s_add_i32 s51, s51, 2
	s_add_u32 s49, s49, 0x100
	s_addc_u32 s50, s50, 0
	s_add_u32 s26, s26, 0x100
	s_addc_u32 s27, s27, 0
	s_cmp_gt_u32 s51, 13
	s_cbranch_scc0 .LBB0_1281
	s_and_b64 vcc, exec, s[16:17]
	s_cbranch_vccz .LBB0_1284
	s_barrier

.LBB0_1513:
	ds_read_b128 v[154:157], v150
	ds_read_b128 v[158:161], v150 offset:1024
	ds_read_b128 v[162:165], v150 offset:2048
	ds_read_b128 v[166:169], v150 offset:3072
	ds_read_b128 v[170:173], v151
	ds_read_b128 v[174:177], v151 offset:1024
	ds_read_b128 v[178:181], v151 offset:2048
	ds_read_b128 v[182:185], v151 offset:3072
	s_add_u32 s40, s38, 0xfffc0080
	s_addc_u32 s41, s39, -1
	s_cmp_eq_u32 s63, 12
	s_cselect_b32 s43, s31, s41
	s_cselect_b32 s42, s59, s40
	s_cselect_b32 s41, s29, s62
	s_cselect_b32 s40, s60, s61
	v_lshl_add_u64 v[146:147], s[38:39], 0, v[138:139]
	s_add_i32 m0, s44, 0xc000
	ds_read_b128 v[186:189], v152
	ds_read_b128 v[190:193], v152 offset:1024
	ds_read_b128 v[194:197], v152 offset:2048
	ds_read_b128 v[198:201], v152 offset:3072
	ds_read_b128 v[202:205], v152 offset:4096
	ds_read_b128 v[206:209], v152 offset:5120
	ds_read_b128 v[210:213], v152 offset:6144
	ds_read_b128 v[214:217], v152 offset:7168
	global_load_lds_dwordx4 v[146:147], off
	v_lshl_add_u64 v[146:147], s[38:39], 0, v[136:137]
	s_add_i32 m0, s44, 0xe000
	s_nop 0
	global_load_lds_dwordx4 v[146:147], off
	s_waitcnt vmcnt(8)
	s_waitcnt lgkmcnt(0)
	s_setprio 1
	s_barrier
	s_waitcnt lgkmcnt(0)
	v_mfma_f32_16x16x32_bf16 v[124:127], v[154:157], v[186:189], v[124:127]
	v_mfma_f32_16x16x32_bf16 v[120:123], v[162:165], v[186:189], v[120:123]
	v_mfma_f32_16x16x32_bf16 v[116:119], v[154:157], v[194:197], v[116:119]
	v_mfma_f32_16x16x32_bf16 v[108:111], v[162:165], v[194:197], v[108:111]
	v_mfma_f32_16x16x32_bf16 v[100:103], v[154:157], v[202:205], v[100:103]
	v_mfma_f32_16x16x32_bf16 v[92:95], v[162:165], v[202:205], v[92:95]
	v_mfma_f32_16x16x32_bf16 v[84:87], v[154:157], v[210:213], v[84:87]
	v_mfma_f32_16x16x32_bf16 v[76:79], v[162:165], v[210:213], v[76:79]
	v_mfma_f32_16x16x32_bf16 v[124:127], v[158:161], v[190:193], v[124:127]
	v_mfma_f32_16x16x32_bf16 v[120:123], v[166:169], v[190:193], v[120:123]
	v_mfma_f32_16x16x32_bf16 v[116:119], v[158:161], v[198:201], v[116:119]
	v_mfma_f32_16x16x32_bf16 v[108:111], v[166:169], v[198:201], v[108:111]
	v_mfma_f32_16x16x32_bf16 v[100:103], v[158:161], v[206:209], v[100:103]
	v_mfma_f32_16x16x32_bf16 v[92:95], v[166:169], v[206:209], v[92:95]
	v_mfma_f32_16x16x32_bf16 v[84:87], v[158:161], v[214:217], v[84:87]
	v_mfma_f32_16x16x32_bf16 v[76:79], v[166:169], v[214:217], v[76:79]
	s_setprio 0
	s_setprio 1
	v_mfma_f32_16x16x32_bf16 v[112:115], v[170:173], v[186:189], v[112:115]
	v_mfma_f32_16x16x32_bf16 v[104:107], v[178:181], v[186:189], v[104:107]
	v_mfma_f32_16x16x32_bf16 v[96:99], v[170:173], v[194:197], v[96:99]
	v_mfma_f32_16x16x32_bf16 v[88:91], v[178:181], v[194:197], v[88:91]
	v_mfma_f32_16x16x32_bf16 v[80:83], v[170:173], v[202:205], v[80:83]
	v_mfma_f32_16x16x32_bf16 v[72:75], v[178:181], v[202:205], v[72:75]
	v_mfma_f32_16x16x32_bf16 v[68:71], v[170:173], v[210:213], v[68:71]
	v_mfma_f32_16x16x32_bf16 v[64:67], v[178:181], v[210:213], v[64:67]
	v_mfma_f32_16x16x32_bf16 v[112:115], v[174:177], v[190:193], v[112:115]
	v_mfma_f32_16x16x32_bf16 v[104:107], v[182:185], v[190:193], v[104:107]
	v_mfma_f32_16x16x32_bf16 v[96:99], v[174:177], v[198:201], v[96:99]
	v_mfma_f32_16x16x32_bf16 v[88:91], v[182:185], v[198:201], v[88:91]
	v_mfma_f32_16x16x32_bf16 v[80:83], v[174:177], v[206:209], v[80:83]
	v_mfma_f32_16x16x32_bf16 v[72:75], v[182:185], v[206:209], v[72:75]
	v_mfma_f32_16x16x32_bf16 v[68:71], v[174:177], v[214:217], v[68:71]
	v_mfma_f32_16x16x32_bf16 v[64:67], v[182:185], v[214:217], v[64:67]
	s_setprio 0
	s_barrier
	s_add_i32 s64, s51, s33
	v_lshl_add_u64 v[146:147], s[40:41], 0, v[132:133]
	s_mov_b32 m0, s64
	ds_read_b128 v[186:189], v152 offset:16384
	ds_read_b128 v[190:193], v152 offset:17408
	ds_read_b128 v[194:197], v152 offset:18432
	ds_read_b128 v[198:201], v152 offset:19456
	ds_read_b128 v[202:205], v152 offset:20480
	ds_read_b128 v[206:209], v152 offset:21504
	ds_read_b128 v[210:213], v152 offset:22528
	ds_read_b128 v[214:217], v152 offset:23552
	global_load_lds_dwordx4 v[146:147], off
	s_add_i32 m0, s64, 0x2000
	s_add_u32 s64, s40, 0x40000
	v_lshl_add_u64 v[218:219], s[40:41], 0, v[128:129]
	s_addc_u32 s65, s41, 0
	s_add_i32 s66, s52, s33
	global_load_lds_dwordx4 v[218:219], off
	v_lshl_add_u64 v[220:221], s[64:65], 0, v[132:133]
	s_mov_b32 m0, s66
	v_lshl_add_u64 v[222:223], s[42:43], 0, v[130:131]
	global_load_lds_dwordx4 v[220:221], off
	v_lshl_add_u64 v[220:221], s[64:65], 0, v[128:129]
	s_add_i32 m0, s66, 0x2000
	s_nop 0
	global_load_lds_dwordx4 v[220:221], off
	v_lshl_add_u64 v[220:221], s[42:43], 0, v[134:135]
	s_mov_b32 m0, s44
	s_nop 0
	global_load_lds_dwordx4 v[220:221], off
	s_mov_b32 m0, s45
	s_nop 0
	global_load_lds_dwordx4 v[222:223], off
	s_waitcnt vmcnt(8)
	s_waitcnt lgkmcnt(0)
	s_setprio 1
	s_barrier
	s_waitcnt lgkmcnt(0)
	v_mfma_f32_16x16x32_bf16 v[60:63], v[154:157], v[186:189], v[60:63]
	v_mfma_f32_16x16x32_bf16 v[56:59], v[162:165], v[186:189], v[56:59]
	v_mfma_f32_16x16x32_bf16 v[52:55], v[154:157], v[194:197], v[52:55]
	v_mfma_f32_16x16x32_bf16 v[44:47], v[162:165], v[194:197], v[44:47]
	v_mfma_f32_16x16x32_bf16 v[36:39], v[154:157], v[202:205], v[36:39]
	v_mfma_f32_16x16x32_bf16 v[28:31], v[162:165], v[202:205], v[28:31]
	v_mfma_f32_16x16x32_bf16 v[20:23], v[154:157], v[210:213], v[20:23]
	v_mfma_f32_16x16x32_bf16 v[12:15], v[162:165], v[210:213], v[12:15]
	v_mfma_f32_16x16x32_bf16 v[60:63], v[158:161], v[190:193], v[60:63]
	v_mfma_f32_16x16x32_bf16 v[56:59], v[166:169], v[190:193], v[56:59]
	v_mfma_f32_16x16x32_bf16 v[52:55], v[158:161], v[198:201], v[52:55]
	v_mfma_f32_16x16x32_bf16 v[44:47], v[166:169], v[198:201], v[44:47]
	v_mfma_f32_16x16x32_bf16 v[36:39], v[158:161], v[206:209], v[36:39]
	v_mfma_f32_16x16x32_bf16 v[28:31], v[166:169], v[206:209], v[28:31]
	v_mfma_f32_16x16x32_bf16 v[20:23], v[158:161], v[214:217], v[20:23]
	v_mfma_f32_16x16x32_bf16 v[12:15], v[166:169], v[214:217], v[12:15]
	s_setprio 0
	s_setprio 1
	v_mfma_f32_16x16x32_bf16 v[48:51], v[170:173], v[186:189], v[48:51]
	v_mfma_f32_16x16x32_bf16 v[40:43], v[178:181], v[186:189], v[40:43]
	v_mfma_f32_16x16x32_bf16 v[32:35], v[170:173], v[194:197], v[32:35]
	v_mfma_f32_16x16x32_bf16 v[24:27], v[178:181], v[194:197], v[24:27]
	v_mfma_f32_16x16x32_bf16 v[16:19], v[170:173], v[202:205], v[16:19]
	v_mfma_f32_16x16x32_bf16 v[8:11], v[178:181], v[202:205], v[8:11]
	v_mfma_f32_16x16x32_bf16 v[4:7], v[170:173], v[210:213], v[4:7]
	v_mfma_f32_16x16x32_bf16 v[0:3], v[178:181], v[210:213], v[0:3]
	v_mfma_f32_16x16x32_bf16 v[48:51], v[174:177], v[190:193], v[48:51]
	v_mfma_f32_16x16x32_bf16 v[40:43], v[182:185], v[190:193], v[40:43]
	v_mfma_f32_16x16x32_bf16 v[32:35], v[174:177], v[198:201], v[32:35]
	v_mfma_f32_16x16x32_bf16 v[24:27], v[182:185], v[198:201], v[24:27]
	v_mfma_f32_16x16x32_bf16 v[16:19], v[174:177], v[206:209], v[16:19]
	v_mfma_f32_16x16x32_bf16 v[8:11], v[182:185], v[206:209], v[8:11]
	v_mfma_f32_16x16x32_bf16 v[4:7], v[174:177], v[214:217], v[4:7]
	v_mfma_f32_16x16x32_bf16 v[0:3], v[182:185], v[214:217], v[0:3]
	s_setprio 0
	s_barrier
	s_add_i32 s64, 0, 0x18000
	v_add_u32_e32 v144, s64, v148
	s_add_i32 s65, 0, 0x1c000
	ds_read_b128 v[154:157], v144
	ds_read_b128 v[158:161], v144 offset:1024
	ds_read_b128 v[162:165], v144 offset:2048
	ds_read_b128 v[166:169], v144 offset:3072
	v_add_u32_e32 v144, s65, v148
	ds_read_b128 v[170:173], v144
	ds_read_b128 v[174:177], v144 offset:1024
	ds_read_b128 v[178:181], v144 offset:2048
	ds_read_b128 v[182:185], v144 offset:3072
	s_add_u32 s42, s42, 0x40000
	s_addc_u32 s43, s43, 0
	s_mov_b32 m0, s46
	v_lshl_add_u64 v[224:225], s[42:43], 0, v[134:135]
	ds_read_b128 v[186:189], v152 offset:32768
	ds_read_b128 v[190:193], v152 offset:33792
	ds_read_b128 v[194:197], v152 offset:34816
	ds_read_b128 v[198:201], v152 offset:35840
	ds_read_b128 v[202:205], v152 offset:36864
	ds_read_b128 v[206:209], v152 offset:37888
	ds_read_b128 v[210:213], v152 offset:38912
	ds_read_b128 v[214:217], v152 offset:39936
	global_load_lds_dwordx4 v[224:225], off
	v_lshl_add_u64 v[224:225], s[42:43], 0, v[130:131]
	s_mov_b32 m0, s47
	s_nop 0
	global_load_lds_dwordx4 v[224:225], off
	s_waitcnt vmcnt(8)
	s_waitcnt lgkmcnt(0)
	s_setprio 1
	s_barrier
	s_waitcnt lgkmcnt(0)
	v_mfma_f32_16x16x32_bf16 v[124:127], v[154:157], v[186:189], v[124:127]
	v_mfma_f32_16x16x32_bf16 v[120:123], v[162:165], v[186:189], v[120:123]
	v_mfma_f32_16x16x32_bf16 v[116:119], v[154:157], v[194:197], v[116:119]
	v_mfma_f32_16x16x32_bf16 v[108:111], v[162:165], v[194:197], v[108:111]
	v_mfma_f32_16x16x32_bf16 v[100:103], v[154:157], v[202:205], v[100:103]
	v_mfma_f32_16x16x32_bf16 v[92:95], v[162:165], v[202:205], v[92:95]
	v_mfma_f32_16x16x32_bf16 v[84:87], v[154:157], v[210:213], v[84:87]
	v_mfma_f32_16x16x32_bf16 v[76:79], v[162:165], v[210:213], v[76:79]
	v_mfma_f32_16x16x32_bf16 v[124:127], v[158:161], v[190:193], v[124:127]
	v_mfma_f32_16x16x32_bf16 v[120:123], v[166:169], v[190:193], v[120:123]
	v_mfma_f32_16x16x32_bf16 v[116:119], v[158:161], v[198:201], v[116:119]
	v_mfma_f32_16x16x32_bf16 v[108:111], v[166:169], v[198:201], v[108:111]
	v_mfma_f32_16x16x32_bf16 v[100:103], v[158:161], v[206:209], v[100:103]
	v_mfma_f32_16x16x32_bf16 v[92:95], v[166:169], v[206:209], v[92:95]
	v_mfma_f32_16x16x32_bf16 v[84:87], v[158:161], v[214:217], v[84:87]
	v_mfma_f32_16x16x32_bf16 v[76:79], v[166:169], v[214:217], v[76:79]
	s_setprio 0
	s_setprio 1
	v_mfma_f32_16x16x32_bf16 v[112:115], v[170:173], v[186:189], v[112:115]
	v_mfma_f32_16x16x32_bf16 v[104:107], v[178:181], v[186:189], v[104:107]
	v_mfma_f32_16x16x32_bf16 v[96:99], v[170:173], v[194:197], v[96:99]
	v_mfma_f32_16x16x32_bf16 v[88:91], v[178:181], v[194:197], v[88:91]
	v_mfma_f32_16x16x32_bf16 v[80:83], v[170:173], v[202:205], v[80:83]
	v_mfma_f32_16x16x32_bf16 v[72:75], v[178:181], v[202:205], v[72:75]
	v_mfma_f32_16x16x32_bf16 v[68:71], v[170:173], v[210:213], v[68:71]
	v_mfma_f32_16x16x32_bf16 v[64:67], v[178:181], v[210:213], v[64:67]
	v_mfma_f32_16x16x32_bf16 v[112:115], v[174:177], v[190:193], v[112:115]
	v_mfma_f32_16x16x32_bf16 v[104:107], v[182:185], v[190:193], v[104:107]
	v_mfma_f32_16x16x32_bf16 v[96:99], v[174:177], v[198:201], v[96:99]
	v_mfma_f32_16x16x32_bf16 v[88:91], v[182:185], v[198:201], v[88:91]
	v_mfma_f32_16x16x32_bf16 v[80:83], v[174:177], v[206:209], v[80:83]
	v_mfma_f32_16x16x32_bf16 v[72:75], v[182:185], v[206:209], v[72:75]
	v_mfma_f32_16x16x32_bf16 v[68:71], v[174:177], v[214:217], v[68:71]
	v_mfma_f32_16x16x32_bf16 v[64:67], v[182:185], v[214:217], v[64:67]
	s_setprio 0
	s_barrier
	s_add_i32 s42, s64, s33
	v_lshl_add_u64 v[146:147], v[146:147], 0, s[18:19]
	s_mov_b32 m0, s42
	ds_read_b128 v[186:189], v152 offset:49152
	ds_read_b128 v[190:193], v152 offset:50176
	ds_read_b128 v[194:197], v152 offset:51200
	ds_read_b128 v[198:201], v152 offset:52224
	ds_read_b128 v[202:205], v152 offset:53248
	ds_read_b128 v[206:209], v152 offset:54272
	ds_read_b128 v[210:213], v152 offset:55296
	ds_read_b128 v[214:217], v152 offset:56320
	global_load_lds_dwordx4 v[146:147], off
	s_add_i32 m0, s42, 0x2000
	s_add_u32 s40, s40, 0x40080
	v_lshl_add_u64 v[146:147], v[218:219], 0, s[18:19]
	s_addc_u32 s41, s41, 0
	s_add_i32 s42, s65, s33
	global_load_lds_dwordx4 v[146:147], off
	v_lshl_add_u64 v[146:147], s[40:41], 0, v[132:133]
	s_mov_b32 m0, s42
	s_nop 0
	global_load_lds_dwordx4 v[146:147], off
	v_lshl_add_u64 v[146:147], s[40:41], 0, v[128:129]
	s_add_i32 m0, s42, 0x2000
	s_nop 0
	global_load_lds_dwordx4 v[146:147], off
	v_lshl_add_u64 v[146:147], v[220:221], 0, s[18:19]
	s_mov_b32 m0, s49
	s_nop 0
	global_load_lds_dwordx4 v[146:147], off
	v_lshl_add_u64 v[146:147], v[222:223], 0, s[18:19]
	s_mov_b32 m0, s50
	s_nop 0
	global_load_lds_dwordx4 v[146:147], off
	s_waitcnt vmcnt(8)
	s_waitcnt lgkmcnt(0)
	s_setprio 1
	s_barrier
	s_waitcnt lgkmcnt(0)
	v_mfma_f32_16x16x32_bf16 v[60:63], v[154:157], v[186:189], v[60:63]
	v_mfma_f32_16x16x32_bf16 v[56:59], v[162:165], v[186:189], v[56:59]
	v_mfma_f32_16x16x32_bf16 v[52:55], v[154:157], v[194:197], v[52:55]
	v_mfma_f32_16x16x32_bf16 v[44:47], v[162:165], v[194:197], v[44:47]
	v_mfma_f32_16x16x32_bf16 v[36:39], v[154:157], v[202:205], v[36:39]
	v_mfma_f32_16x16x32_bf16 v[28:31], v[162:165], v[202:205], v[28:31]
	v_mfma_f32_16x16x32_bf16 v[20:23], v[154:157], v[210:213], v[20:23]
	v_mfma_f32_16x16x32_bf16 v[12:15], v[162:165], v[210:213], v[12:15]
	v_mfma_f32_16x16x32_bf16 v[60:63], v[158:161], v[190:193], v[60:63]
	v_mfma_f32_16x16x32_bf16 v[56:59], v[166:169], v[190:193], v[56:59]
	v_mfma_f32_16x16x32_bf16 v[52:55], v[158:161], v[198:201], v[52:55]
	v_mfma_f32_16x16x32_bf16 v[44:47], v[166:169], v[198:201], v[44:47]
	v_mfma_f32_16x16x32_bf16 v[36:39], v[158:161], v[206:209], v[36:39]
	v_mfma_f32_16x16x32_bf16 v[28:31], v[166:169], v[206:209], v[28:31]
	v_mfma_f32_16x16x32_bf16 v[20:23], v[158:161], v[214:217], v[20:23]
	v_mfma_f32_16x16x32_bf16 v[12:15], v[166:169], v[214:217], v[12:15]
	s_setprio 0
	s_setprio 1
	v_mfma_f32_16x16x32_bf16 v[48:51], v[170:173], v[186:189], v[48:51]
	v_mfma_f32_16x16x32_bf16 v[40:43], v[178:181], v[186:189], v[40:43]
	v_mfma_f32_16x16x32_bf16 v[32:35], v[170:173], v[194:197], v[32:35]
	v_mfma_f32_16x16x32_bf16 v[24:27], v[178:181], v[194:197], v[24:27]
	v_mfma_f32_16x16x32_bf16 v[16:19], v[170:173], v[202:205], v[16:19]
	v_mfma_f32_16x16x32_bf16 v[8:11], v[178:181], v[202:205], v[8:11]
	v_mfma_f32_16x16x32_bf16 v[4:7], v[170:173], v[210:213], v[4:7]
	v_mfma_f32_16x16x32_bf16 v[0:3], v[178:181], v[210:213], v[0:3]
	v_mfma_f32_16x16x32_bf16 v[48:51], v[174:177], v[190:193], v[48:51]
	v_mfma_f32_16x16x32_bf16 v[40:43], v[182:185], v[190:193], v[40:43]
	v_mfma_f32_16x16x32_bf16 v[32:35], v[174:177], v[198:201], v[32:35]
	v_mfma_f32_16x16x32_bf16 v[24:27], v[182:185], v[198:201], v[24:27]
	v_mfma_f32_16x16x32_bf16 v[16:19], v[174:177], v[206:209], v[16:19]
	v_mfma_f32_16x16x32_bf16 v[8:11], v[182:185], v[206:209], v[8:11]
	v_mfma_f32_16x16x32_bf16 v[4:7], v[174:177], v[214:217], v[4:7]
	v_mfma_f32_16x16x32_bf16 v[0:3], v[182:185], v[214:217], v[0:3]
	s_setprio 0
	s_barrier
	s_add_i32 s63, s63, 2
	s_add_u32 s61, s61, 0x100
	s_addc_u32 s62, s62, 0
	s_add_u32 s38, s38, 0x100
	s_addc_u32 s39, s39, 0
	s_cmp_gt_u32 s63, 13
	s_cbranch_scc0 .LBB0_1513
	s_and_b64 vcc, exec, s[20:21]
	s_cbranch_vccz .LBB0_1516
	s_barrier

.LBB0_1529:
	ds_read_b128 v[150:153], v147
	ds_read_b128 v[154:157], v147 offset:1024
	ds_read_b128 v[158:161], v147 offset:2048
	ds_read_b128 v[162:165], v147 offset:3072
	ds_read_b128 v[166:169], v148
	ds_read_b128 v[170:173], v148 offset:1024
	ds_read_b128 v[174:177], v148 offset:2048
	ds_read_b128 v[178:181], v148 offset:3072
	s_add_u32 s40, s38, 0xfffc0080
	s_addc_u32 s41, s39, -1
	s_cmp_eq_u32 s62, 12
	s_cselect_b32 s43, s31, s41
	s_cselect_b32 s42, s58, s40
	s_cselect_b32 s41, s29, s61
	s_cselect_b32 s40, s59, s60
	v_lshl_add_u64 v[214:215], s[38:39], 0, v[138:139]
	s_add_i32 m0, s27, 0xc000
	ds_read_b128 v[182:185], v149
	ds_read_b128 v[186:189], v149 offset:1024
	ds_read_b128 v[190:193], v149 offset:2048
	ds_read_b128 v[194:197], v149 offset:3072
	ds_read_b128 v[198:201], v149 offset:4096
	ds_read_b128 v[202:205], v149 offset:5120
	ds_read_b128 v[206:209], v149 offset:6144
	ds_read_b128 v[210:213], v149 offset:7168
	global_load_lds_dwordx4 v[214:215], off
	v_lshl_add_u64 v[214:215], s[38:39], 0, v[136:137]
	s_add_i32 m0, s27, 0xe000
	s_nop 0
	global_load_lds_dwordx4 v[214:215], off
	s_waitcnt vmcnt(8)
	s_waitcnt lgkmcnt(0)
	s_setprio 1
	s_barrier
	s_waitcnt lgkmcnt(0)
	v_mfma_f32_16x16x32_bf16 v[124:127], v[150:153], v[182:185], v[124:127]
	v_mfma_f32_16x16x32_bf16 v[120:123], v[158:161], v[182:185], v[120:123]
	v_mfma_f32_16x16x32_bf16 v[116:119], v[150:153], v[190:193], v[116:119]
	v_mfma_f32_16x16x32_bf16 v[112:115], v[158:161], v[190:193], v[112:115]
	v_mfma_f32_16x16x32_bf16 v[100:103], v[150:153], v[198:201], v[100:103]
	v_mfma_f32_16x16x32_bf16 v[96:99], v[158:161], v[198:201], v[96:99]
	v_mfma_f32_16x16x32_bf16 v[84:87], v[150:153], v[206:209], v[84:87]
	v_mfma_f32_16x16x32_bf16 v[80:83], v[158:161], v[206:209], v[80:83]
	v_mfma_f32_16x16x32_bf16 v[124:127], v[154:157], v[186:189], v[124:127]
	v_mfma_f32_16x16x32_bf16 v[120:123], v[162:165], v[186:189], v[120:123]
	v_mfma_f32_16x16x32_bf16 v[116:119], v[154:157], v[194:197], v[116:119]
	v_mfma_f32_16x16x32_bf16 v[112:115], v[162:165], v[194:197], v[112:115]
	v_mfma_f32_16x16x32_bf16 v[100:103], v[154:157], v[202:205], v[100:103]
	v_mfma_f32_16x16x32_bf16 v[96:99], v[162:165], v[202:205], v[96:99]
	v_mfma_f32_16x16x32_bf16 v[84:87], v[154:157], v[210:213], v[84:87]
	v_mfma_f32_16x16x32_bf16 v[80:83], v[162:165], v[210:213], v[80:83]
	s_setprio 0
	s_setprio 1
	v_mfma_f32_16x16x32_bf16 v[108:111], v[166:169], v[182:185], v[108:111]
	v_mfma_f32_16x16x32_bf16 v[104:107], v[174:177], v[182:185], v[104:107]
	v_mfma_f32_16x16x32_bf16 v[92:95], v[166:169], v[190:193], v[92:95]
	v_mfma_f32_16x16x32_bf16 v[88:91], v[174:177], v[190:193], v[88:91]
	v_mfma_f32_16x16x32_bf16 v[76:79], v[166:169], v[198:201], v[76:79]
	v_mfma_f32_16x16x32_bf16 v[72:75], v[174:177], v[198:201], v[72:75]
	v_mfma_f32_16x16x32_bf16 v[68:71], v[166:169], v[206:209], v[68:71]
	v_mfma_f32_16x16x32_bf16 v[64:67], v[174:177], v[206:209], v[64:67]
	v_mfma_f32_16x16x32_bf16 v[108:111], v[170:173], v[186:189], v[108:111]
	v_mfma_f32_16x16x32_bf16 v[104:107], v[178:181], v[186:189], v[104:107]
	v_mfma_f32_16x16x32_bf16 v[92:95], v[170:173], v[194:197], v[92:95]
	v_mfma_f32_16x16x32_bf16 v[88:91], v[178:181], v[194:197], v[88:91]
	v_mfma_f32_16x16x32_bf16 v[76:79], v[170:173], v[202:205], v[76:79]
	v_mfma_f32_16x16x32_bf16 v[72:75], v[178:181], v[202:205], v[72:75]
	v_mfma_f32_16x16x32_bf16 v[68:71], v[170:173], v[210:213], v[68:71]
	v_mfma_f32_16x16x32_bf16 v[64:67], v[178:181], v[210:213], v[64:67]
	s_setprio 0
	s_barrier
	s_add_i32 s63, s51, s33
	v_lshl_add_u64 v[214:215], s[40:41], 0, v[132:133]
	s_mov_b32 m0, s63
	ds_read_b128 v[182:185], v149 offset:16384
	ds_read_b128 v[186:189], v149 offset:17408
	ds_read_b128 v[190:193], v149 offset:18432
	ds_read_b128 v[194:197], v149 offset:19456
	ds_read_b128 v[198:201], v149 offset:20480
	ds_read_b128 v[202:205], v149 offset:21504
	ds_read_b128 v[206:209], v149 offset:22528
	ds_read_b128 v[210:213], v149 offset:23552
	global_load_lds_dwordx4 v[214:215], off
	s_add_i32 m0, s63, 0x2000
	s_add_u32 s64, s40, 0x40000
	v_lshl_add_u64 v[216:217], s[40:41], 0, v[128:129]
	s_addc_u32 s65, s41, 0
	s_add_i32 s63, s52, s33
	global_load_lds_dwordx4 v[216:217], off
	v_lshl_add_u64 v[218:219], s[64:65], 0, v[132:133]
	s_mov_b32 m0, s63
	v_lshl_add_u64 v[220:221], s[42:43], 0, v[130:131]
	global_load_lds_dwordx4 v[218:219], off
	v_lshl_add_u64 v[218:219], s[64:65], 0, v[128:129]
	s_add_i32 m0, s63, 0x2000
	s_nop 0
	global_load_lds_dwordx4 v[218:219], off
	v_lshl_add_u64 v[218:219], s[42:43], 0, v[134:135]
	s_mov_b32 m0, s27
	s_nop 0
	global_load_lds_dwordx4 v[218:219], off
	s_mov_b32 m0, s45
	s_nop 0
	global_load_lds_dwordx4 v[220:221], off
	s_waitcnt vmcnt(8)
	s_waitcnt lgkmcnt(0)
	s_setprio 1
	s_barrier
	s_waitcnt lgkmcnt(0)
	v_mfma_f32_16x16x32_bf16 v[60:63], v[150:153], v[182:185], v[60:63]
	v_mfma_f32_16x16x32_bf16 v[56:59], v[158:161], v[182:185], v[56:59]
	v_mfma_f32_16x16x32_bf16 v[52:55], v[150:153], v[190:193], v[52:55]
	v_mfma_f32_16x16x32_bf16 v[48:51], v[158:161], v[190:193], v[48:51]
	v_mfma_f32_16x16x32_bf16 v[36:39], v[150:153], v[198:201], v[36:39]
	v_mfma_f32_16x16x32_bf16 v[32:35], v[158:161], v[198:201], v[32:35]
	v_mfma_f32_16x16x32_bf16 v[20:23], v[150:153], v[206:209], v[20:23]
	v_mfma_f32_16x16x32_bf16 v[16:19], v[158:161], v[206:209], v[16:19]
	v_mfma_f32_16x16x32_bf16 v[60:63], v[154:157], v[186:189], v[60:63]
	v_mfma_f32_16x16x32_bf16 v[56:59], v[162:165], v[186:189], v[56:59]
	v_mfma_f32_16x16x32_bf16 v[52:55], v[154:157], v[194:197], v[52:55]
	v_mfma_f32_16x16x32_bf16 v[48:51], v[162:165], v[194:197], v[48:51]
	v_mfma_f32_16x16x32_bf16 v[36:39], v[154:157], v[202:205], v[36:39]
	v_mfma_f32_16x16x32_bf16 v[32:35], v[162:165], v[202:205], v[32:35]
	v_mfma_f32_16x16x32_bf16 v[20:23], v[154:157], v[210:213], v[20:23]
	v_mfma_f32_16x16x32_bf16 v[16:19], v[162:165], v[210:213], v[16:19]
	s_setprio 0
	s_setprio 1
	v_mfma_f32_16x16x32_bf16 v[44:47], v[166:169], v[182:185], v[44:47]
	v_mfma_f32_16x16x32_bf16 v[40:43], v[174:177], v[182:185], v[40:43]
	v_mfma_f32_16x16x32_bf16 v[28:31], v[166:169], v[190:193], v[28:31]
	v_mfma_f32_16x16x32_bf16 v[24:27], v[174:177], v[190:193], v[24:27]
	v_mfma_f32_16x16x32_bf16 v[12:15], v[166:169], v[198:201], v[12:15]
	v_mfma_f32_16x16x32_bf16 v[8:11], v[174:177], v[198:201], v[8:11]
	v_mfma_f32_16x16x32_bf16 v[4:7], v[166:169], v[206:209], v[4:7]
	v_mfma_f32_16x16x32_bf16 v[0:3], v[174:177], v[206:209], v[0:3]
	v_mfma_f32_16x16x32_bf16 v[44:47], v[170:173], v[186:189], v[44:47]
	v_mfma_f32_16x16x32_bf16 v[40:43], v[178:181], v[186:189], v[40:43]
	v_mfma_f32_16x16x32_bf16 v[28:31], v[170:173], v[194:197], v[28:31]
	v_mfma_f32_16x16x32_bf16 v[24:27], v[178:181], v[194:197], v[24:27]
	v_mfma_f32_16x16x32_bf16 v[12:15], v[170:173], v[202:205], v[12:15]
	v_mfma_f32_16x16x32_bf16 v[8:11], v[178:181], v[202:205], v[8:11]
	v_mfma_f32_16x16x32_bf16 v[4:7], v[170:173], v[210:213], v[4:7]
	v_mfma_f32_16x16x32_bf16 v[0:3], v[178:181], v[210:213], v[0:3]
	s_setprio 0
	s_barrier
	s_add_i32 s63, 0, 0x18000
	s_add_i32 s64, 0, 0x1c000
	v_add_u32_e32 v162, s63, v145
	v_add_u32_e32 v178, s64, v145
	ds_read_b128 v[150:153], v162
	ds_read_b128 v[154:157], v162 offset:1024
	ds_read_b128 v[158:161], v162 offset:2048
	ds_read_b128 v[162:165], v162 offset:3072
	ds_read_b128 v[166:169], v178
	ds_read_b128 v[170:173], v178 offset:1024
	ds_read_b128 v[174:177], v178 offset:2048
	ds_read_b128 v[178:181], v178 offset:3072
	s_add_u32 s42, s42, 0x40000
	s_addc_u32 s43, s43, 0
	s_mov_b32 m0, s46
	v_lshl_add_u64 v[222:223], s[42:43], 0, v[134:135]
	ds_read_b128 v[182:185], v149 offset:32768
	ds_read_b128 v[186:189], v149 offset:33792
	ds_read_b128 v[190:193], v149 offset:34816
	ds_read_b128 v[194:197], v149 offset:35840
	ds_read_b128 v[198:201], v149 offset:36864
	ds_read_b128 v[202:205], v149 offset:37888
	ds_read_b128 v[206:209], v149 offset:38912
	ds_read_b128 v[210:213], v149 offset:39936
	global_load_lds_dwordx4 v[222:223], off
	v_lshl_add_u64 v[222:223], s[42:43], 0, v[130:131]
	s_mov_b32 m0, s47
	s_nop 0
	global_load_lds_dwordx4 v[222:223], off
	s_waitcnt vmcnt(8)
	s_waitcnt lgkmcnt(0)
	s_setprio 1
	s_barrier
	s_waitcnt lgkmcnt(0)
	v_mfma_f32_16x16x32_bf16 v[124:127], v[150:153], v[182:185], v[124:127]
	v_mfma_f32_16x16x32_bf16 v[120:123], v[158:161], v[182:185], v[120:123]
	v_mfma_f32_16x16x32_bf16 v[116:119], v[150:153], v[190:193], v[116:119]
	v_mfma_f32_16x16x32_bf16 v[112:115], v[158:161], v[190:193], v[112:115]
	v_mfma_f32_16x16x32_bf16 v[100:103], v[150:153], v[198:201], v[100:103]
	v_mfma_f32_16x16x32_bf16 v[96:99], v[158:161], v[198:201], v[96:99]
	v_mfma_f32_16x16x32_bf16 v[84:87], v[150:153], v[206:209], v[84:87]
	v_mfma_f32_16x16x32_bf16 v[80:83], v[158:161], v[206:209], v[80:83]
	v_mfma_f32_16x16x32_bf16 v[124:127], v[154:157], v[186:189], v[124:127]
	v_mfma_f32_16x16x32_bf16 v[120:123], v[162:165], v[186:189], v[120:123]
	v_mfma_f32_16x16x32_bf16 v[116:119], v[154:157], v[194:197], v[116:119]
	v_mfma_f32_16x16x32_bf16 v[112:115], v[162:165], v[194:197], v[112:115]
	v_mfma_f32_16x16x32_bf16 v[100:103], v[154:157], v[202:205], v[100:103]
	v_mfma_f32_16x16x32_bf16 v[96:99], v[162:165], v[202:205], v[96:99]
	v_mfma_f32_16x16x32_bf16 v[84:87], v[154:157], v[210:213], v[84:87]
	v_mfma_f32_16x16x32_bf16 v[80:83], v[162:165], v[210:213], v[80:83]
	s_setprio 0
	s_setprio 1
	v_mfma_f32_16x16x32_bf16 v[108:111], v[166:169], v[182:185], v[108:111]
	v_mfma_f32_16x16x32_bf16 v[104:107], v[174:177], v[182:185], v[104:107]
	v_mfma_f32_16x16x32_bf16 v[92:95], v[166:169], v[190:193], v[92:95]
	v_mfma_f32_16x16x32_bf16 v[88:91], v[174:177], v[190:193], v[88:91]
	v_mfma_f32_16x16x32_bf16 v[76:79], v[166:169], v[198:201], v[76:79]
	v_mfma_f32_16x16x32_bf16 v[72:75], v[174:177], v[198:201], v[72:75]
	v_mfma_f32_16x16x32_bf16 v[68:71], v[166:169], v[206:209], v[68:71]
	v_mfma_f32_16x16x32_bf16 v[64:67], v[174:177], v[206:209], v[64:67]
	v_mfma_f32_16x16x32_bf16 v[108:111], v[170:173], v[186:189], v[108:111]
	v_mfma_f32_16x16x32_bf16 v[104:107], v[178:181], v[186:189], v[104:107]
	v_mfma_f32_16x16x32_bf16 v[92:95], v[170:173], v[194:197], v[92:95]
	v_mfma_f32_16x16x32_bf16 v[88:91], v[178:181], v[194:197], v[88:91]
	v_mfma_f32_16x16x32_bf16 v[76:79], v[170:173], v[202:205], v[76:79]
	v_mfma_f32_16x16x32_bf16 v[72:75], v[178:181], v[202:205], v[72:75]
	v_mfma_f32_16x16x32_bf16 v[68:71], v[170:173], v[210:213], v[68:71]
	v_mfma_f32_16x16x32_bf16 v[64:67], v[178:181], v[210:213], v[64:67]
	s_setprio 0
	s_barrier
	s_add_i32 s42, s63, s33
	v_lshl_add_u64 v[214:215], v[214:215], 0, s[16:17]
	s_mov_b32 m0, s42
	ds_read_b128 v[182:185], v149 offset:49152
	ds_read_b128 v[186:189], v149 offset:50176
	ds_read_b128 v[190:193], v149 offset:51200
	ds_read_b128 v[194:197], v149 offset:52224
	ds_read_b128 v[198:201], v149 offset:53248
	ds_read_b128 v[202:205], v149 offset:54272
	ds_read_b128 v[206:209], v149 offset:55296
	ds_read_b128 v[210:213], v149 offset:56320
	global_load_lds_dwordx4 v[214:215], off
	s_add_i32 m0, s42, 0x2000
	s_add_u32 s40, s40, 0x40080
	v_lshl_add_u64 v[214:215], v[216:217], 0, s[16:17]
	s_addc_u32 s41, s41, 0
	s_add_i32 s42, s64, s33
	global_load_lds_dwordx4 v[214:215], off
	v_lshl_add_u64 v[214:215], s[40:41], 0, v[132:133]
	s_mov_b32 m0, s42
	s_nop 0
	global_load_lds_dwordx4 v[214:215], off
	v_lshl_add_u64 v[214:215], s[40:41], 0, v[128:129]
	s_add_i32 m0, s42, 0x2000
	s_nop 0
	global_load_lds_dwordx4 v[214:215], off
	v_lshl_add_u64 v[214:215], v[218:219], 0, s[16:17]
	s_mov_b32 m0, s49
	s_nop 0
	global_load_lds_dwordx4 v[214:215], off
	v_lshl_add_u64 v[214:215], v[220:221], 0, s[16:17]
	s_mov_b32 m0, s50
	s_nop 0
	global_load_lds_dwordx4 v[214:215], off
	s_waitcnt vmcnt(8)
	s_waitcnt lgkmcnt(0)
	s_setprio 1
	s_barrier
	s_waitcnt lgkmcnt(0)
	v_mfma_f32_16x16x32_bf16 v[60:63], v[150:153], v[182:185], v[60:63]
	v_mfma_f32_16x16x32_bf16 v[56:59], v[158:161], v[182:185], v[56:59]
	v_mfma_f32_16x16x32_bf16 v[52:55], v[150:153], v[190:193], v[52:55]
	v_mfma_f32_16x16x32_bf16 v[48:51], v[158:161], v[190:193], v[48:51]
	v_mfma_f32_16x16x32_bf16 v[36:39], v[150:153], v[198:201], v[36:39]
	v_mfma_f32_16x16x32_bf16 v[32:35], v[158:161], v[198:201], v[32:35]
	v_mfma_f32_16x16x32_bf16 v[20:23], v[150:153], v[206:209], v[20:23]
	v_mfma_f32_16x16x32_bf16 v[16:19], v[158:161], v[206:209], v[16:19]
	v_mfma_f32_16x16x32_bf16 v[60:63], v[154:157], v[186:189], v[60:63]
	v_mfma_f32_16x16x32_bf16 v[56:59], v[162:165], v[186:189], v[56:59]
	v_mfma_f32_16x16x32_bf16 v[52:55], v[154:157], v[194:197], v[52:55]
	v_mfma_f32_16x16x32_bf16 v[48:51], v[162:165], v[194:197], v[48:51]
	v_mfma_f32_16x16x32_bf16 v[36:39], v[154:157], v[202:205], v[36:39]
	v_mfma_f32_16x16x32_bf16 v[32:35], v[162:165], v[202:205], v[32:35]
	v_mfma_f32_16x16x32_bf16 v[20:23], v[154:157], v[210:213], v[20:23]
	v_mfma_f32_16x16x32_bf16 v[16:19], v[162:165], v[210:213], v[16:19]
	s_setprio 0
	s_setprio 1
	v_mfma_f32_16x16x32_bf16 v[44:47], v[166:169], v[182:185], v[44:47]
	v_mfma_f32_16x16x32_bf16 v[40:43], v[174:177], v[182:185], v[40:43]
	v_mfma_f32_16x16x32_bf16 v[28:31], v[166:169], v[190:193], v[28:31]
	v_mfma_f32_16x16x32_bf16 v[24:27], v[174:177], v[190:193], v[24:27]
	v_mfma_f32_16x16x32_bf16 v[12:15], v[166:169], v[198:201], v[12:15]
	v_mfma_f32_16x16x32_bf16 v[8:11], v[174:177], v[198:201], v[8:11]
	v_mfma_f32_16x16x32_bf16 v[4:7], v[166:169], v[206:209], v[4:7]
	v_mfma_f32_16x16x32_bf16 v[0:3], v[174:177], v[206:209], v[0:3]
	v_mfma_f32_16x16x32_bf16 v[44:47], v[170:173], v[186:189], v[44:47]
	v_mfma_f32_16x16x32_bf16 v[40:43], v[178:181], v[186:189], v[40:43]
	v_mfma_f32_16x16x32_bf16 v[28:31], v[170:173], v[194:197], v[28:31]
	v_mfma_f32_16x16x32_bf16 v[24:27], v[178:181], v[194:197], v[24:27]
	v_mfma_f32_16x16x32_bf16 v[12:15], v[170:173], v[202:205], v[12:15]
	v_mfma_f32_16x16x32_bf16 v[8:11], v[178:181], v[202:205], v[8:11]
	v_mfma_f32_16x16x32_bf16 v[4:7], v[170:173], v[210:213], v[4:7]
	v_mfma_f32_16x16x32_bf16 v[0:3], v[178:181], v[210:213], v[0:3]
	s_setprio 0
	s_barrier
	s_add_i32 s62, s62, 2
	s_add_u32 s60, s60, 0x100
	s_addc_u32 s61, s61, 0
	s_add_u32 s38, s38, 0x100
	s_addc_u32 s39, s39, 0
	s_cmp_gt_u32 s62, 13
	s_cbranch_scc0 .LBB0_1529
	s_and_b64 vcc, exec, s[18:19]
	s_cbranch_vccz .LBB0_1532
	s_barrier

.LBB0_1801:
	ds_read_b128 v[150:153], v147
	ds_read_b128 v[154:157], v147 offset:1024
	ds_read_b128 v[158:161], v147 offset:2048
	ds_read_b128 v[162:165], v147 offset:3072
	ds_read_b128 v[166:169], v148
	ds_read_b128 v[170:173], v148 offset:1024
	ds_read_b128 v[174:177], v148 offset:2048
	ds_read_b128 v[178:181], v148 offset:3072
	s_add_u32 s38, s36, 0xfffc0080
	s_addc_u32 s39, s37, -1
	s_cmp_eq_u32 s61, 12
	s_cselect_b32 s41, s29, s39
	s_cselect_b32 s40, s57, s38
	s_cselect_b32 s39, s27, s60
	s_cselect_b32 s38, s58, s59
	v_lshl_add_u64 v[214:215], s[36:37], 0, v[138:139]
	s_add_i32 m0, s42, 0xc000
	ds_read_b128 v[182:185], v149
	ds_read_b128 v[186:189], v149 offset:1024
	ds_read_b128 v[190:193], v149 offset:2048
	ds_read_b128 v[194:197], v149 offset:3072
	ds_read_b128 v[198:201], v149 offset:4096
	ds_read_b128 v[202:205], v149 offset:5120
	ds_read_b128 v[206:209], v149 offset:6144
	ds_read_b128 v[210:213], v149 offset:7168
	global_load_lds_dwordx4 v[214:215], off
	v_lshl_add_u64 v[214:215], s[36:37], 0, v[136:137]
	s_add_i32 m0, s42, 0xe000
	s_nop 0
	global_load_lds_dwordx4 v[214:215], off
	s_waitcnt vmcnt(8)
	s_waitcnt lgkmcnt(0)
	s_setprio 1
	s_barrier
	s_waitcnt lgkmcnt(0)
	v_mfma_f32_16x16x32_bf16 v[124:127], v[150:153], v[182:185], v[124:127]
	v_mfma_f32_16x16x32_bf16 v[120:123], v[158:161], v[182:185], v[120:123]
	v_mfma_f32_16x16x32_bf16 v[116:119], v[150:153], v[190:193], v[116:119]
	v_mfma_f32_16x16x32_bf16 v[112:115], v[158:161], v[190:193], v[112:115]
	v_mfma_f32_16x16x32_bf16 v[100:103], v[150:153], v[198:201], v[100:103]
	v_mfma_f32_16x16x32_bf16 v[96:99], v[158:161], v[198:201], v[96:99]
	v_mfma_f32_16x16x32_bf16 v[84:87], v[150:153], v[206:209], v[84:87]
	v_mfma_f32_16x16x32_bf16 v[80:83], v[158:161], v[206:209], v[80:83]
	v_mfma_f32_16x16x32_bf16 v[124:127], v[154:157], v[186:189], v[124:127]
	v_mfma_f32_16x16x32_bf16 v[120:123], v[162:165], v[186:189], v[120:123]
	v_mfma_f32_16x16x32_bf16 v[116:119], v[154:157], v[194:197], v[116:119]
	v_mfma_f32_16x16x32_bf16 v[112:115], v[162:165], v[194:197], v[112:115]
	v_mfma_f32_16x16x32_bf16 v[100:103], v[154:157], v[202:205], v[100:103]
	v_mfma_f32_16x16x32_bf16 v[96:99], v[162:165], v[202:205], v[96:99]
	v_mfma_f32_16x16x32_bf16 v[84:87], v[154:157], v[210:213], v[84:87]
	v_mfma_f32_16x16x32_bf16 v[80:83], v[162:165], v[210:213], v[80:83]
	s_setprio 0
	s_setprio 1
	v_mfma_f32_16x16x32_bf16 v[108:111], v[166:169], v[182:185], v[108:111]
	v_mfma_f32_16x16x32_bf16 v[104:107], v[174:177], v[182:185], v[104:107]
	v_mfma_f32_16x16x32_bf16 v[92:95], v[166:169], v[190:193], v[92:95]
	v_mfma_f32_16x16x32_bf16 v[88:91], v[174:177], v[190:193], v[88:91]
	v_mfma_f32_16x16x32_bf16 v[76:79], v[166:169], v[198:201], v[76:79]
	v_mfma_f32_16x16x32_bf16 v[72:75], v[174:177], v[198:201], v[72:75]
	v_mfma_f32_16x16x32_bf16 v[68:71], v[166:169], v[206:209], v[68:71]
	v_mfma_f32_16x16x32_bf16 v[64:67], v[174:177], v[206:209], v[64:67]
	v_mfma_f32_16x16x32_bf16 v[108:111], v[170:173], v[186:189], v[108:111]
	v_mfma_f32_16x16x32_bf16 v[104:107], v[178:181], v[186:189], v[104:107]
	v_mfma_f32_16x16x32_bf16 v[92:95], v[170:173], v[194:197], v[92:95]
	v_mfma_f32_16x16x32_bf16 v[88:91], v[178:181], v[194:197], v[88:91]
	v_mfma_f32_16x16x32_bf16 v[76:79], v[170:173], v[202:205], v[76:79]
	v_mfma_f32_16x16x32_bf16 v[72:75], v[178:181], v[202:205], v[72:75]
	v_mfma_f32_16x16x32_bf16 v[68:71], v[170:173], v[210:213], v[68:71]
	v_mfma_f32_16x16x32_bf16 v[64:67], v[178:181], v[210:213], v[64:67]
	s_setprio 0
	s_barrier
	s_add_i32 s62, s49, s33
	v_lshl_add_u64 v[214:215], s[38:39], 0, v[132:133]
	s_mov_b32 m0, s62
	ds_read_b128 v[182:185], v149 offset:16384
	ds_read_b128 v[186:189], v149 offset:17408
	ds_read_b128 v[190:193], v149 offset:18432
	ds_read_b128 v[194:197], v149 offset:19456
	ds_read_b128 v[198:201], v149 offset:20480
	ds_read_b128 v[202:205], v149 offset:21504
	ds_read_b128 v[206:209], v149 offset:22528
	ds_read_b128 v[210:213], v149 offset:23552
	global_load_lds_dwordx4 v[214:215], off
	s_add_i32 m0, s62, 0x2000
	s_add_u32 s62, s38, 0x40000
	v_lshl_add_u64 v[216:217], s[38:39], 0, v[128:129]
	s_addc_u32 s63, s39, 0
	s_add_i32 s64, s50, s33
	global_load_lds_dwordx4 v[216:217], off
	v_lshl_add_u64 v[218:219], s[62:63], 0, v[132:133]
	s_mov_b32 m0, s64
	v_lshl_add_u64 v[220:221], s[40:41], 0, v[130:131]
	global_load_lds_dwordx4 v[218:219], off
	v_lshl_add_u64 v[218:219], s[62:63], 0, v[128:129]
	s_add_i32 m0, s64, 0x2000
	s_nop 0
	global_load_lds_dwordx4 v[218:219], off
	v_lshl_add_u64 v[218:219], s[40:41], 0, v[134:135]
	s_mov_b32 m0, s42
	s_nop 0
	global_load_lds_dwordx4 v[218:219], off
	s_mov_b32 m0, s43
	s_nop 0
	global_load_lds_dwordx4 v[220:221], off
	s_waitcnt vmcnt(8)
	s_waitcnt lgkmcnt(0)
	s_setprio 1
	s_barrier
	s_waitcnt lgkmcnt(0)
	v_mfma_f32_16x16x32_bf16 v[60:63], v[150:153], v[182:185], v[60:63]
	v_mfma_f32_16x16x32_bf16 v[56:59], v[158:161], v[182:185], v[56:59]
	v_mfma_f32_16x16x32_bf16 v[52:55], v[150:153], v[190:193], v[52:55]
	v_mfma_f32_16x16x32_bf16 v[48:51], v[158:161], v[190:193], v[48:51]
	v_mfma_f32_16x16x32_bf16 v[36:39], v[150:153], v[198:201], v[36:39]
	v_mfma_f32_16x16x32_bf16 v[32:35], v[158:161], v[198:201], v[32:35]
	v_mfma_f32_16x16x32_bf16 v[20:23], v[150:153], v[206:209], v[20:23]
	v_mfma_f32_16x16x32_bf16 v[16:19], v[158:161], v[206:209], v[16:19]
	v_mfma_f32_16x16x32_bf16 v[60:63], v[154:157], v[186:189], v[60:63]
	v_mfma_f32_16x16x32_bf16 v[56:59], v[162:165], v[186:189], v[56:59]
	v_mfma_f32_16x16x32_bf16 v[52:55], v[154:157], v[194:197], v[52:55]
	v_mfma_f32_16x16x32_bf16 v[48:51], v[162:165], v[194:197], v[48:51]
	v_mfma_f32_16x16x32_bf16 v[36:39], v[154:157], v[202:205], v[36:39]
	v_mfma_f32_16x16x32_bf16 v[32:35], v[162:165], v[202:205], v[32:35]
	v_mfma_f32_16x16x32_bf16 v[20:23], v[154:157], v[210:213], v[20:23]
	v_mfma_f32_16x16x32_bf16 v[16:19], v[162:165], v[210:213], v[16:19]
	s_setprio 0
	s_setprio 1
	v_mfma_f32_16x16x32_bf16 v[44:47], v[166:169], v[182:185], v[44:47]
	v_mfma_f32_16x16x32_bf16 v[40:43], v[174:177], v[182:185], v[40:43]
	v_mfma_f32_16x16x32_bf16 v[28:31], v[166:169], v[190:193], v[28:31]
	v_mfma_f32_16x16x32_bf16 v[24:27], v[174:177], v[190:193], v[24:27]
	v_mfma_f32_16x16x32_bf16 v[12:15], v[166:169], v[198:201], v[12:15]
	v_mfma_f32_16x16x32_bf16 v[8:11], v[174:177], v[198:201], v[8:11]
	v_mfma_f32_16x16x32_bf16 v[4:7], v[166:169], v[206:209], v[4:7]
	v_mfma_f32_16x16x32_bf16 v[0:3], v[174:177], v[206:209], v[0:3]
	v_mfma_f32_16x16x32_bf16 v[44:47], v[170:173], v[186:189], v[44:47]
	v_mfma_f32_16x16x32_bf16 v[40:43], v[178:181], v[186:189], v[40:43]
	v_mfma_f32_16x16x32_bf16 v[28:31], v[170:173], v[194:197], v[28:31]
	v_mfma_f32_16x16x32_bf16 v[24:27], v[178:181], v[194:197], v[24:27]
	v_mfma_f32_16x16x32_bf16 v[12:15], v[170:173], v[202:205], v[12:15]
	v_mfma_f32_16x16x32_bf16 v[8:11], v[178:181], v[202:205], v[8:11]
	v_mfma_f32_16x16x32_bf16 v[4:7], v[170:173], v[210:213], v[4:7]
	v_mfma_f32_16x16x32_bf16 v[0:3], v[178:181], v[210:213], v[0:3]
	s_setprio 0
	s_barrier
	s_add_i32 s62, 0, 0x18000
	s_add_i32 s63, 0, 0x1c000
	v_add_u32_e32 v162, s62, v145
	v_add_u32_e32 v178, s63, v145
	ds_read_b128 v[150:153], v162
	ds_read_b128 v[154:157], v162 offset:1024
	ds_read_b128 v[158:161], v162 offset:2048
	ds_read_b128 v[162:165], v162 offset:3072
	ds_read_b128 v[166:169], v178
	ds_read_b128 v[170:173], v178 offset:1024
	ds_read_b128 v[174:177], v178 offset:2048
	ds_read_b128 v[178:181], v178 offset:3072
	s_add_u32 s40, s40, 0x40000
	s_addc_u32 s41, s41, 0
	s_mov_b32 m0, s44
	v_lshl_add_u64 v[222:223], s[40:41], 0, v[134:135]
	ds_read_b128 v[182:185], v149 offset:32768
	ds_read_b128 v[186:189], v149 offset:33792
	ds_read_b128 v[190:193], v149 offset:34816
	ds_read_b128 v[194:197], v149 offset:35840
	ds_read_b128 v[198:201], v149 offset:36864
	ds_read_b128 v[202:205], v149 offset:37888
	ds_read_b128 v[206:209], v149 offset:38912
	ds_read_b128 v[210:213], v149 offset:39936
	global_load_lds_dwordx4 v[222:223], off
	v_lshl_add_u64 v[222:223], s[40:41], 0, v[130:131]
	s_mov_b32 m0, s45
	s_nop 0
	global_load_lds_dwordx4 v[222:223], off
	s_waitcnt vmcnt(8)
	s_waitcnt lgkmcnt(0)
	s_setprio 1
	s_barrier
	s_waitcnt lgkmcnt(0)
	v_mfma_f32_16x16x32_bf16 v[124:127], v[150:153], v[182:185], v[124:127]
	v_mfma_f32_16x16x32_bf16 v[120:123], v[158:161], v[182:185], v[120:123]
	v_mfma_f32_16x16x32_bf16 v[116:119], v[150:153], v[190:193], v[116:119]
	v_mfma_f32_16x16x32_bf16 v[112:115], v[158:161], v[190:193], v[112:115]
	v_mfma_f32_16x16x32_bf16 v[100:103], v[150:153], v[198:201], v[100:103]
	v_mfma_f32_16x16x32_bf16 v[96:99], v[158:161], v[198:201], v[96:99]
	v_mfma_f32_16x16x32_bf16 v[84:87], v[150:153], v[206:209], v[84:87]
	v_mfma_f32_16x16x32_bf16 v[80:83], v[158:161], v[206:209], v[80:83]
	v_mfma_f32_16x16x32_bf16 v[124:127], v[154:157], v[186:189], v[124:127]
	v_mfma_f32_16x16x32_bf16 v[120:123], v[162:165], v[186:189], v[120:123]
	v_mfma_f32_16x16x32_bf16 v[116:119], v[154:157], v[194:197], v[116:119]
	v_mfma_f32_16x16x32_bf16 v[112:115], v[162:165], v[194:197], v[112:115]
	v_mfma_f32_16x16x32_bf16 v[100:103], v[154:157], v[202:205], v[100:103]
	v_mfma_f32_16x16x32_bf16 v[96:99], v[162:165], v[202:205], v[96:99]
	v_mfma_f32_16x16x32_bf16 v[84:87], v[154:157], v[210:213], v[84:87]
	v_mfma_f32_16x16x32_bf16 v[80:83], v[162:165], v[210:213], v[80:83]
	s_setprio 0
	s_setprio 1
	v_mfma_f32_16x16x32_bf16 v[108:111], v[166:169], v[182:185], v[108:111]
	v_mfma_f32_16x16x32_bf16 v[104:107], v[174:177], v[182:185], v[104:107]
	v_mfma_f32_16x16x32_bf16 v[92:95], v[166:169], v[190:193], v[92:95]
	v_mfma_f32_16x16x32_bf16 v[88:91], v[174:177], v[190:193], v[88:91]
	v_mfma_f32_16x16x32_bf16 v[76:79], v[166:169], v[198:201], v[76:79]
	v_mfma_f32_16x16x32_bf16 v[72:75], v[174:177], v[198:201], v[72:75]
	v_mfma_f32_16x16x32_bf16 v[68:71], v[166:169], v[206:209], v[68:71]
	v_mfma_f32_16x16x32_bf16 v[64:67], v[174:177], v[206:209], v[64:67]
	v_mfma_f32_16x16x32_bf16 v[108:111], v[170:173], v[186:189], v[108:111]
	v_mfma_f32_16x16x32_bf16 v[104:107], v[178:181], v[186:189], v[104:107]
	v_mfma_f32_16x16x32_bf16 v[92:95], v[170:173], v[194:197], v[92:95]
	v_mfma_f32_16x16x32_bf16 v[88:91], v[178:181], v[194:197], v[88:91]
	v_mfma_f32_16x16x32_bf16 v[76:79], v[170:173], v[202:205], v[76:79]
	v_mfma_f32_16x16x32_bf16 v[72:75], v[178:181], v[202:205], v[72:75]
	v_mfma_f32_16x16x32_bf16 v[68:71], v[170:173], v[210:213], v[68:71]
	v_mfma_f32_16x16x32_bf16 v[64:67], v[178:181], v[210:213], v[64:67]
	s_setprio 0
	s_barrier
	s_add_i32 s40, s62, s33
	v_lshl_add_u64 v[214:215], v[214:215], 0, s[16:17]
	s_mov_b32 m0, s40
	ds_read_b128 v[182:185], v149 offset:49152
	ds_read_b128 v[186:189], v149 offset:50176
	ds_read_b128 v[190:193], v149 offset:51200
	ds_read_b128 v[194:197], v149 offset:52224
	ds_read_b128 v[198:201], v149 offset:53248
	ds_read_b128 v[202:205], v149 offset:54272
	ds_read_b128 v[206:209], v149 offset:55296
	ds_read_b128 v[210:213], v149 offset:56320
	global_load_lds_dwordx4 v[214:215], off
	s_add_i32 m0, s40, 0x2000
	s_add_u32 s38, s38, 0x40080
	v_lshl_add_u64 v[214:215], v[216:217], 0, s[16:17]
	s_addc_u32 s39, s39, 0
	s_add_i32 s40, s63, s33
	global_load_lds_dwordx4 v[214:215], off
	v_lshl_add_u64 v[214:215], s[38:39], 0, v[132:133]
	s_mov_b32 m0, s40
	s_nop 0
	global_load_lds_dwordx4 v[214:215], off
	v_lshl_add_u64 v[214:215], s[38:39], 0, v[128:129]
	s_add_i32 m0, s40, 0x2000
	s_nop 0
	global_load_lds_dwordx4 v[214:215], off
	v_lshl_add_u64 v[214:215], v[218:219], 0, s[16:17]
	s_mov_b32 m0, s47
	s_nop 0
	global_load_lds_dwordx4 v[214:215], off
	v_lshl_add_u64 v[214:215], v[220:221], 0, s[16:17]
	s_mov_b32 m0, s48
	s_nop 0
	global_load_lds_dwordx4 v[214:215], off
	s_waitcnt vmcnt(8)
	s_waitcnt lgkmcnt(0)
	s_setprio 1
	s_barrier
	s_waitcnt lgkmcnt(0)
	v_mfma_f32_16x16x32_bf16 v[60:63], v[150:153], v[182:185], v[60:63]
	v_mfma_f32_16x16x32_bf16 v[56:59], v[158:161], v[182:185], v[56:59]
	v_mfma_f32_16x16x32_bf16 v[52:55], v[150:153], v[190:193], v[52:55]
	v_mfma_f32_16x16x32_bf16 v[48:51], v[158:161], v[190:193], v[48:51]
	v_mfma_f32_16x16x32_bf16 v[36:39], v[150:153], v[198:201], v[36:39]
	v_mfma_f32_16x16x32_bf16 v[32:35], v[158:161], v[198:201], v[32:35]
	v_mfma_f32_16x16x32_bf16 v[20:23], v[150:153], v[206:209], v[20:23]
	v_mfma_f32_16x16x32_bf16 v[16:19], v[158:161], v[206:209], v[16:19]
	v_mfma_f32_16x16x32_bf16 v[60:63], v[154:157], v[186:189], v[60:63]
	v_mfma_f32_16x16x32_bf16 v[56:59], v[162:165], v[186:189], v[56:59]
	v_mfma_f32_16x16x32_bf16 v[52:55], v[154:157], v[194:197], v[52:55]
	v_mfma_f32_16x16x32_bf16 v[48:51], v[162:165], v[194:197], v[48:51]
	v_mfma_f32_16x16x32_bf16 v[36:39], v[154:157], v[202:205], v[36:39]
	v_mfma_f32_16x16x32_bf16 v[32:35], v[162:165], v[202:205], v[32:35]
	v_mfma_f32_16x16x32_bf16 v[20:23], v[154:157], v[210:213], v[20:23]
	v_mfma_f32_16x16x32_bf16 v[16:19], v[162:165], v[210:213], v[16:19]
	s_setprio 0
	s_setprio 1
	v_mfma_f32_16x16x32_bf16 v[44:47], v[166:169], v[182:185], v[44:47]
	v_mfma_f32_16x16x32_bf16 v[40:43], v[174:177], v[182:185], v[40:43]
	v_mfma_f32_16x16x32_bf16 v[28:31], v[166:169], v[190:193], v[28:31]
	v_mfma_f32_16x16x32_bf16 v[24:27], v[174:177], v[190:193], v[24:27]
	v_mfma_f32_16x16x32_bf16 v[12:15], v[166:169], v[198:201], v[12:15]
	v_mfma_f32_16x16x32_bf16 v[8:11], v[174:177], v[198:201], v[8:11]
	v_mfma_f32_16x16x32_bf16 v[4:7], v[166:169], v[206:209], v[4:7]
	v_mfma_f32_16x16x32_bf16 v[0:3], v[174:177], v[206:209], v[0:3]
	v_mfma_f32_16x16x32_bf16 v[44:47], v[170:173], v[186:189], v[44:47]
	v_mfma_f32_16x16x32_bf16 v[40:43], v[178:181], v[186:189], v[40:43]
	v_mfma_f32_16x16x32_bf16 v[28:31], v[170:173], v[194:197], v[28:31]
	v_mfma_f32_16x16x32_bf16 v[24:27], v[178:181], v[194:197], v[24:27]
	v_mfma_f32_16x16x32_bf16 v[12:15], v[170:173], v[202:205], v[12:15]
	v_mfma_f32_16x16x32_bf16 v[8:11], v[178:181], v[202:205], v[8:11]
	v_mfma_f32_16x16x32_bf16 v[4:7], v[170:173], v[210:213], v[4:7]
	v_mfma_f32_16x16x32_bf16 v[0:3], v[178:181], v[210:213], v[0:3]
	s_setprio 0
	s_barrier
	s_add_i32 s61, s61, 2
	s_add_u32 s59, s59, 0x100
	s_addc_u32 s60, s60, 0
	s_add_u32 s36, s36, 0x100
	s_addc_u32 s37, s37, 0
	s_cmp_gt_u32 s61, 13
	s_cbranch_scc0 .LBB0_1801
	s_and_b64 vcc, exec, s[18:19]
	s_cbranch_vccz .LBB0_1804
	s_barrier

.LBB0_1949:
	ds_read_b128 v[152:155], v149
	ds_read_b128 v[156:159], v149 offset:1024
	ds_read_b128 v[160:163], v149 offset:2048
	ds_read_b128 v[164:167], v149 offset:3072
	ds_read_b128 v[168:171], v150
	ds_read_b128 v[172:175], v150 offset:1024
	ds_read_b128 v[176:179], v150 offset:2048
	ds_read_b128 v[180:183], v150 offset:3072
	s_add_u32 s28, s26, 0xfffc0080
	s_addc_u32 s29, s27, -1
	s_cmp_eq_u32 s49, 12
	s_cselect_b32 s31, s21, s29
	s_cselect_b32 s30, s45, s28
	s_cselect_b32 s29, s19, s48
	s_cselect_b32 s28, s46, s47
	v_lshl_add_u64 v[144:145], s[26:27], 0, v[138:139]
	s_add_i32 m0, s34, 0xc000
	ds_read_b128 v[184:187], v151
	ds_read_b128 v[188:191], v151 offset:1024
	ds_read_b128 v[192:195], v151 offset:2048
	ds_read_b128 v[196:199], v151 offset:3072
	ds_read_b128 v[200:203], v151 offset:4096
	ds_read_b128 v[204:207], v151 offset:5120
	ds_read_b128 v[208:211], v151 offset:6144
	ds_read_b128 v[212:215], v151 offset:7168
	global_load_lds_dwordx4 v[144:145], off
	v_lshl_add_u64 v[144:145], s[26:27], 0, v[136:137]
	s_add_i32 m0, s34, 0xe000
	s_nop 0
	global_load_lds_dwordx4 v[144:145], off
	s_waitcnt vmcnt(8)
	s_waitcnt lgkmcnt(0)
	s_setprio 1
	s_barrier
	s_waitcnt lgkmcnt(0)
	v_mfma_f32_16x16x32_bf16 v[124:127], v[152:155], v[184:187], v[124:127]
	v_mfma_f32_16x16x32_bf16 v[120:123], v[160:163], v[184:187], v[120:123]
	v_mfma_f32_16x16x32_bf16 v[108:111], v[152:155], v[192:195], v[108:111]
	v_mfma_f32_16x16x32_bf16 v[104:107], v[160:163], v[192:195], v[104:107]
	v_mfma_f32_16x16x32_bf16 v[92:95], v[152:155], v[200:203], v[92:95]
	v_mfma_f32_16x16x32_bf16 v[88:91], v[160:163], v[200:203], v[88:91]
	v_mfma_f32_16x16x32_bf16 v[76:79], v[152:155], v[208:211], v[76:79]
	v_mfma_f32_16x16x32_bf16 v[72:75], v[160:163], v[208:211], v[72:75]
	v_mfma_f32_16x16x32_bf16 v[124:127], v[156:159], v[188:191], v[124:127]
	v_mfma_f32_16x16x32_bf16 v[120:123], v[164:167], v[188:191], v[120:123]
	v_mfma_f32_16x16x32_bf16 v[108:111], v[156:159], v[196:199], v[108:111]
	v_mfma_f32_16x16x32_bf16 v[104:107], v[164:167], v[196:199], v[104:107]
	v_mfma_f32_16x16x32_bf16 v[92:95], v[156:159], v[204:207], v[92:95]
	v_mfma_f32_16x16x32_bf16 v[88:91], v[164:167], v[204:207], v[88:91]
	v_mfma_f32_16x16x32_bf16 v[76:79], v[156:159], v[212:215], v[76:79]
	v_mfma_f32_16x16x32_bf16 v[72:75], v[164:167], v[212:215], v[72:75]
	s_setprio 0
	s_setprio 1
	v_mfma_f32_16x16x32_bf16 v[116:119], v[168:171], v[184:187], v[116:119]
	v_mfma_f32_16x16x32_bf16 v[112:115], v[176:179], v[184:187], v[112:115]
	v_mfma_f32_16x16x32_bf16 v[100:103], v[168:171], v[192:195], v[100:103]
	v_mfma_f32_16x16x32_bf16 v[96:99], v[176:179], v[192:195], v[96:99]
	v_mfma_f32_16x16x32_bf16 v[84:87], v[168:171], v[200:203], v[84:87]
	v_mfma_f32_16x16x32_bf16 v[80:83], v[176:179], v[200:203], v[80:83]
	v_mfma_f32_16x16x32_bf16 v[68:71], v[168:171], v[208:211], v[68:71]
	v_mfma_f32_16x16x32_bf16 v[64:67], v[176:179], v[208:211], v[64:67]
	v_mfma_f32_16x16x32_bf16 v[116:119], v[172:175], v[188:191], v[116:119]
	v_mfma_f32_16x16x32_bf16 v[112:115], v[180:183], v[188:191], v[112:115]
	v_mfma_f32_16x16x32_bf16 v[100:103], v[172:175], v[196:199], v[100:103]
	v_mfma_f32_16x16x32_bf16 v[96:99], v[180:183], v[196:199], v[96:99]
	v_mfma_f32_16x16x32_bf16 v[84:87], v[172:175], v[204:207], v[84:87]
	v_mfma_f32_16x16x32_bf16 v[80:83], v[180:183], v[204:207], v[80:83]
	v_mfma_f32_16x16x32_bf16 v[68:71], v[172:175], v[212:215], v[68:71]
	v_mfma_f32_16x16x32_bf16 v[64:67], v[180:183], v[212:215], v[64:67]
	s_setprio 0
	s_barrier
	s_add_i32 s50, s42, s33
	v_lshl_add_u64 v[144:145], s[28:29], 0, v[132:133]
	s_mov_b32 m0, s50
	ds_read_b128 v[184:187], v151 offset:16384
	ds_read_b128 v[188:191], v151 offset:17408
	ds_read_b128 v[192:195], v151 offset:18432
	ds_read_b128 v[196:199], v151 offset:19456
	ds_read_b128 v[200:203], v151 offset:20480
	ds_read_b128 v[204:207], v151 offset:21504
	ds_read_b128 v[208:211], v151 offset:22528
	ds_read_b128 v[212:215], v151 offset:23552
	global_load_lds_dwordx4 v[144:145], off
	s_add_i32 m0, s50, 0x2000
	s_add_u32 s50, s28, 0x40000
	v_lshl_add_u64 v[216:217], s[28:29], 0, v[128:129]
	s_addc_u32 s51, s29, 0
	s_add_i32 s52, s43, s33
	global_load_lds_dwordx4 v[216:217], off
	v_lshl_add_u64 v[218:219], s[50:51], 0, v[132:133]
	s_mov_b32 m0, s52
	v_lshl_add_u64 v[220:221], s[30:31], 0, v[130:131]
	global_load_lds_dwordx4 v[218:219], off
	v_lshl_add_u64 v[218:219], s[50:51], 0, v[128:129]
	s_add_i32 m0, s52, 0x2000
	s_nop 0
	global_load_lds_dwordx4 v[218:219], off
	v_lshl_add_u64 v[218:219], s[30:31], 0, v[134:135]
	s_mov_b32 m0, s34
	s_nop 0
	global_load_lds_dwordx4 v[218:219], off
	s_mov_b32 m0, s35
	s_nop 0
	global_load_lds_dwordx4 v[220:221], off
	s_waitcnt vmcnt(8)
	s_waitcnt lgkmcnt(0)
	s_setprio 1
	s_barrier
	s_waitcnt lgkmcnt(0)
	v_mfma_f32_16x16x32_bf16 v[60:63], v[152:155], v[184:187], v[60:63]
	v_mfma_f32_16x16x32_bf16 v[56:59], v[160:163], v[184:187], v[56:59]
	v_mfma_f32_16x16x32_bf16 v[44:47], v[152:155], v[192:195], v[44:47]
	v_mfma_f32_16x16x32_bf16 v[40:43], v[160:163], v[192:195], v[40:43]
	v_mfma_f32_16x16x32_bf16 v[28:31], v[152:155], v[200:203], v[28:31]
	v_mfma_f32_16x16x32_bf16 v[24:27], v[160:163], v[200:203], v[24:27]
	v_mfma_f32_16x16x32_bf16 v[12:15], v[152:155], v[208:211], v[12:15]
	v_mfma_f32_16x16x32_bf16 v[8:11], v[160:163], v[208:211], v[8:11]
	v_mfma_f32_16x16x32_bf16 v[60:63], v[156:159], v[188:191], v[60:63]
	v_mfma_f32_16x16x32_bf16 v[56:59], v[164:167], v[188:191], v[56:59]
	v_mfma_f32_16x16x32_bf16 v[44:47], v[156:159], v[196:199], v[44:47]
	v_mfma_f32_16x16x32_bf16 v[40:43], v[164:167], v[196:199], v[40:43]
	v_mfma_f32_16x16x32_bf16 v[28:31], v[156:159], v[204:207], v[28:31]
	v_mfma_f32_16x16x32_bf16 v[24:27], v[164:167], v[204:207], v[24:27]
	v_mfma_f32_16x16x32_bf16 v[12:15], v[156:159], v[212:215], v[12:15]
	v_mfma_f32_16x16x32_bf16 v[8:11], v[164:167], v[212:215], v[8:11]
	s_setprio 0
	s_setprio 1
	v_mfma_f32_16x16x32_bf16 v[52:55], v[168:171], v[184:187], v[52:55]
	v_mfma_f32_16x16x32_bf16 v[48:51], v[176:179], v[184:187], v[48:51]
	v_mfma_f32_16x16x32_bf16 v[36:39], v[168:171], v[192:195], v[36:39]
	v_mfma_f32_16x16x32_bf16 v[32:35], v[176:179], v[192:195], v[32:35]
	v_mfma_f32_16x16x32_bf16 v[20:23], v[168:171], v[200:203], v[20:23]
	v_mfma_f32_16x16x32_bf16 v[16:19], v[176:179], v[200:203], v[16:19]
	v_mfma_f32_16x16x32_bf16 v[4:7], v[168:171], v[208:211], v[4:7]
	v_mfma_f32_16x16x32_bf16 v[0:3], v[176:179], v[208:211], v[0:3]
	v_mfma_f32_16x16x32_bf16 v[52:55], v[172:175], v[188:191], v[52:55]
	v_mfma_f32_16x16x32_bf16 v[48:51], v[180:183], v[188:191], v[48:51]
	v_mfma_f32_16x16x32_bf16 v[36:39], v[172:175], v[196:199], v[36:39]
	v_mfma_f32_16x16x32_bf16 v[32:35], v[180:183], v[196:199], v[32:35]
	v_mfma_f32_16x16x32_bf16 v[20:23], v[172:175], v[204:207], v[20:23]
	v_mfma_f32_16x16x32_bf16 v[16:19], v[180:183], v[204:207], v[16:19]
	v_mfma_f32_16x16x32_bf16 v[4:7], v[172:175], v[212:215], v[4:7]
	v_mfma_f32_16x16x32_bf16 v[0:3], v[180:183], v[212:215], v[0:3]
	s_setprio 0
	s_barrier
	s_add_i32 s50, 0, 0x18000
	s_add_i32 s51, 0, 0x1c000
	v_add_u32_e32 v164, s50, v147
	v_add_u32_e32 v180, s51, v147
	ds_read_b128 v[152:155], v164
	ds_read_b128 v[156:159], v164 offset:1024
	ds_read_b128 v[160:163], v164 offset:2048
	ds_read_b128 v[164:167], v164 offset:3072
	ds_read_b128 v[168:171], v180
	ds_read_b128 v[172:175], v180 offset:1024
	ds_read_b128 v[176:179], v180 offset:2048
	ds_read_b128 v[180:183], v180 offset:3072
	s_add_u32 s30, s30, 0x40000
	s_addc_u32 s31, s31, 0
	s_mov_b32 m0, s36
	v_lshl_add_u64 v[222:223], s[30:31], 0, v[134:135]
	ds_read_b128 v[184:187], v151 offset:32768
	ds_read_b128 v[188:191], v151 offset:33792
	ds_read_b128 v[192:195], v151 offset:34816
	ds_read_b128 v[196:199], v151 offset:35840
	ds_read_b128 v[200:203], v151 offset:36864
	ds_read_b128 v[204:207], v151 offset:37888
	ds_read_b128 v[208:211], v151 offset:38912
	ds_read_b128 v[212:215], v151 offset:39936
	global_load_lds_dwordx4 v[222:223], off
	v_lshl_add_u64 v[222:223], s[30:31], 0, v[130:131]
	s_mov_b32 m0, s37
	s_nop 0
	global_load_lds_dwordx4 v[222:223], off
	s_waitcnt vmcnt(8)
	s_waitcnt lgkmcnt(0)
	s_setprio 1
	s_barrier
	s_waitcnt lgkmcnt(0)
	v_mfma_f32_16x16x32_bf16 v[124:127], v[152:155], v[184:187], v[124:127]
	v_mfma_f32_16x16x32_bf16 v[120:123], v[160:163], v[184:187], v[120:123]
	v_mfma_f32_16x16x32_bf16 v[108:111], v[152:155], v[192:195], v[108:111]
	v_mfma_f32_16x16x32_bf16 v[104:107], v[160:163], v[192:195], v[104:107]
	v_mfma_f32_16x16x32_bf16 v[92:95], v[152:155], v[200:203], v[92:95]
	v_mfma_f32_16x16x32_bf16 v[88:91], v[160:163], v[200:203], v[88:91]
	v_mfma_f32_16x16x32_bf16 v[76:79], v[152:155], v[208:211], v[76:79]
	v_mfma_f32_16x16x32_bf16 v[72:75], v[160:163], v[208:211], v[72:75]
	v_mfma_f32_16x16x32_bf16 v[124:127], v[156:159], v[188:191], v[124:127]
	v_mfma_f32_16x16x32_bf16 v[120:123], v[164:167], v[188:191], v[120:123]
	v_mfma_f32_16x16x32_bf16 v[108:111], v[156:159], v[196:199], v[108:111]
	v_mfma_f32_16x16x32_bf16 v[104:107], v[164:167], v[196:199], v[104:107]
	v_mfma_f32_16x16x32_bf16 v[92:95], v[156:159], v[204:207], v[92:95]
	v_mfma_f32_16x16x32_bf16 v[88:91], v[164:167], v[204:207], v[88:91]
	v_mfma_f32_16x16x32_bf16 v[76:79], v[156:159], v[212:215], v[76:79]
	v_mfma_f32_16x16x32_bf16 v[72:75], v[164:167], v[212:215], v[72:75]
	s_setprio 0
	s_setprio 1
	v_mfma_f32_16x16x32_bf16 v[116:119], v[168:171], v[184:187], v[116:119]
	v_mfma_f32_16x16x32_bf16 v[112:115], v[176:179], v[184:187], v[112:115]
	v_mfma_f32_16x16x32_bf16 v[100:103], v[168:171], v[192:195], v[100:103]
	v_mfma_f32_16x16x32_bf16 v[96:99], v[176:179], v[192:195], v[96:99]
	v_mfma_f32_16x16x32_bf16 v[84:87], v[168:171], v[200:203], v[84:87]
	v_mfma_f32_16x16x32_bf16 v[80:83], v[176:179], v[200:203], v[80:83]
	v_mfma_f32_16x16x32_bf16 v[68:71], v[168:171], v[208:211], v[68:71]
	v_mfma_f32_16x16x32_bf16 v[64:67], v[176:179], v[208:211], v[64:67]
	v_mfma_f32_16x16x32_bf16 v[116:119], v[172:175], v[188:191], v[116:119]
	v_mfma_f32_16x16x32_bf16 v[112:115], v[180:183], v[188:191], v[112:115]
	v_mfma_f32_16x16x32_bf16 v[100:103], v[172:175], v[196:199], v[100:103]
	v_mfma_f32_16x16x32_bf16 v[96:99], v[180:183], v[196:199], v[96:99]
	v_mfma_f32_16x16x32_bf16 v[84:87], v[172:175], v[204:207], v[84:87]
	v_mfma_f32_16x16x32_bf16 v[80:83], v[180:183], v[204:207], v[80:83]
	v_mfma_f32_16x16x32_bf16 v[68:71], v[172:175], v[212:215], v[68:71]
	v_mfma_f32_16x16x32_bf16 v[64:67], v[180:183], v[212:215], v[64:67]
	s_setprio 0
	s_barrier
	s_add_i32 s30, s50, s33
	v_lshl_add_u64 v[144:145], v[144:145], 0, s[14:15]
	s_mov_b32 m0, s30
	ds_read_b128 v[184:187], v151 offset:49152
	ds_read_b128 v[188:191], v151 offset:50176
	ds_read_b128 v[192:195], v151 offset:51200
	ds_read_b128 v[196:199], v151 offset:52224
	ds_read_b128 v[200:203], v151 offset:53248
	ds_read_b128 v[204:207], v151 offset:54272
	ds_read_b128 v[208:211], v151 offset:55296
	ds_read_b128 v[212:215], v151 offset:56320
	global_load_lds_dwordx4 v[144:145], off
	s_add_i32 m0, s30, 0x2000
	s_add_u32 s28, s28, 0x40080
	v_lshl_add_u64 v[144:145], v[216:217], 0, s[14:15]
	s_addc_u32 s29, s29, 0
	s_add_i32 s30, s51, s33
	global_load_lds_dwordx4 v[144:145], off
	v_lshl_add_u64 v[144:145], s[28:29], 0, v[132:133]
	s_mov_b32 m0, s30
	s_nop 0
	global_load_lds_dwordx4 v[144:145], off
	v_lshl_add_u64 v[144:145], s[28:29], 0, v[128:129]
	s_add_i32 m0, s30, 0x2000
	s_nop 0
	global_load_lds_dwordx4 v[144:145], off
	v_lshl_add_u64 v[144:145], v[218:219], 0, s[14:15]
	s_mov_b32 m0, s39
	s_nop 0
	global_load_lds_dwordx4 v[144:145], off
	v_lshl_add_u64 v[144:145], v[220:221], 0, s[14:15]
	s_mov_b32 m0, s40
	s_nop 0
	global_load_lds_dwordx4 v[144:145], off
	s_waitcnt vmcnt(8)
	s_waitcnt lgkmcnt(0)
	s_setprio 1
	s_barrier
	s_waitcnt lgkmcnt(0)
	v_mfma_f32_16x16x32_bf16 v[60:63], v[152:155], v[184:187], v[60:63]
	v_mfma_f32_16x16x32_bf16 v[56:59], v[160:163], v[184:187], v[56:59]
	v_mfma_f32_16x16x32_bf16 v[44:47], v[152:155], v[192:195], v[44:47]
	v_mfma_f32_16x16x32_bf16 v[40:43], v[160:163], v[192:195], v[40:43]
	v_mfma_f32_16x16x32_bf16 v[28:31], v[152:155], v[200:203], v[28:31]
	v_mfma_f32_16x16x32_bf16 v[24:27], v[160:163], v[200:203], v[24:27]
	v_mfma_f32_16x16x32_bf16 v[12:15], v[152:155], v[208:211], v[12:15]
	v_mfma_f32_16x16x32_bf16 v[8:11], v[160:163], v[208:211], v[8:11]
	v_mfma_f32_16x16x32_bf16 v[60:63], v[156:159], v[188:191], v[60:63]
	v_mfma_f32_16x16x32_bf16 v[56:59], v[164:167], v[188:191], v[56:59]
	v_mfma_f32_16x16x32_bf16 v[44:47], v[156:159], v[196:199], v[44:47]
	v_mfma_f32_16x16x32_bf16 v[40:43], v[164:167], v[196:199], v[40:43]
	v_mfma_f32_16x16x32_bf16 v[28:31], v[156:159], v[204:207], v[28:31]
	v_mfma_f32_16x16x32_bf16 v[24:27], v[164:167], v[204:207], v[24:27]
	v_mfma_f32_16x16x32_bf16 v[12:15], v[156:159], v[212:215], v[12:15]
	v_mfma_f32_16x16x32_bf16 v[8:11], v[164:167], v[212:215], v[8:11]
	s_setprio 0
	s_setprio 1
	v_mfma_f32_16x16x32_bf16 v[52:55], v[168:171], v[184:187], v[52:55]
	v_mfma_f32_16x16x32_bf16 v[48:51], v[176:179], v[184:187], v[48:51]
	v_mfma_f32_16x16x32_bf16 v[36:39], v[168:171], v[192:195], v[36:39]
	v_mfma_f32_16x16x32_bf16 v[32:35], v[176:179], v[192:195], v[32:35]
	v_mfma_f32_16x16x32_bf16 v[20:23], v[168:171], v[200:203], v[20:23]
	v_mfma_f32_16x16x32_bf16 v[16:19], v[176:179], v[200:203], v[16:19]
	v_mfma_f32_16x16x32_bf16 v[4:7], v[168:171], v[208:211], v[4:7]
	v_mfma_f32_16x16x32_bf16 v[0:3], v[176:179], v[208:211], v[0:3]
	v_mfma_f32_16x16x32_bf16 v[52:55], v[172:175], v[188:191], v[52:55]
	v_mfma_f32_16x16x32_bf16 v[48:51], v[180:183], v[188:191], v[48:51]
	v_mfma_f32_16x16x32_bf16 v[36:39], v[172:175], v[196:199], v[36:39]
	v_mfma_f32_16x16x32_bf16 v[32:35], v[180:183], v[196:199], v[32:35]
	v_mfma_f32_16x16x32_bf16 v[20:23], v[172:175], v[204:207], v[20:23]
	v_mfma_f32_16x16x32_bf16 v[16:19], v[180:183], v[204:207], v[16:19]
	v_mfma_f32_16x16x32_bf16 v[4:7], v[172:175], v[212:215], v[4:7]
	v_mfma_f32_16x16x32_bf16 v[0:3], v[180:183], v[212:215], v[0:3]
	s_setprio 0
	s_barrier
	s_add_i32 s49, s49, 2
	s_add_u32 s47, s47, 0x100
	s_addc_u32 s48, s48, 0
	s_add_u32 s26, s26, 0x100
	s_addc_u32 s27, s27, 0
	s_cmp_gt_u32 s49, 13
	s_cbranch_scc0 .LBB0_1949
	s_and_b64 vcc, exec, s[16:17]
	s_cbranch_vccz .LBB0_1952
	s_barrier

.LBB0_2021:
	ds_read_b128 v[150:153], v147
	ds_read_b128 v[154:157], v147 offset:1024
	ds_read_b128 v[158:161], v147 offset:2048
	ds_read_b128 v[162:165], v147 offset:3072
	ds_read_b128 v[166:169], v148
	ds_read_b128 v[170:173], v148 offset:1024
	ds_read_b128 v[174:177], v148 offset:2048
	ds_read_b128 v[178:181], v148 offset:3072
	s_add_u32 s34, s30, 0x100
	s_addc_u32 s35, s31, 0
	s_cmp_eq_u32 s57, 40
	s_cselect_b32 s39, s11, s35
	s_cselect_b32 s38, s10, s34
	s_cselect_b32 s37, s29, s56
	s_cselect_b32 s36, s28, s55
	v_lshl_add_u64 v[214:215], s[30:31], 0, v[138:139]
	s_add_i32 m0, s40, 0xc000
	ds_read_b128 v[182:185], v149
	ds_read_b128 v[186:189], v149 offset:1024
	ds_read_b128 v[190:193], v149 offset:2048
	ds_read_b128 v[194:197], v149 offset:3072
	ds_read_b128 v[198:201], v149 offset:4096
	ds_read_b128 v[202:205], v149 offset:5120
	ds_read_b128 v[206:209], v149 offset:6144
	ds_read_b128 v[210:213], v149 offset:7168
	global_load_lds_dwordx4 v[214:215], off
	v_lshl_add_u64 v[214:215], s[30:31], 0, v[136:137]
	s_add_i32 m0, s40, 0xe000
	s_nop 0
	global_load_lds_dwordx4 v[214:215], off
	s_waitcnt vmcnt(8)
	s_waitcnt lgkmcnt(0)
	s_setprio 1
	s_barrier
	s_waitcnt lgkmcnt(0)
	v_mfma_f32_16x16x32_bf16 v[124:127], v[150:153], v[182:185], v[124:127]
	v_mfma_f32_16x16x32_bf16 v[120:123], v[158:161], v[182:185], v[120:123]
	v_mfma_f32_16x16x32_bf16 v[116:119], v[150:153], v[190:193], v[116:119]
	v_mfma_f32_16x16x32_bf16 v[112:115], v[158:161], v[190:193], v[112:115]
	v_mfma_f32_16x16x32_bf16 v[100:103], v[150:153], v[198:201], v[100:103]
	v_mfma_f32_16x16x32_bf16 v[96:99], v[158:161], v[198:201], v[96:99]
	v_mfma_f32_16x16x32_bf16 v[84:87], v[150:153], v[206:209], v[84:87]
	v_mfma_f32_16x16x32_bf16 v[80:83], v[158:161], v[206:209], v[80:83]
	v_mfma_f32_16x16x32_bf16 v[124:127], v[154:157], v[186:189], v[124:127]
	v_mfma_f32_16x16x32_bf16 v[120:123], v[162:165], v[186:189], v[120:123]
	v_mfma_f32_16x16x32_bf16 v[116:119], v[154:157], v[194:197], v[116:119]
	v_mfma_f32_16x16x32_bf16 v[112:115], v[162:165], v[194:197], v[112:115]
	v_mfma_f32_16x16x32_bf16 v[100:103], v[154:157], v[202:205], v[100:103]
	v_mfma_f32_16x16x32_bf16 v[96:99], v[162:165], v[202:205], v[96:99]
	v_mfma_f32_16x16x32_bf16 v[84:87], v[154:157], v[210:213], v[84:87]
	v_mfma_f32_16x16x32_bf16 v[80:83], v[162:165], v[210:213], v[80:83]
	s_setprio 0
	s_setprio 1
	v_mfma_f32_16x16x32_bf16 v[108:111], v[166:169], v[182:185], v[108:111]
	v_mfma_f32_16x16x32_bf16 v[104:107], v[174:177], v[182:185], v[104:107]
	v_mfma_f32_16x16x32_bf16 v[92:95], v[166:169], v[190:193], v[92:95]
	v_mfma_f32_16x16x32_bf16 v[88:91], v[174:177], v[190:193], v[88:91]
	v_mfma_f32_16x16x32_bf16 v[76:79], v[166:169], v[198:201], v[76:79]
	v_mfma_f32_16x16x32_bf16 v[72:75], v[174:177], v[198:201], v[72:75]
	v_mfma_f32_16x16x32_bf16 v[68:71], v[166:169], v[206:209], v[68:71]
	v_mfma_f32_16x16x32_bf16 v[64:67], v[174:177], v[206:209], v[64:67]
	v_mfma_f32_16x16x32_bf16 v[108:111], v[170:173], v[186:189], v[108:111]
	v_mfma_f32_16x16x32_bf16 v[104:107], v[178:181], v[186:189], v[104:107]
	v_mfma_f32_16x16x32_bf16 v[92:95], v[170:173], v[194:197], v[92:95]
	v_mfma_f32_16x16x32_bf16 v[88:91], v[178:181], v[194:197], v[88:91]
	v_mfma_f32_16x16x32_bf16 v[76:79], v[170:173], v[202:205], v[76:79]
	v_mfma_f32_16x16x32_bf16 v[72:75], v[178:181], v[202:205], v[72:75]
	v_mfma_f32_16x16x32_bf16 v[68:71], v[170:173], v[210:213], v[68:71]
	v_mfma_f32_16x16x32_bf16 v[64:67], v[178:181], v[210:213], v[64:67]
	s_setprio 0
	s_barrier
	s_add_i32 s30, s47, s33
	v_lshl_add_u64 v[214:215], s[36:37], 0, v[132:133]
	s_mov_b32 m0, s30
	ds_read_b128 v[182:185], v149 offset:16384
	ds_read_b128 v[186:189], v149 offset:17408
	ds_read_b128 v[190:193], v149 offset:18432
	ds_read_b128 v[194:197], v149 offset:19456
	ds_read_b128 v[198:201], v149 offset:20480
	ds_read_b128 v[202:205], v149 offset:21504
	ds_read_b128 v[206:209], v149 offset:22528
	ds_read_b128 v[210:213], v149 offset:23552
	global_load_lds_dwordx4 v[214:215], off
	s_add_i32 m0, s30, 0x2000
	s_add_u32 s30, s36, 0xb0000
	v_lshl_add_u64 v[216:217], s[36:37], 0, v[128:129]
	s_addc_u32 s31, s37, 0
	s_add_i32 s58, s48, s33
	global_load_lds_dwordx4 v[216:217], off
	v_lshl_add_u64 v[218:219], s[30:31], 0, v[132:133]
	s_mov_b32 m0, s58
	v_lshl_add_u64 v[220:221], s[38:39], 0, v[130:131]
	global_load_lds_dwordx4 v[218:219], off
	v_lshl_add_u64 v[218:219], s[30:31], 0, v[128:129]
	s_add_i32 m0, s58, 0x2000
	s_nop 0
	global_load_lds_dwordx4 v[218:219], off
	v_lshl_add_u64 v[218:219], s[38:39], 0, v[134:135]
	s_mov_b32 m0, s40
	s_nop 0
	global_load_lds_dwordx4 v[218:219], off
	s_mov_b32 m0, s41
	s_nop 0
	global_load_lds_dwordx4 v[220:221], off
	s_waitcnt vmcnt(8)
	s_waitcnt lgkmcnt(0)
	s_setprio 1
	s_barrier
	s_waitcnt lgkmcnt(0)
	v_mfma_f32_16x16x32_bf16 v[60:63], v[150:153], v[182:185], v[60:63]
	v_mfma_f32_16x16x32_bf16 v[56:59], v[158:161], v[182:185], v[56:59]
	v_mfma_f32_16x16x32_bf16 v[52:55], v[150:153], v[190:193], v[52:55]
	v_mfma_f32_16x16x32_bf16 v[48:51], v[158:161], v[190:193], v[48:51]
	v_mfma_f32_16x16x32_bf16 v[36:39], v[150:153], v[198:201], v[36:39]
	v_mfma_f32_16x16x32_bf16 v[32:35], v[158:161], v[198:201], v[32:35]
	v_mfma_f32_16x16x32_bf16 v[20:23], v[150:153], v[206:209], v[20:23]
	v_mfma_f32_16x16x32_bf16 v[16:19], v[158:161], v[206:209], v[16:19]
	v_mfma_f32_16x16x32_bf16 v[60:63], v[154:157], v[186:189], v[60:63]
	v_mfma_f32_16x16x32_bf16 v[56:59], v[162:165], v[186:189], v[56:59]
	v_mfma_f32_16x16x32_bf16 v[52:55], v[154:157], v[194:197], v[52:55]
	v_mfma_f32_16x16x32_bf16 v[48:51], v[162:165], v[194:197], v[48:51]
	v_mfma_f32_16x16x32_bf16 v[36:39], v[154:157], v[202:205], v[36:39]
	v_mfma_f32_16x16x32_bf16 v[32:35], v[162:165], v[202:205], v[32:35]
	v_mfma_f32_16x16x32_bf16 v[20:23], v[154:157], v[210:213], v[20:23]
	v_mfma_f32_16x16x32_bf16 v[16:19], v[162:165], v[210:213], v[16:19]
	s_setprio 0
	s_setprio 1
	v_mfma_f32_16x16x32_bf16 v[44:47], v[166:169], v[182:185], v[44:47]
	v_mfma_f32_16x16x32_bf16 v[40:43], v[174:177], v[182:185], v[40:43]
	v_mfma_f32_16x16x32_bf16 v[28:31], v[166:169], v[190:193], v[28:31]
	v_mfma_f32_16x16x32_bf16 v[24:27], v[174:177], v[190:193], v[24:27]
	v_mfma_f32_16x16x32_bf16 v[12:15], v[166:169], v[198:201], v[12:15]
	v_mfma_f32_16x16x32_bf16 v[8:11], v[174:177], v[198:201], v[8:11]
	v_mfma_f32_16x16x32_bf16 v[4:7], v[166:169], v[206:209], v[4:7]
	v_mfma_f32_16x16x32_bf16 v[0:3], v[174:177], v[206:209], v[0:3]
	v_mfma_f32_16x16x32_bf16 v[44:47], v[170:173], v[186:189], v[44:47]
	v_mfma_f32_16x16x32_bf16 v[40:43], v[178:181], v[186:189], v[40:43]
	v_mfma_f32_16x16x32_bf16 v[28:31], v[170:173], v[194:197], v[28:31]
	v_mfma_f32_16x16x32_bf16 v[24:27], v[178:181], v[194:197], v[24:27]
	v_mfma_f32_16x16x32_bf16 v[12:15], v[170:173], v[202:205], v[12:15]
	v_mfma_f32_16x16x32_bf16 v[8:11], v[178:181], v[202:205], v[8:11]
	v_mfma_f32_16x16x32_bf16 v[4:7], v[170:173], v[210:213], v[4:7]
	v_mfma_f32_16x16x32_bf16 v[0:3], v[178:181], v[210:213], v[0:3]
	s_setprio 0
	s_barrier
	s_add_i32 s58, 0, 0x18000
	s_add_i32 s59, 0, 0x1c000
	v_add_u32_e32 v162, s58, v145
	v_add_u32_e32 v178, s59, v145
	ds_read_b128 v[150:153], v162
	ds_read_b128 v[154:157], v162 offset:1024
	ds_read_b128 v[158:161], v162 offset:2048
	ds_read_b128 v[162:165], v162 offset:3072
	ds_read_b128 v[166:169], v178
	ds_read_b128 v[170:173], v178 offset:1024
	ds_read_b128 v[174:177], v178 offset:2048
	ds_read_b128 v[178:181], v178 offset:3072
	s_add_u32 s30, s38, 0xb0000
	s_addc_u32 s31, s39, 0
	s_mov_b32 m0, s42
	v_lshl_add_u64 v[222:223], s[30:31], 0, v[134:135]
	ds_read_b128 v[182:185], v149 offset:32768
	ds_read_b128 v[186:189], v149 offset:33792
	ds_read_b128 v[190:193], v149 offset:34816
	ds_read_b128 v[194:197], v149 offset:35840
	ds_read_b128 v[198:201], v149 offset:36864
	ds_read_b128 v[202:205], v149 offset:37888
	ds_read_b128 v[206:209], v149 offset:38912
	ds_read_b128 v[210:213], v149 offset:39936
	global_load_lds_dwordx4 v[222:223], off
	v_lshl_add_u64 v[222:223], s[30:31], 0, v[130:131]
	s_mov_b32 m0, s43
	s_nop 0
	global_load_lds_dwordx4 v[222:223], off
	s_waitcnt vmcnt(8)
	s_waitcnt lgkmcnt(0)
	s_setprio 1
	s_barrier
	s_waitcnt lgkmcnt(0)
	v_mfma_f32_16x16x32_bf16 v[124:127], v[150:153], v[182:185], v[124:127]
	v_mfma_f32_16x16x32_bf16 v[120:123], v[158:161], v[182:185], v[120:123]
	v_mfma_f32_16x16x32_bf16 v[116:119], v[150:153], v[190:193], v[116:119]
	v_mfma_f32_16x16x32_bf16 v[112:115], v[158:161], v[190:193], v[112:115]
	v_mfma_f32_16x16x32_bf16 v[100:103], v[150:153], v[198:201], v[100:103]
	v_mfma_f32_16x16x32_bf16 v[96:99], v[158:161], v[198:201], v[96:99]
	v_mfma_f32_16x16x32_bf16 v[84:87], v[150:153], v[206:209], v[84:87]
	v_mfma_f32_16x16x32_bf16 v[80:83], v[158:161], v[206:209], v[80:83]
	v_mfma_f32_16x16x32_bf16 v[124:127], v[154:157], v[186:189], v[124:127]
	v_mfma_f32_16x16x32_bf16 v[120:123], v[162:165], v[186:189], v[120:123]
	v_mfma_f32_16x16x32_bf16 v[116:119], v[154:157], v[194:197], v[116:119]
	v_mfma_f32_16x16x32_bf16 v[112:115], v[162:165], v[194:197], v[112:115]
	v_mfma_f32_16x16x32_bf16 v[100:103], v[154:157], v[202:205], v[100:103]
	v_mfma_f32_16x16x32_bf16 v[96:99], v[162:165], v[202:205], v[96:99]
	v_mfma_f32_16x16x32_bf16 v[84:87], v[154:157], v[210:213], v[84:87]
	v_mfma_f32_16x16x32_bf16 v[80:83], v[162:165], v[210:213], v[80:83]
	s_setprio 0
	s_setprio 1
	v_mfma_f32_16x16x32_bf16 v[108:111], v[166:169], v[182:185], v[108:111]
	v_mfma_f32_16x16x32_bf16 v[104:107], v[174:177], v[182:185], v[104:107]
	v_mfma_f32_16x16x32_bf16 v[92:95], v[166:169], v[190:193], v[92:95]
	v_mfma_f32_16x16x32_bf16 v[88:91], v[174:177], v[190:193], v[88:91]
	v_mfma_f32_16x16x32_bf16 v[76:79], v[166:169], v[198:201], v[76:79]
	v_mfma_f32_16x16x32_bf16 v[72:75], v[174:177], v[198:201], v[72:75]
	v_mfma_f32_16x16x32_bf16 v[68:71], v[166:169], v[206:209], v[68:71]
	v_mfma_f32_16x16x32_bf16 v[64:67], v[174:177], v[206:209], v[64:67]
	v_mfma_f32_16x16x32_bf16 v[108:111], v[170:173], v[186:189], v[108:111]
	v_mfma_f32_16x16x32_bf16 v[104:107], v[178:181], v[186:189], v[104:107]
	v_mfma_f32_16x16x32_bf16 v[92:95], v[170:173], v[194:197], v[92:95]
	v_mfma_f32_16x16x32_bf16 v[88:91], v[178:181], v[194:197], v[88:91]
	v_mfma_f32_16x16x32_bf16 v[76:79], v[170:173], v[202:205], v[76:79]
	v_mfma_f32_16x16x32_bf16 v[72:75], v[178:181], v[202:205], v[72:75]
	v_mfma_f32_16x16x32_bf16 v[68:71], v[170:173], v[210:213], v[68:71]
	v_mfma_f32_16x16x32_bf16 v[64:67], v[178:181], v[210:213], v[64:67]
	s_setprio 0
	s_barrier
	s_add_i32 s30, s58, s33
	v_lshl_add_u64 v[214:215], v[214:215], 0, s[16:17]
	s_mov_b32 m0, s30
	ds_read_b128 v[182:185], v149 offset:49152
	ds_read_b128 v[186:189], v149 offset:50176
	ds_read_b128 v[190:193], v149 offset:51200
	ds_read_b128 v[194:197], v149 offset:52224
	ds_read_b128 v[198:201], v149 offset:53248
	ds_read_b128 v[202:205], v149 offset:54272
	ds_read_b128 v[206:209], v149 offset:55296
	ds_read_b128 v[210:213], v149 offset:56320
	global_load_lds_dwordx4 v[214:215], off
	s_add_i32 m0, s30, 0x2000
	s_add_u32 s30, s36, 0xb0080
	v_lshl_add_u64 v[214:215], v[216:217], 0, s[16:17]
	s_addc_u32 s31, s37, 0
	s_add_i32 s36, s59, s33
	global_load_lds_dwordx4 v[214:215], off
	v_lshl_add_u64 v[214:215], s[30:31], 0, v[132:133]
	s_mov_b32 m0, s36
	s_nop 0
	global_load_lds_dwordx4 v[214:215], off
	v_lshl_add_u64 v[214:215], s[30:31], 0, v[128:129]
	s_add_i32 m0, s36, 0x2000
	s_nop 0
	global_load_lds_dwordx4 v[214:215], off
	v_lshl_add_u64 v[214:215], v[218:219], 0, s[16:17]
	s_mov_b32 m0, s45
	s_nop 0
	global_load_lds_dwordx4 v[214:215], off
	v_lshl_add_u64 v[214:215], v[220:221], 0, s[16:17]
	s_mov_b32 m0, s46
	s_nop 0
	global_load_lds_dwordx4 v[214:215], off
	s_waitcnt vmcnt(8)
	s_waitcnt lgkmcnt(0)
	s_setprio 1
	s_barrier
	s_waitcnt lgkmcnt(0)
	v_mfma_f32_16x16x32_bf16 v[60:63], v[150:153], v[182:185], v[60:63]
	v_mfma_f32_16x16x32_bf16 v[56:59], v[158:161], v[182:185], v[56:59]
	v_mfma_f32_16x16x32_bf16 v[52:55], v[150:153], v[190:193], v[52:55]
	v_mfma_f32_16x16x32_bf16 v[48:51], v[158:161], v[190:193], v[48:51]
	v_mfma_f32_16x16x32_bf16 v[36:39], v[150:153], v[198:201], v[36:39]
	v_mfma_f32_16x16x32_bf16 v[32:35], v[158:161], v[198:201], v[32:35]
	v_mfma_f32_16x16x32_bf16 v[20:23], v[150:153], v[206:209], v[20:23]
	v_mfma_f32_16x16x32_bf16 v[16:19], v[158:161], v[206:209], v[16:19]
	v_mfma_f32_16x16x32_bf16 v[60:63], v[154:157], v[186:189], v[60:63]
	v_mfma_f32_16x16x32_bf16 v[56:59], v[162:165], v[186:189], v[56:59]
	v_mfma_f32_16x16x32_bf16 v[52:55], v[154:157], v[194:197], v[52:55]
	v_mfma_f32_16x16x32_bf16 v[48:51], v[162:165], v[194:197], v[48:51]
	v_mfma_f32_16x16x32_bf16 v[36:39], v[154:157], v[202:205], v[36:39]
	v_mfma_f32_16x16x32_bf16 v[32:35], v[162:165], v[202:205], v[32:35]
	v_mfma_f32_16x16x32_bf16 v[20:23], v[154:157], v[210:213], v[20:23]
	v_mfma_f32_16x16x32_bf16 v[16:19], v[162:165], v[210:213], v[16:19]
	s_setprio 0
	s_setprio 1
	v_mfma_f32_16x16x32_bf16 v[44:47], v[166:169], v[182:185], v[44:47]
	v_mfma_f32_16x16x32_bf16 v[40:43], v[174:177], v[182:185], v[40:43]
	v_mfma_f32_16x16x32_bf16 v[28:31], v[166:169], v[190:193], v[28:31]
	v_mfma_f32_16x16x32_bf16 v[24:27], v[174:177], v[190:193], v[24:27]
	v_mfma_f32_16x16x32_bf16 v[12:15], v[166:169], v[198:201], v[12:15]
	v_mfma_f32_16x16x32_bf16 v[8:11], v[174:177], v[198:201], v[8:11]
	v_mfma_f32_16x16x32_bf16 v[4:7], v[166:169], v[206:209], v[4:7]
	v_mfma_f32_16x16x32_bf16 v[0:3], v[174:177], v[206:209], v[0:3]
	v_mfma_f32_16x16x32_bf16 v[44:47], v[170:173], v[186:189], v[44:47]
	v_mfma_f32_16x16x32_bf16 v[40:43], v[178:181], v[186:189], v[40:43]
	v_mfma_f32_16x16x32_bf16 v[28:31], v[170:173], v[194:197], v[28:31]
	v_mfma_f32_16x16x32_bf16 v[24:27], v[178:181], v[194:197], v[24:27]
	v_mfma_f32_16x16x32_bf16 v[12:15], v[170:173], v[202:205], v[12:15]
	v_mfma_f32_16x16x32_bf16 v[8:11], v[178:181], v[202:205], v[8:11]
	v_mfma_f32_16x16x32_bf16 v[4:7], v[170:173], v[210:213], v[4:7]
	v_mfma_f32_16x16x32_bf16 v[0:3], v[178:181], v[210:213], v[0:3]
	s_setprio 0
	s_barrier
	s_add_i32 s57, s57, 2
	s_add_u32 s55, s55, 0x100
	s_addc_u32 s56, s56, 0
	s_cmp_gt_u32 s57, 41
	s_mov_b64 s[30:31], s[34:35]
	s_cbranch_scc0 .LBB0_2021
	s_and_b64 vcc, exec, s[18:19]
	s_cbranch_vccz .LBB0_2024
	s_barrier

.LBB0_2196:
	ds_read_b128 v[0:3], v161
	ds_read_b128 v[4:7], v161 offset:1024
	ds_read_b128 v[8:11], v161 offset:2048
	ds_read_b128 v[12:15], v161 offset:3072
	ds_read_b128 v[16:19], v162
	ds_read_b128 v[20:23], v162 offset:1024
	ds_read_b128 v[24:27], v162 offset:2048
	ds_read_b128 v[28:31], v162 offset:3072
	s_ashr_i32 s35, s34, 31
	s_lshl_b64 s[36:37], s[34:35], 17
	s_add_u32 s36, s8, s36
	s_addc_u32 s37, s9, s37
	s_and_b64 s[38:39], s[6:7], exec
	s_cselect_b32 s49, s37, s43
	s_cselect_b32 s48, s36, s42
	s_ashr_i32 s31, s30, 31
	s_lshl_b64 s[38:39], s[30:31], 17
	s_add_u32 s38, s4, s38
	s_addc_u32 s39, s5, s39
	s_and_b64 s[46:47], s[6:7], exec
	s_cselect_b32 s47, s39, s45
	s_cselect_b32 s46, s38, s44
	s_add_u32 s64, s42, 0x10080
	s_addc_u32 s65, s43, 0
	s_mov_b32 m0, s56
	v_lshl_add_u64 v[64:65], s[64:65], 0, v[140:141]
	ds_read_b128 v[32:35], v163
	ds_read_b128 v[36:39], v163 offset:1024
	ds_read_b128 v[40:43], v163 offset:2048
	ds_read_b128 v[44:47], v163 offset:3072
	ds_read_b128 v[48:51], v163 offset:4096
	ds_read_b128 v[52:55], v163 offset:5120
	ds_read_b128 v[56:59], v163 offset:6144
	ds_read_b128 v[60:63], v163 offset:7168
	global_load_lds_dwordx4 v[64:65], off
	v_lshl_add_u64 v[64:65], s[64:65], 0, v[144:145]
	s_mov_b32 m0, s57
	s_nop 0
	global_load_lds_dwordx4 v[64:65], off
	s_waitcnt vmcnt(8)
	s_waitcnt lgkmcnt(0)
	s_setprio 1
	s_barrier
	s_waitcnt lgkmcnt(0)
	v_mfma_f32_16x16x32_bf16 v[64:67], v[0:3], v[32:35], 0
	v_mfma_f32_16x16x32_bf16 v[68:71], v[8:11], v[32:35], 0
	v_mfma_f32_16x16x32_bf16 v[72:75], v[0:3], v[40:43], 0
	v_mfma_f32_16x16x32_bf16 v[76:79], v[8:11], v[40:43], 0
	v_mfma_f32_16x16x32_bf16 v[80:83], v[0:3], v[48:51], 0
	v_mfma_f32_16x16x32_bf16 v[84:87], v[8:11], v[48:51], 0
	v_mfma_f32_16x16x32_bf16 v[88:91], v[0:3], v[56:59], 0
	v_mfma_f32_16x16x32_bf16 v[92:95], v[8:11], v[56:59], 0
	v_mfma_f32_16x16x32_bf16 v[64:67], v[4:7], v[36:39], v[64:67]
	v_mfma_f32_16x16x32_bf16 v[68:71], v[12:15], v[36:39], v[68:71]
	v_mfma_f32_16x16x32_bf16 v[72:75], v[4:7], v[44:47], v[72:75]
	v_mfma_f32_16x16x32_bf16 v[76:79], v[12:15], v[44:47], v[76:79]
	v_mfma_f32_16x16x32_bf16 v[80:83], v[4:7], v[52:55], v[80:83]
	v_mfma_f32_16x16x32_bf16 v[84:87], v[12:15], v[52:55], v[84:87]
	v_mfma_f32_16x16x32_bf16 v[88:91], v[4:7], v[60:63], v[88:91]
	v_mfma_f32_16x16x32_bf16 v[92:95], v[12:15], v[60:63], v[92:95]
	s_setprio 0
	s_setprio 1
	v_mfma_f32_16x16x32_bf16 v[96:99], v[16:19], v[32:35], 0
	v_mfma_f32_16x16x32_bf16 v[32:35], v[24:27], v[32:35], 0
	v_mfma_f32_16x16x32_bf16 v[96:99], v[20:23], v[36:39], v[96:99]
	v_mfma_f32_16x16x32_bf16 v[32:35], v[28:31], v[36:39], v[32:35]
	v_mfma_f32_16x16x32_bf16 v[36:39], v[16:19], v[40:43], 0
	v_mfma_f32_16x16x32_bf16 v[40:43], v[24:27], v[40:43], 0
	v_mfma_f32_16x16x32_bf16 v[36:39], v[20:23], v[44:47], v[36:39]
	v_mfma_f32_16x16x32_bf16 v[40:43], v[28:31], v[44:47], v[40:43]
	v_mfma_f32_16x16x32_bf16 v[44:47], v[16:19], v[48:51], 0
	v_mfma_f32_16x16x32_bf16 v[48:51], v[24:27], v[48:51], 0
	v_mfma_f32_16x16x32_bf16 v[44:47], v[20:23], v[52:55], v[44:47]
	v_mfma_f32_16x16x32_bf16 v[48:51], v[28:31], v[52:55], v[48:51]
	v_mfma_f32_16x16x32_bf16 v[52:55], v[16:19], v[56:59], 0
	v_mfma_f32_16x16x32_bf16 v[56:59], v[24:27], v[56:59], 0
	v_mfma_f32_16x16x32_bf16 v[52:55], v[20:23], v[60:63], v[52:55]
	v_mfma_f32_16x16x32_bf16 v[56:59], v[28:31], v[60:63], v[56:59]
	s_setprio 0
	s_barrier
	s_add_i32 s64, s3, s33
	v_lshl_add_u64 v[156:157], s[44:45], 0, v[142:143]
	s_add_i32 s31, s64, 0x2000
	v_lshl_add_u64 v[128:129], v[156:157], 0, s[18:19]
	s_mov_b32 m0, s64
	v_lshl_add_u64 v[212:213], s[44:45], 0, v[146:147]
	s_add_u32 s66, s44, 0x10100
	ds_read_b128 v[60:63], v163 offset:16384
	ds_read_b128 v[100:103], v163 offset:17408
	ds_read_b128 v[104:107], v163 offset:18432
	ds_read_b128 v[108:111], v163 offset:19456
	ds_read_b128 v[112:115], v163 offset:20480
	ds_read_b128 v[116:119], v163 offset:21504
	ds_read_b128 v[120:123], v163 offset:22528
	ds_read_b128 v[124:127], v163 offset:23552
	global_load_lds_dwordx4 v[128:129], off
	v_lshl_add_u64 v[128:129], v[212:213], 0, s[18:19]
	s_mov_b32 m0, s31
	s_addc_u32 s67, s45, 0
	s_add_i32 s35, s55, s33
	global_load_lds_dwordx4 v[128:129], off
	v_lshl_add_u64 v[128:129], s[66:67], 0, v[142:143]
	s_mov_b32 m0, s35
	s_add_i32 s63, s35, 0x2000
	global_load_lds_dwordx4 v[128:129], off
	v_lshl_add_u64 v[128:129], s[66:67], 0, v[146:147]
	s_mov_b32 m0, s63
	v_lshl_add_u64 v[214:215], s[42:43], 0, v[140:141]
	global_load_lds_dwordx4 v[128:129], off
	v_lshl_add_u64 v[128:129], v[214:215], 0, s[18:19]
	s_mov_b32 m0, s41
	v_lshl_add_u64 v[216:217], s[42:43], 0, v[144:145]
	global_load_lds_dwordx4 v[128:129], off
	v_lshl_add_u64 v[128:129], v[216:217], 0, s[18:19]
	s_mov_b32 m0, s50
	s_nop 0
	global_load_lds_dwordx4 v[128:129], off
	s_waitcnt vmcnt(8)
	s_waitcnt lgkmcnt(0)
	s_setprio 1
	s_barrier
	s_waitcnt lgkmcnt(0)
	v_mfma_f32_16x16x32_bf16 v[128:131], v[0:3], v[60:63], 0
	v_mfma_f32_16x16x32_bf16 v[136:139], v[0:3], v[104:107], 0
	v_mfma_f32_16x16x32_bf16 v[164:167], v[0:3], v[112:115], 0
	v_mfma_f32_16x16x32_bf16 v[0:3], v[0:3], v[120:123], 0
	v_mfma_f32_16x16x32_bf16 v[128:131], v[4:7], v[100:103], v[128:131]
	v_mfma_f32_16x16x32_bf16 v[136:139], v[4:7], v[108:111], v[136:139]
	v_mfma_f32_16x16x32_bf16 v[164:167], v[4:7], v[116:119], v[164:167]
	v_mfma_f32_16x16x32_bf16 v[0:3], v[4:7], v[124:127], v[0:3]
	v_mfma_f32_16x16x32_bf16 v[4:7], v[8:11], v[120:123], 0
	v_mfma_f32_16x16x32_bf16 v[132:135], v[8:11], v[60:63], 0
	v_mfma_f32_16x16x32_bf16 v[152:155], v[8:11], v[104:107], 0
	v_mfma_f32_16x16x32_bf16 v[168:171], v[8:11], v[112:115], 0
	v_mfma_f32_16x16x32_bf16 v[4:7], v[12:15], v[124:127], v[4:7]
	v_mfma_f32_16x16x32_bf16 v[132:135], v[12:15], v[100:103], v[132:135]
	v_mfma_f32_16x16x32_bf16 v[152:155], v[12:15], v[108:111], v[152:155]
	v_mfma_f32_16x16x32_bf16 v[168:171], v[12:15], v[116:119], v[168:171]
	s_setprio 0
	s_setprio 1
	v_mfma_f32_16x16x32_bf16 v[8:11], v[16:19], v[60:63], 0
	v_mfma_f32_16x16x32_bf16 v[12:15], v[24:27], v[60:63], 0
	v_mfma_f32_16x16x32_bf16 v[8:11], v[20:23], v[100:103], v[8:11]
	v_mfma_f32_16x16x32_bf16 v[12:15], v[28:31], v[100:103], v[12:15]
	v_mfma_f32_16x16x32_bf16 v[60:63], v[16:19], v[104:107], 0
	v_mfma_f32_16x16x32_bf16 v[100:103], v[24:27], v[104:107], 0
	v_mfma_f32_16x16x32_bf16 v[104:107], v[16:19], v[112:115], 0
	v_mfma_f32_16x16x32_bf16 v[16:19], v[16:19], v[120:123], 0
	v_mfma_f32_16x16x32_bf16 v[60:63], v[20:23], v[108:111], v[60:63]
	v_mfma_f32_16x16x32_bf16 v[100:103], v[28:31], v[108:111], v[100:103]
	v_mfma_f32_16x16x32_bf16 v[104:107], v[20:23], v[116:119], v[104:107]
	v_mfma_f32_16x16x32_bf16 v[108:111], v[24:27], v[112:115], 0
	v_mfma_f32_16x16x32_bf16 v[16:19], v[20:23], v[124:127], v[16:19]
	v_mfma_f32_16x16x32_bf16 v[20:23], v[24:27], v[120:123], 0
	v_mfma_f32_16x16x32_bf16 v[108:111], v[28:31], v[116:119], v[108:111]
	v_mfma_f32_16x16x32_bf16 v[20:23], v[28:31], v[124:127], v[20:23]
	s_setprio 0
	s_barrier
	s_add_i32 s65, 0, 0x18000
	s_add_i32 s70, 0, 0x1c000
	v_add_u32_e32 v224, s65, v159
	v_add_u32_e32 v228, s70, v159
	ds_read_b128 v[24:27], v224
	ds_read_b128 v[28:31], v224 offset:1024
	ds_read_b128 v[112:115], v224 offset:2048
	ds_read_b128 v[116:119], v224 offset:3072
	ds_read_b128 v[120:123], v228
	ds_read_b128 v[124:127], v228 offset:1024
	ds_read_b128 v[172:175], v228 offset:2048
	ds_read_b128 v[176:179], v228 offset:3072
	s_add_u32 s66, s42, 0x10100
	s_addc_u32 s67, s43, 0
	s_mov_b32 m0, s51
	v_lshl_add_u64 v[218:219], s[66:67], 0, v[140:141]
	ds_read_b128 v[180:183], v163 offset:32768
	ds_read_b128 v[184:187], v163 offset:33792
	ds_read_b128 v[188:191], v163 offset:34816
	ds_read_b128 v[192:195], v163 offset:35840
	ds_read_b128 v[196:199], v163 offset:36864
	ds_read_b128 v[200:203], v163 offset:37888
	ds_read_b128 v[204:207], v163 offset:38912
	ds_read_b128 v[208:211], v163 offset:39936
	global_load_lds_dwordx4 v[218:219], off
	v_lshl_add_u64 v[218:219], s[66:67], 0, v[144:145]
	s_mov_b32 m0, s52
	s_nop 0
	global_load_lds_dwordx4 v[218:219], off
	s_waitcnt vmcnt(8)
	s_waitcnt lgkmcnt(0)
	s_setprio 1
	s_barrier
	s_waitcnt lgkmcnt(0)
	v_mfma_f32_16x16x32_bf16 v[64:67], v[24:27], v[180:183], v[64:67]
	v_mfma_f32_16x16x32_bf16 v[68:71], v[112:115], v[180:183], v[68:71]
	v_mfma_f32_16x16x32_bf16 v[72:75], v[24:27], v[188:191], v[72:75]
	v_mfma_f32_16x16x32_bf16 v[76:79], v[112:115], v[188:191], v[76:79]
	v_mfma_f32_16x16x32_bf16 v[80:83], v[24:27], v[196:199], v[80:83]
	v_mfma_f32_16x16x32_bf16 v[84:87], v[112:115], v[196:199], v[84:87]
	v_mfma_f32_16x16x32_bf16 v[88:91], v[24:27], v[204:207], v[88:91]
	v_mfma_f32_16x16x32_bf16 v[92:95], v[112:115], v[204:207], v[92:95]
	v_mfma_f32_16x16x32_bf16 v[64:67], v[28:31], v[184:187], v[64:67]
	v_mfma_f32_16x16x32_bf16 v[68:71], v[116:119], v[184:187], v[68:71]
	v_mfma_f32_16x16x32_bf16 v[72:75], v[28:31], v[192:195], v[72:75]
	v_mfma_f32_16x16x32_bf16 v[76:79], v[116:119], v[192:195], v[76:79]
	v_mfma_f32_16x16x32_bf16 v[80:83], v[28:31], v[200:203], v[80:83]
	v_mfma_f32_16x16x32_bf16 v[84:87], v[116:119], v[200:203], v[84:87]
	v_mfma_f32_16x16x32_bf16 v[88:91], v[28:31], v[208:211], v[88:91]
	v_mfma_f32_16x16x32_bf16 v[92:95], v[116:119], v[208:211], v[92:95]
	s_setprio 0
	s_setprio 1
	v_mfma_f32_16x16x32_bf16 v[96:99], v[120:123], v[180:183], v[96:99]
	v_mfma_f32_16x16x32_bf16 v[32:35], v[172:175], v[180:183], v[32:35]
	v_mfma_f32_16x16x32_bf16 v[36:39], v[120:123], v[188:191], v[36:39]
	v_mfma_f32_16x16x32_bf16 v[40:43], v[172:175], v[188:191], v[40:43]
	v_mfma_f32_16x16x32_bf16 v[44:47], v[120:123], v[196:199], v[44:47]
	v_mfma_f32_16x16x32_bf16 v[48:51], v[172:175], v[196:199], v[48:51]
	v_mfma_f32_16x16x32_bf16 v[52:55], v[120:123], v[204:207], v[52:55]
	v_mfma_f32_16x16x32_bf16 v[56:59], v[172:175], v[204:207], v[56:59]
	v_mfma_f32_16x16x32_bf16 v[96:99], v[124:127], v[184:187], v[96:99]
	v_mfma_f32_16x16x32_bf16 v[32:35], v[176:179], v[184:187], v[32:35]
	v_mfma_f32_16x16x32_bf16 v[36:39], v[124:127], v[192:195], v[36:39]
	v_mfma_f32_16x16x32_bf16 v[40:43], v[176:179], v[192:195], v[40:43]
	v_mfma_f32_16x16x32_bf16 v[44:47], v[124:127], v[200:203], v[44:47]
	v_mfma_f32_16x16x32_bf16 v[48:51], v[176:179], v[200:203], v[48:51]
	v_mfma_f32_16x16x32_bf16 v[52:55], v[124:127], v[208:211], v[52:55]
	v_mfma_f32_16x16x32_bf16 v[56:59], v[176:179], v[208:211], v[56:59]
	s_setprio 0
	s_barrier
	s_add_i32 s66, s65, s33
	s_add_i32 s65, s66, 0x2000
	v_lshl_add_u64 v[156:157], v[156:157], 0, s[20:21]
	s_mov_b32 m0, s66
	s_add_u32 s68, s44, 0x10180
	ds_read_b128 v[180:183], v163 offset:49152
	ds_read_b128 v[184:187], v163 offset:50176
	ds_read_b128 v[188:191], v163 offset:51200
	ds_read_b128 v[192:195], v163 offset:52224
	ds_read_b128 v[196:199], v163 offset:53248
	ds_read_b128 v[200:203], v163 offset:54272
	ds_read_b128 v[204:207], v163 offset:55296
	ds_read_b128 v[208:211], v163 offset:56320
	global_load_lds_dwordx4 v[156:157], off
	v_lshl_add_u64 v[156:157], v[212:213], 0, s[20:21]
	s_mov_b32 m0, s65
	s_addc_u32 s69, s45, 0
	s_add_i32 s44, s70, s33
	global_load_lds_dwordx4 v[156:157], off
	v_lshl_add_u64 v[156:157], s[68:69], 0, v[142:143]
	s_mov_b32 m0, s44
	s_add_i32 s45, s44, 0x2000
	global_load_lds_dwordx4 v[156:157], off
	v_lshl_add_u64 v[156:157], s[68:69], 0, v[146:147]
	s_mov_b32 m0, s45
	s_nop 0
	global_load_lds_dwordx4 v[156:157], off
	v_lshl_add_u64 v[156:157], v[214:215], 0, s[20:21]
	s_mov_b32 m0, s53
	s_nop 0
	global_load_lds_dwordx4 v[156:157], off
	v_lshl_add_u64 v[156:157], v[216:217], 0, s[20:21]
	s_mov_b32 m0, s54
	s_nop 0
	global_load_lds_dwordx4 v[156:157], off
	s_waitcnt vmcnt(8)
	s_waitcnt lgkmcnt(0)
	s_setprio 1
	s_barrier
	s_waitcnt lgkmcnt(0)
	v_mfma_f32_16x16x32_bf16 v[0:3], v[24:27], v[204:207], v[0:3]
	v_mfma_f32_16x16x32_bf16 v[4:7], v[112:115], v[204:207], v[4:7]
	v_mfma_f32_16x16x32_bf16 v[128:131], v[24:27], v[180:183], v[128:131]
	v_mfma_f32_16x16x32_bf16 v[132:135], v[112:115], v[180:183], v[132:135]
	v_mfma_f32_16x16x32_bf16 v[136:139], v[24:27], v[188:191], v[136:139]
	v_mfma_f32_16x16x32_bf16 v[152:155], v[112:115], v[188:191], v[152:155]
	v_mfma_f32_16x16x32_bf16 v[164:167], v[24:27], v[196:199], v[164:167]
	v_mfma_f32_16x16x32_bf16 v[168:171], v[112:115], v[196:199], v[168:171]
	v_mfma_f32_16x16x32_bf16 v[0:3], v[28:31], v[208:211], v[0:3]
	v_mfma_f32_16x16x32_bf16 v[4:7], v[116:119], v[208:211], v[4:7]
	v_mfma_f32_16x16x32_bf16 v[128:131], v[28:31], v[184:187], v[128:131]
	v_mfma_f32_16x16x32_bf16 v[132:135], v[116:119], v[184:187], v[132:135]
	v_mfma_f32_16x16x32_bf16 v[136:139], v[28:31], v[192:195], v[136:139]
	v_mfma_f32_16x16x32_bf16 v[152:155], v[116:119], v[192:195], v[152:155]
	v_mfma_f32_16x16x32_bf16 v[164:167], v[28:31], v[200:203], v[164:167]
	v_mfma_f32_16x16x32_bf16 v[168:171], v[116:119], v[200:203], v[168:171]
	s_setprio 0
	s_setprio 1
	v_mfma_f32_16x16x32_bf16 v[8:11], v[120:123], v[180:183], v[8:11]
	v_mfma_f32_16x16x32_bf16 v[12:15], v[172:175], v[180:183], v[12:15]
	v_mfma_f32_16x16x32_bf16 v[24:27], v[120:123], v[188:191], v[60:63]
	v_mfma_f32_16x16x32_bf16 v[28:31], v[172:175], v[188:191], v[100:103]
	v_mfma_f32_16x16x32_bf16 v[60:63], v[120:123], v[196:199], v[104:107]
	v_mfma_f32_16x16x32_bf16 v[100:103], v[172:175], v[196:199], v[108:111]
	v_mfma_f32_16x16x32_bf16 v[16:19], v[120:123], v[204:207], v[16:19]
	v_mfma_f32_16x16x32_bf16 v[20:23], v[172:175], v[204:207], v[20:23]
	v_mfma_f32_16x16x32_bf16 v[8:11], v[124:127], v[184:187], v[8:11]
	v_mfma_f32_16x16x32_bf16 v[12:15], v[176:179], v[184:187], v[12:15]
	v_mfma_f32_16x16x32_bf16 v[24:27], v[124:127], v[192:195], v[24:27]
	v_mfma_f32_16x16x32_bf16 v[28:31], v[176:179], v[192:195], v[28:31]
	v_mfma_f32_16x16x32_bf16 v[60:63], v[124:127], v[200:203], v[60:63]
	v_mfma_f32_16x16x32_bf16 v[100:103], v[176:179], v[200:203], v[100:103]
	v_mfma_f32_16x16x32_bf16 v[16:19], v[124:127], v[208:211], v[16:19]
	v_mfma_f32_16x16x32_bf16 v[20:23], v[176:179], v[208:211], v[20:23]
	s_setprio 0
	s_barrier
	ds_read_b128 v[104:107], v161
	ds_read_b128 v[108:111], v161 offset:1024
	ds_read_b128 v[112:115], v161 offset:2048
	ds_read_b128 v[116:119], v161 offset:3072
	ds_read_b128 v[120:123], v162
	ds_read_b128 v[124:127], v162 offset:1024
	ds_read_b128 v[172:175], v162 offset:2048
	ds_read_b128 v[176:179], v162 offset:3072
	s_add_u32 s42, s42, 0x10180
	s_addc_u32 s43, s43, 0
	s_mov_b32 m0, s56
	v_lshl_add_u64 v[156:157], s[42:43], 0, v[140:141]
	ds_read_b128 v[180:183], v163
	ds_read_b128 v[184:187], v163 offset:1024
	ds_read_b128 v[188:191], v163 offset:2048
	ds_read_b128 v[192:195], v163 offset:3072
	ds_read_b128 v[196:199], v163 offset:4096
	ds_read_b128 v[200:203], v163 offset:5120
	ds_read_b128 v[204:207], v163 offset:6144
	ds_read_b128 v[208:211], v163 offset:7168
	global_load_lds_dwordx4 v[156:157], off
	v_lshl_add_u64 v[156:157], s[42:43], 0, v[144:145]
	s_mov_b32 m0, s57
	s_nop 0
	global_load_lds_dwordx4 v[156:157], off
	s_waitcnt vmcnt(8)
	s_waitcnt lgkmcnt(0)
	s_setprio 1
	s_barrier
	s_waitcnt lgkmcnt(0)
	v_mfma_f32_16x16x32_bf16 v[64:67], v[104:107], v[180:183], v[64:67]
	v_mfma_f32_16x16x32_bf16 v[68:71], v[112:115], v[180:183], v[68:71]
	v_mfma_f32_16x16x32_bf16 v[72:75], v[104:107], v[188:191], v[72:75]
	v_mfma_f32_16x16x32_bf16 v[76:79], v[112:115], v[188:191], v[76:79]
	v_mfma_f32_16x16x32_bf16 v[80:83], v[104:107], v[196:199], v[80:83]
	v_mfma_f32_16x16x32_bf16 v[84:87], v[112:115], v[196:199], v[84:87]
	v_mfma_f32_16x16x32_bf16 v[88:91], v[104:107], v[204:207], v[88:91]
	v_mfma_f32_16x16x32_bf16 v[64:67], v[108:111], v[184:187], v[64:67]
	v_mfma_f32_16x16x32_bf16 v[68:71], v[116:119], v[184:187], v[68:71]
	v_mfma_f32_16x16x32_bf16 v[72:75], v[108:111], v[192:195], v[72:75]
	v_mfma_f32_16x16x32_bf16 v[76:79], v[116:119], v[192:195], v[76:79]
	v_mfma_f32_16x16x32_bf16 v[80:83], v[108:111], v[200:203], v[80:83]
	v_mfma_f32_16x16x32_bf16 v[84:87], v[116:119], v[200:203], v[84:87]
	v_mfma_f32_16x16x32_bf16 v[212:215], v[108:111], v[208:211], v[88:91]
	v_mfma_f32_16x16x32_bf16 v[88:91], v[112:115], v[204:207], v[92:95]
	v_mfma_f32_16x16x32_bf16 v[216:219], v[116:119], v[208:211], v[88:91]
	s_setprio 0
	s_setprio 1
	v_mfma_f32_16x16x32_bf16 v[32:35], v[172:175], v[180:183], v[32:35]
	v_mfma_f32_16x16x32_bf16 v[36:39], v[120:123], v[188:191], v[36:39]
	v_mfma_f32_16x16x32_bf16 v[40:43], v[172:175], v[188:191], v[40:43]
	v_mfma_f32_16x16x32_bf16 v[44:47], v[120:123], v[196:199], v[44:47]
	v_mfma_f32_16x16x32_bf16 v[48:51], v[172:175], v[196:199], v[48:51]
	v_mfma_f32_16x16x32_bf16 v[52:55], v[120:123], v[204:207], v[52:55]
	v_mfma_f32_16x16x32_bf16 v[56:59], v[172:175], v[204:207], v[56:59]
	v_mfma_f32_16x16x32_bf16 v[88:91], v[120:123], v[180:183], v[96:99]
	v_mfma_f32_16x16x32_bf16 v[32:35], v[176:179], v[184:187], v[32:35]
	v_mfma_f32_16x16x32_bf16 v[36:39], v[124:127], v[192:195], v[36:39]
	v_mfma_f32_16x16x32_bf16 v[40:43], v[176:179], v[192:195], v[40:43]
	v_mfma_f32_16x16x32_bf16 v[44:47], v[124:127], v[200:203], v[44:47]
	v_mfma_f32_16x16x32_bf16 v[48:51], v[176:179], v[200:203], v[48:51]
	v_mfma_f32_16x16x32_bf16 v[52:55], v[124:127], v[208:211], v[52:55]
	v_mfma_f32_16x16x32_bf16 v[56:59], v[176:179], v[208:211], v[56:59]
	v_mfma_f32_16x16x32_bf16 v[220:223], v[124:127], v[184:187], v[88:91]
	s_setprio 0
	s_barrier
	s_mov_b32 m0, s64
	v_lshl_add_u64 v[156:157], s[46:47], 0, v[142:143]
	s_add_u32 s42, s46, 0x10000
	ds_read_b128 v[88:91], v163 offset:16384
	ds_read_b128 v[92:95], v163 offset:17408
	ds_read_b128 v[96:99], v163 offset:18432
	ds_read_b128 v[180:183], v163 offset:19456
	ds_read_b128 v[184:187], v163 offset:20480
	ds_read_b128 v[188:191], v163 offset:21504
	ds_read_b128 v[192:195], v163 offset:22528
	ds_read_b128 v[196:199], v163 offset:23552
	global_load_lds_dwordx4 v[156:157], off
	v_lshl_add_u64 v[250:251], s[46:47], 0, v[146:147]
	s_mov_b32 m0, s31
	s_addc_u32 s43, s47, 0
	global_load_lds_dwordx4 v[250:251], off
	v_lshl_add_u64 v[200:201], s[42:43], 0, v[142:143]
	s_mov_b32 m0, s35
	v_lshl_add_u64 v[252:253], s[48:49], 0, v[140:141]
	global_load_lds_dwordx4 v[200:201], off
	v_lshl_add_u64 v[200:201], s[42:43], 0, v[146:147]
	s_mov_b32 m0, s63
	v_lshl_add_u64 v[148:149], s[48:49], 0, v[144:145]
	global_load_lds_dwordx4 v[200:201], off
	s_mov_b32 m0, s41
	s_nop 0
	global_load_lds_dwordx4 v[252:253], off
	s_mov_b32 m0, s50
	s_nop 0
	global_load_lds_dwordx4 v[148:149], off
	s_waitcnt vmcnt(8)
	s_waitcnt lgkmcnt(0)
	s_setprio 1
	s_barrier
	s_waitcnt lgkmcnt(0)
	v_mfma_f32_16x16x32_bf16 v[0:3], v[104:107], v[192:195], v[0:3]
	v_mfma_f32_16x16x32_bf16 v[4:7], v[112:115], v[192:195], v[4:7]
	v_mfma_f32_16x16x32_bf16 v[128:131], v[104:107], v[88:91], v[128:131]
	v_mfma_f32_16x16x32_bf16 v[132:135], v[112:115], v[88:91], v[132:135]
	v_mfma_f32_16x16x32_bf16 v[136:139], v[104:107], v[96:99], v[136:139]
	v_mfma_f32_16x16x32_bf16 v[152:155], v[112:115], v[96:99], v[152:155]
	v_mfma_f32_16x16x32_bf16 v[164:167], v[104:107], v[184:187], v[164:167]
	v_mfma_f32_16x16x32_bf16 v[168:171], v[112:115], v[184:187], v[168:171]
	v_mfma_f32_16x16x32_bf16 v[0:3], v[108:111], v[196:199], v[0:3]
	v_mfma_f32_16x16x32_bf16 v[4:7], v[116:119], v[196:199], v[4:7]
	v_mfma_f32_16x16x32_bf16 v[128:131], v[108:111], v[92:95], v[128:131]
	v_mfma_f32_16x16x32_bf16 v[132:135], v[116:119], v[92:95], v[132:135]
	v_mfma_f32_16x16x32_bf16 v[136:139], v[108:111], v[180:183], v[136:139]
	v_mfma_f32_16x16x32_bf16 v[152:155], v[116:119], v[180:183], v[152:155]
	v_mfma_f32_16x16x32_bf16 v[164:167], v[108:111], v[188:191], v[164:167]
	v_mfma_f32_16x16x32_bf16 v[168:171], v[116:119], v[188:191], v[168:171]
	s_setprio 0
	s_setprio 1
	v_mfma_f32_16x16x32_bf16 v[8:11], v[120:123], v[88:91], v[8:11]
	v_mfma_f32_16x16x32_bf16 v[200:203], v[124:127], v[92:95], v[8:11]
	v_mfma_f32_16x16x32_bf16 v[8:11], v[172:175], v[88:91], v[12:15]
	v_mfma_f32_16x16x32_bf16 v[204:207], v[176:179], v[92:95], v[8:11]
	v_mfma_f32_16x16x32_bf16 v[8:11], v[120:123], v[96:99], v[24:27]
	v_mfma_f32_16x16x32_bf16 v[208:211], v[124:127], v[180:183], v[8:11]
	v_mfma_f32_16x16x32_bf16 v[8:11], v[172:175], v[96:99], v[28:31]
	v_mfma_f32_16x16x32_bf16 v[28:31], v[176:179], v[180:183], v[8:11]
	v_mfma_f32_16x16x32_bf16 v[8:11], v[120:123], v[184:187], v[60:63]
	v_mfma_f32_16x16x32_bf16 v[180:183], v[124:127], v[188:191], v[8:11]
	v_mfma_f32_16x16x32_bf16 v[8:11], v[172:175], v[184:187], v[100:103]
	v_mfma_f32_16x16x32_bf16 v[184:187], v[176:179], v[188:191], v[8:11]
	v_mfma_f32_16x16x32_bf16 v[8:11], v[120:123], v[192:195], v[16:19]
	v_mfma_f32_16x16x32_bf16 v[188:191], v[124:127], v[196:199], v[8:11]
	v_mfma_f32_16x16x32_bf16 v[8:11], v[172:175], v[192:195], v[20:23]
	v_mfma_f32_16x16x32_bf16 v[172:175], v[176:179], v[196:199], v[8:11]
	s_setprio 0
	s_barrier
	s_nop 4
	ds_read_b128 v[8:11], v224
	ds_read_b128 v[12:15], v224 offset:1024
	ds_read_b128 v[20:23], v224 offset:2048
	ds_read_b128 v[176:179], v224 offset:3072
	ds_read_b128 v[192:195], v228
	ds_read_b128 v[196:199], v228 offset:1024
	ds_read_b128 v[224:227], v228 offset:2048
	ds_read_b128 v[230:233], v228 offset:3072
	s_add_u32 s42, s48, 0x10000
	s_addc_u32 s43, s49, 0
	s_mov_b32 m0, s51
	v_lshl_add_u64 v[88:89], s[42:43], 0, v[140:141]
	ds_read_b128 v[16:19], v163 offset:32768
	ds_read_b128 v[24:27], v163 offset:33792
	ds_read_b128 v[60:63], v163 offset:34816
	ds_read_b128 v[104:107], v163 offset:35840
	ds_read_b128 v[234:237], v163 offset:36864
	ds_read_b128 v[238:241], v163 offset:37888
	ds_read_b128 v[242:245], v163 offset:38912
	ds_read_b128 v[246:249], v163 offset:39936
	global_load_lds_dwordx4 v[88:89], off
	v_lshl_add_u64 v[88:89], s[42:43], 0, v[144:145]
	s_mov_b32 m0, s52
	s_nop 0
	global_load_lds_dwordx4 v[88:89], off
	s_waitcnt vmcnt(8)
	s_waitcnt lgkmcnt(0)
	s_setprio 1
	s_barrier
	s_waitcnt lgkmcnt(0)
	v_mfma_f32_16x16x32_bf16 v[64:67], v[8:11], v[16:19], v[64:67]
	v_mfma_f32_16x16x32_bf16 v[112:115], v[12:15], v[24:27], v[64:67]
	v_mfma_f32_16x16x32_bf16 v[64:67], v[20:23], v[16:19], v[68:71]
	v_mfma_f32_16x16x32_bf16 v[116:119], v[176:179], v[24:27], v[64:67]
	v_mfma_f32_16x16x32_bf16 v[64:67], v[8:11], v[60:63], v[72:75]
	v_mfma_f32_16x16x32_bf16 v[96:99], v[12:15], v[104:107], v[64:67]
	v_mfma_f32_16x16x32_bf16 v[64:67], v[20:23], v[60:63], v[76:79]
	v_mfma_f32_16x16x32_bf16 v[100:103], v[176:179], v[104:107], v[64:67]
	v_mfma_f32_16x16x32_bf16 v[64:67], v[8:11], v[234:237], v[80:83]
	v_mfma_f32_16x16x32_bf16 v[92:95], v[12:15], v[238:241], v[64:67]
	v_mfma_f32_16x16x32_bf16 v[64:67], v[20:23], v[234:237], v[84:87]
	v_mfma_f32_16x16x32_bf16 v[88:91], v[176:179], v[238:241], v[64:67]
	v_mfma_f32_16x16x32_bf16 v[64:67], v[8:11], v[242:245], v[212:215]
	v_mfma_f32_16x16x32_bf16 v[76:79], v[12:15], v[246:249], v[64:67]
	v_mfma_f32_16x16x32_bf16 v[64:67], v[20:23], v[242:245], v[216:219]
	v_mfma_f32_16x16x32_bf16 v[72:75], v[176:179], v[246:249], v[64:67]
	s_setprio 0
	s_setprio 1
	v_mfma_f32_16x16x32_bf16 v[64:67], v[192:195], v[16:19], v[220:223]
	v_mfma_f32_16x16x32_bf16 v[16:19], v[224:227], v[16:19], v[32:35]
	v_mfma_f32_16x16x32_bf16 v[124:127], v[230:233], v[24:27], v[16:19]
	v_mfma_f32_16x16x32_bf16 v[16:19], v[192:195], v[60:63], v[36:39]
	v_mfma_f32_16x16x32_bf16 v[108:111], v[196:199], v[104:107], v[16:19]
	v_mfma_f32_16x16x32_bf16 v[16:19], v[224:227], v[60:63], v[40:43]
	v_mfma_f32_16x16x32_bf16 v[104:107], v[230:233], v[104:107], v[16:19]
	v_mfma_f32_16x16x32_bf16 v[16:19], v[192:195], v[234:237], v[44:47]
	v_mfma_f32_16x16x32_bf16 v[84:87], v[196:199], v[238:241], v[16:19]
	v_mfma_f32_16x16x32_bf16 v[16:19], v[224:227], v[234:237], v[48:51]
	v_mfma_f32_16x16x32_bf16 v[80:83], v[230:233], v[238:241], v[16:19]
	v_mfma_f32_16x16x32_bf16 v[16:19], v[192:195], v[242:245], v[52:55]
	v_mfma_f32_16x16x32_bf16 v[68:71], v[196:199], v[246:249], v[16:19]
	v_mfma_f32_16x16x32_bf16 v[16:19], v[224:227], v[242:245], v[56:59]
	v_mfma_f32_16x16x32_bf16 v[120:123], v[196:199], v[24:27], v[64:67]
	v_mfma_f32_16x16x32_bf16 v[64:67], v[230:233], v[246:249], v[16:19]
	s_setprio 0
	s_barrier
	s_mov_b32 m0, s66
	s_nop 2
	v_lshl_add_u64 v[16:17], v[156:157], 0, s[12:13]
	s_add_u32 s42, s46, 0x10080
	ds_read_b128 v[36:39], v163 offset:49152
	ds_read_b128 v[40:43], v163 offset:50176
	ds_read_b128 v[212:215], v163 offset:51200
	ds_read_b128 v[216:219], v163 offset:52224
	ds_read_b128 v[220:223], v163 offset:53248
	ds_read_b128 v[234:237], v163 offset:54272
	ds_read_b128 v[238:241], v163 offset:55296
	ds_read_b128 v[242:245], v163 offset:56320
	global_load_lds_dwordx4 v[16:17], off
	v_lshl_add_u64 v[16:17], v[250:251], 0, s[12:13]
	s_mov_b32 m0, s65
	s_addc_u32 s43, s47, 0
	global_load_lds_dwordx4 v[16:17], off
	v_lshl_add_u64 v[16:17], s[42:43], 0, v[142:143]
	s_mov_b32 m0, s44
	s_nop 0
	global_load_lds_dwordx4 v[16:17], off
	v_lshl_add_u64 v[16:17], s[42:43], 0, v[146:147]
	s_mov_b32 m0, s45
	s_nop 0
	global_load_lds_dwordx4 v[16:17], off
	v_lshl_add_u64 v[16:17], v[252:253], 0, s[12:13]
	s_mov_b32 m0, s53
	s_nop 0
	global_load_lds_dwordx4 v[16:17], off
	v_lshl_add_u64 v[16:17], v[148:149], 0, s[12:13]
	s_mov_b32 m0, s54
	s_nop 0
	global_load_lds_dwordx4 v[16:17], off
	s_waitcnt vmcnt(8)
	s_waitcnt lgkmcnt(0)
	s_setprio 1
	s_barrier
	s_waitcnt lgkmcnt(0)
	v_mfma_f32_16x16x32_bf16 v[16:19], v[8:11], v[36:39], v[128:131]
	v_mfma_f32_16x16x32_bf16 v[60:63], v[12:15], v[40:43], v[16:19]
	v_mfma_f32_16x16x32_bf16 v[16:19], v[20:23], v[36:39], v[132:135]
	v_mfma_f32_16x16x32_bf16 v[56:59], v[176:179], v[40:43], v[16:19]
	v_mfma_f32_16x16x32_bf16 v[16:19], v[8:11], v[212:215], v[136:139]
	v_mfma_f32_16x16x32_bf16 v[44:47], v[12:15], v[216:219], v[16:19]
	v_mfma_f32_16x16x32_bf16 v[16:19], v[20:23], v[212:215], v[152:155]
	v_mfma_f32_16x16x32_bf16 v[32:35], v[176:179], v[216:219], v[16:19]
	v_mfma_f32_16x16x32_bf16 v[16:19], v[8:11], v[220:223], v[164:167]
	v_mfma_f32_16x16x32_bf16 v[0:3], v[8:11], v[238:241], v[0:3]
	v_mfma_f32_16x16x32_bf16 v[24:27], v[12:15], v[234:237], v[16:19]
	v_mfma_f32_16x16x32_bf16 v[16:19], v[20:23], v[220:223], v[168:171]
	v_mfma_f32_16x16x32_bf16 v[12:15], v[12:15], v[242:245], v[0:3]
	v_mfma_f32_16x16x32_bf16 v[0:3], v[20:23], v[238:241], v[4:7]
	v_mfma_f32_16x16x32_bf16 v[16:19], v[176:179], v[234:237], v[16:19]
	v_mfma_f32_16x16x32_bf16 v[8:11], v[176:179], v[242:245], v[0:3]
	s_setprio 0
	s_setprio 1
	v_mfma_f32_16x16x32_bf16 v[0:3], v[192:195], v[36:39], v[200:203]
	v_mfma_f32_16x16x32_bf16 v[52:55], v[196:199], v[40:43], v[0:3]
	v_mfma_f32_16x16x32_bf16 v[0:3], v[224:227], v[36:39], v[204:207]
	v_mfma_f32_16x16x32_bf16 v[48:51], v[230:233], v[40:43], v[0:3]
	v_mfma_f32_16x16x32_bf16 v[0:3], v[192:195], v[212:215], v[208:211]
	v_mfma_f32_16x16x32_bf16 v[40:43], v[196:199], v[216:219], v[0:3]
	v_mfma_f32_16x16x32_bf16 v[0:3], v[224:227], v[212:215], v[28:31]
	v_mfma_f32_16x16x32_bf16 v[36:39], v[230:233], v[216:219], v[0:3]
	v_mfma_f32_16x16x32_bf16 v[0:3], v[192:195], v[220:223], v[180:183]
	v_mfma_f32_16x16x32_bf16 v[28:31], v[196:199], v[234:237], v[0:3]
	v_mfma_f32_16x16x32_bf16 v[0:3], v[224:227], v[220:223], v[184:187]
	v_mfma_f32_16x16x32_bf16 v[20:23], v[230:233], v[234:237], v[0:3]
	v_mfma_f32_16x16x32_bf16 v[0:3], v[192:195], v[238:241], v[188:191]
	v_mfma_f32_16x16x32_bf16 v[4:7], v[196:199], v[242:245], v[0:3]
	v_mfma_f32_16x16x32_bf16 v[0:3], v[224:227], v[238:241], v[172:175]
	v_mfma_f32_16x16x32_bf16 v[0:3], v[230:233], v[242:245], v[0:3]
	s_setprio 0
	s_barrier
	s_andn2_b64 vcc, exec, s[14:15]
	s_cbranch_vccnz .LBB0_2198
	s_barrier
